# tail: nt policy on the pp and hfb stores (each re-read once, much later) on top of nt x loads
# speedup vs baseline: 1.0145x; 1.0145x over previous
.LBB0_517:
	s_add_i32 s59, s31, 1
	s_cmp_lt_u32 s31, 3
	s_cselect_b64 s[60:61], -1, 0
	s_and_b64 s[28:29], s[60:61], exec
	s_cselect_b32 s28, s59, s30
	ds_read_b128 v[46:49], v40
	ds_read_b128 v[50:53], v40 offset:1024
	ds_read_b128 v[54:57], v40 offset:2048
	ds_read_b128 v[58:61], v40 offset:3072
	s_ashr_i32 s29, s28, 31
	s_lshl_b64 s[28:29], s[28:29], 17
	s_add_u32 s28, s84, s28
	s_addc_u32 s29, s85, s29
	s_and_b64 s[30:31], s[60:61], exec
	s_cselect_b32 s31, s29, s35
	s_cselect_b32 s30, s28, s34
	s_mov_b32 m0, s45
	ds_read_b128 v[62:65], v41
	ds_read_b128 v[66:69], v41 offset:1024
	ds_read_b128 v[70:73], v41 offset:2048
	ds_read_b128 v[74:77], v41 offset:3072
	ds_read_b128 v[78:81], v41 offset:4096
	ds_read_b128 v[82:85], v41 offset:5120
	ds_read_b128 v[86:89], v41 offset:6144
	ds_read_b128 v[90:93], v41 offset:7168
	global_load_lds_dwordx4 v[18:19], off
	s_mov_b32 m0, s46
	s_nop 0
	global_load_lds_dwordx4 v[20:21], off
	s_waitcnt lgkmcnt(8)
	s_barrier
	s_waitcnt lgkmcnt(0)
	s_setprio 1
	s_waitcnt lgkmcnt(0)
	v_mfma_f32_16x16x32_bf16 v[94:97], v[46:49], v[62:65], 0
	v_mfma_f32_16x16x32_bf16 v[98:101], v[54:57], v[62:65], 0
	v_mfma_f32_16x16x32_bf16 v[102:105], v[46:49], v[70:73], 0
	v_mfma_f32_16x16x32_bf16 v[106:109], v[54:57], v[70:73], 0
	v_mfma_f32_16x16x32_bf16 v[110:113], v[46:49], v[78:81], 0
	v_mfma_f32_16x16x32_bf16 v[114:117], v[54:57], v[78:81], 0
	v_mfma_f32_16x16x32_bf16 v[118:121], v[46:49], v[86:89], 0
	v_mfma_f32_16x16x32_bf16 v[122:125], v[54:57], v[86:89], 0
	v_mfma_f32_16x16x32_bf16 v[94:97], v[50:53], v[66:69], v[94:97]
	v_mfma_f32_16x16x32_bf16 v[98:101], v[58:61], v[66:69], v[98:101]
	v_mfma_f32_16x16x32_bf16 v[102:105], v[50:53], v[74:77], v[102:105]
	v_mfma_f32_16x16x32_bf16 v[106:109], v[58:61], v[74:77], v[106:109]
	v_mfma_f32_16x16x32_bf16 v[110:113], v[50:53], v[82:85], v[110:113]
	v_mfma_f32_16x16x32_bf16 v[114:117], v[58:61], v[82:85], v[114:117]
	v_mfma_f32_16x16x32_bf16 v[118:121], v[50:53], v[90:93], v[118:121]
	v_mfma_f32_16x16x32_bf16 v[122:125], v[58:61], v[90:93], v[122:125]
	s_setprio 0
	s_barrier
	v_lshl_add_u64 v[238:239], s[34:35], 0, v[2:3]
	s_mov_b32 m0, s47
	v_lshl_add_u64 v[142:143], v[238:239], 0, s[6:7]
	v_lshl_add_u64 v[240:241], s[34:35], 0, v[4:5]
	ds_read_b128 v[126:129], v42
	ds_read_b128 v[130:133], v42 offset:1024
	ds_read_b128 v[134:137], v42 offset:2048
	ds_read_b128 v[138:141], v42 offset:3072
	global_load_lds_dwordx4 v[142:143], off
	v_lshl_add_u64 v[142:143], v[240:241], 0, s[6:7]
	s_mov_b32 m0, s48
	s_nop 0
	global_load_lds_dwordx4 v[142:143], off
	s_barrier
	s_waitcnt lgkmcnt(0)
	s_setprio 1
	s_waitcnt lgkmcnt(0)
	v_mfma_f32_16x16x32_bf16 v[142:145], v[126:129], v[62:65], 0
	v_mfma_f32_16x16x32_bf16 v[62:65], v[134:137], v[62:65], 0
	v_mfma_f32_16x16x32_bf16 v[142:145], v[130:133], v[66:69], v[142:145]
	v_mfma_f32_16x16x32_bf16 v[62:65], v[138:141], v[66:69], v[62:65]
	v_mfma_f32_16x16x32_bf16 v[66:69], v[126:129], v[70:73], 0
	v_mfma_f32_16x16x32_bf16 v[70:73], v[134:137], v[70:73], 0
	v_mfma_f32_16x16x32_bf16 v[66:69], v[130:133], v[74:77], v[66:69]
	v_mfma_f32_16x16x32_bf16 v[70:73], v[138:141], v[74:77], v[70:73]
	v_mfma_f32_16x16x32_bf16 v[74:77], v[126:129], v[78:81], 0
	v_mfma_f32_16x16x32_bf16 v[78:81], v[134:137], v[78:81], 0
	v_mfma_f32_16x16x32_bf16 v[74:77], v[130:133], v[82:85], v[74:77]
	v_mfma_f32_16x16x32_bf16 v[78:81], v[138:141], v[82:85], v[78:81]
	v_mfma_f32_16x16x32_bf16 v[82:85], v[126:129], v[86:89], 0
	v_mfma_f32_16x16x32_bf16 v[86:89], v[134:137], v[86:89], 0
	v_mfma_f32_16x16x32_bf16 v[82:85], v[130:133], v[90:93], v[82:85]
	v_mfma_f32_16x16x32_bf16 v[86:89], v[138:141], v[90:93], v[86:89]
	s_setprio 0
	s_mov_b32 m0, s33
	s_barrier
	ds_read_b128 v[90:93], v41 offset:16384
	ds_read_b128 v[146:149], v41 offset:17408
	ds_read_b128 v[150:153], v41 offset:18432
	ds_read_b128 v[154:157], v41 offset:19456
	ds_read_b128 v[158:161], v41 offset:20480
	ds_read_b128 v[162:165], v41 offset:21504
	ds_read_b128 v[166:169], v41 offset:22528
	ds_read_b128 v[170:173], v41 offset:23552
	global_load_lds_dwordx4 v[22:23], off
	s_mov_b32 m0, s36
	s_nop 0
	global_load_lds_dwordx4 v[24:25], off
	s_barrier
	s_waitcnt lgkmcnt(0)
	s_setprio 1
	s_waitcnt lgkmcnt(0)
	v_mfma_f32_16x16x32_bf16 v[174:177], v[46:49], v[90:93], 0
	v_mfma_f32_16x16x32_bf16 v[182:185], v[46:49], v[150:153], 0
	v_mfma_f32_16x16x32_bf16 v[190:193], v[46:49], v[158:161], 0
	v_mfma_f32_16x16x32_bf16 v[46:49], v[46:49], v[166:169], 0
	v_mfma_f32_16x16x32_bf16 v[174:177], v[50:53], v[146:149], v[174:177]
	v_mfma_f32_16x16x32_bf16 v[178:181], v[54:57], v[90:93], 0
	v_mfma_f32_16x16x32_bf16 v[182:185], v[50:53], v[154:157], v[182:185]
	v_mfma_f32_16x16x32_bf16 v[186:189], v[54:57], v[150:153], 0
	v_mfma_f32_16x16x32_bf16 v[190:193], v[50:53], v[162:165], v[190:193]
	v_mfma_f32_16x16x32_bf16 v[194:197], v[54:57], v[158:161], 0
	v_mfma_f32_16x16x32_bf16 v[46:49], v[50:53], v[170:173], v[46:49]
	v_mfma_f32_16x16x32_bf16 v[50:53], v[54:57], v[166:169], 0
	v_mfma_f32_16x16x32_bf16 v[178:181], v[58:61], v[146:149], v[178:181]
	v_mfma_f32_16x16x32_bf16 v[186:189], v[58:61], v[154:157], v[186:189]
	v_mfma_f32_16x16x32_bf16 v[194:197], v[58:61], v[162:165], v[194:197]
	v_mfma_f32_16x16x32_bf16 v[50:53], v[58:61], v[170:173], v[50:53]
	s_setprio 0
	s_barrier
	s_add_u32 s60, s34, 0x10100
	s_addc_u32 s61, s35, 0
	s_mov_b32 m0, s49
	v_lshl_add_u64 v[54:55], s[60:61], 0, v[2:3]
	global_load_lds_dwordx4 v[54:55], off
	v_lshl_add_u64 v[54:55], s[60:61], 0, v[4:5]
	s_mov_b32 m0, s50
	s_nop 0
	global_load_lds_dwordx4 v[54:55], off
	s_waitcnt vmcnt(6)
	s_barrier
	s_setprio 1
	v_mfma_f32_16x16x32_bf16 v[54:57], v[126:129], v[90:93], 0
	v_mfma_f32_16x16x32_bf16 v[58:61], v[134:137], v[90:93], 0
	v_mfma_f32_16x16x32_bf16 v[54:57], v[130:133], v[146:149], v[54:57]
	v_mfma_f32_16x16x32_bf16 v[58:61], v[138:141], v[146:149], v[58:61]
	v_mfma_f32_16x16x32_bf16 v[90:93], v[126:129], v[150:153], 0
	v_mfma_f32_16x16x32_bf16 v[146:149], v[134:137], v[150:153], 0
	v_mfma_f32_16x16x32_bf16 v[150:153], v[126:129], v[158:161], 0
	v_mfma_f32_16x16x32_bf16 v[126:129], v[126:129], v[166:169], 0
	v_mfma_f32_16x16x32_bf16 v[90:93], v[130:133], v[154:157], v[90:93]
	v_mfma_f32_16x16x32_bf16 v[146:149], v[138:141], v[154:157], v[146:149]
	v_mfma_f32_16x16x32_bf16 v[150:153], v[130:133], v[162:165], v[150:153]
	v_mfma_f32_16x16x32_bf16 v[154:157], v[134:137], v[158:161], 0
	v_mfma_f32_16x16x32_bf16 v[126:129], v[130:133], v[170:173], v[126:129]
	v_mfma_f32_16x16x32_bf16 v[130:133], v[134:137], v[166:169], 0
	v_mfma_f32_16x16x32_bf16 v[154:157], v[138:141], v[162:165], v[154:157]
	v_mfma_f32_16x16x32_bf16 v[130:133], v[138:141], v[170:173], v[130:133]
	s_setprio 0
	s_barrier
	ds_read_b128 v[134:137], v43
	ds_read_b128 v[138:141], v43 offset:1024
	ds_read_b128 v[158:161], v43 offset:2048
	ds_read_b128 v[162:165], v43 offset:3072
	s_mov_b32 m0, s37
	ds_read_b128 v[166:169], v41 offset:32768
	ds_read_b128 v[170:173], v41 offset:33792
	ds_read_b128 v[198:201], v41 offset:34816
	ds_read_b128 v[202:205], v41 offset:35840
	ds_read_b128 v[206:209], v41 offset:36864
	ds_read_b128 v[210:213], v41 offset:37888
	ds_read_b128 v[214:217], v41 offset:38912
	ds_read_b128 v[218:221], v41 offset:39936
	global_load_lds_dwordx4 v[26:27], off
	s_mov_b32 m0, s38
	s_nop 0
	global_load_lds_dwordx4 v[28:29], off
	s_waitcnt lgkmcnt(8)
	s_barrier
	s_waitcnt lgkmcnt(0)
	s_setprio 1
	s_waitcnt lgkmcnt(0)
	v_mfma_f32_16x16x32_bf16 v[94:97], v[134:137], v[166:169], v[94:97]
	v_mfma_f32_16x16x32_bf16 v[98:101], v[158:161], v[166:169], v[98:101]
	v_mfma_f32_16x16x32_bf16 v[102:105], v[134:137], v[198:201], v[102:105]
	v_mfma_f32_16x16x32_bf16 v[106:109], v[158:161], v[198:201], v[106:109]
	v_mfma_f32_16x16x32_bf16 v[110:113], v[134:137], v[206:209], v[110:113]
	v_mfma_f32_16x16x32_bf16 v[114:117], v[158:161], v[206:209], v[114:117]
	v_mfma_f32_16x16x32_bf16 v[118:121], v[134:137], v[214:217], v[118:121]
	v_mfma_f32_16x16x32_bf16 v[122:125], v[158:161], v[214:217], v[122:125]
	v_mfma_f32_16x16x32_bf16 v[94:97], v[138:141], v[170:173], v[94:97]
	v_mfma_f32_16x16x32_bf16 v[98:101], v[162:165], v[170:173], v[98:101]
	v_mfma_f32_16x16x32_bf16 v[102:105], v[138:141], v[202:205], v[102:105]
	v_mfma_f32_16x16x32_bf16 v[106:109], v[162:165], v[202:205], v[106:109]
	v_mfma_f32_16x16x32_bf16 v[110:113], v[138:141], v[210:213], v[110:113]
	v_mfma_f32_16x16x32_bf16 v[114:117], v[162:165], v[210:213], v[114:117]
	v_mfma_f32_16x16x32_bf16 v[118:121], v[138:141], v[218:221], v[118:121]
	v_mfma_f32_16x16x32_bf16 v[122:125], v[162:165], v[218:221], v[122:125]
	s_setprio 0
	s_barrier
	s_mov_b32 m0, s51
	v_lshl_add_u64 v[238:239], v[238:239], 0, s[8:9]
	ds_read_b128 v[222:225], v44
	ds_read_b128 v[226:229], v44 offset:1024
	ds_read_b128 v[230:233], v44 offset:2048
	ds_read_b128 v[234:237], v44 offset:3072
	global_load_lds_dwordx4 v[238:239], off
	v_lshl_add_u64 v[238:239], v[240:241], 0, s[8:9]
	s_mov_b32 m0, s52
	s_nop 0
	global_load_lds_dwordx4 v[238:239], off
	s_barrier
	s_waitcnt lgkmcnt(0)
	s_setprio 1
	s_waitcnt lgkmcnt(0)
	v_mfma_f32_16x16x32_bf16 v[142:145], v[222:225], v[166:169], v[142:145]
	v_mfma_f32_16x16x32_bf16 v[62:65], v[230:233], v[166:169], v[62:65]
	v_mfma_f32_16x16x32_bf16 v[66:69], v[222:225], v[198:201], v[66:69]
	v_mfma_f32_16x16x32_bf16 v[70:73], v[230:233], v[198:201], v[70:73]
	v_mfma_f32_16x16x32_bf16 v[74:77], v[222:225], v[206:209], v[74:77]
	v_mfma_f32_16x16x32_bf16 v[78:81], v[230:233], v[206:209], v[78:81]
	v_mfma_f32_16x16x32_bf16 v[82:85], v[222:225], v[214:217], v[82:85]
	v_mfma_f32_16x16x32_bf16 v[86:89], v[230:233], v[214:217], v[86:89]
	v_mfma_f32_16x16x32_bf16 v[142:145], v[226:229], v[170:173], v[142:145]
	v_mfma_f32_16x16x32_bf16 v[62:65], v[234:237], v[170:173], v[62:65]
	v_mfma_f32_16x16x32_bf16 v[66:69], v[226:229], v[202:205], v[66:69]
	v_mfma_f32_16x16x32_bf16 v[70:73], v[234:237], v[202:205], v[70:73]
	v_mfma_f32_16x16x32_bf16 v[74:77], v[226:229], v[210:213], v[74:77]
	v_mfma_f32_16x16x32_bf16 v[78:81], v[234:237], v[210:213], v[78:81]
	v_mfma_f32_16x16x32_bf16 v[82:85], v[226:229], v[218:221], v[82:85]
	v_mfma_f32_16x16x32_bf16 v[86:89], v[234:237], v[218:221], v[86:89]
	s_setprio 0
	s_mov_b32 m0, s40
	s_barrier
	ds_read_b128 v[166:169], v41 offset:49152
	ds_read_b128 v[170:173], v41 offset:50176
	ds_read_b128 v[198:201], v41 offset:51200
	ds_read_b128 v[202:205], v41 offset:52224
	ds_read_b128 v[206:209], v41 offset:53248
	ds_read_b128 v[210:213], v41 offset:54272
	ds_read_b128 v[214:217], v41 offset:55296
	ds_read_b128 v[218:221], v41 offset:56320
	global_load_lds_dwordx4 v[30:31], off
	s_mov_b32 m0, s41
	s_nop 0
	global_load_lds_dwordx4 v[32:33], off
	s_barrier
	s_waitcnt lgkmcnt(0)
	s_setprio 1
	s_waitcnt lgkmcnt(0)
	v_mfma_f32_16x16x32_bf16 v[174:177], v[134:137], v[166:169], v[174:177]
	v_mfma_f32_16x16x32_bf16 v[178:181], v[158:161], v[166:169], v[178:181]
	v_mfma_f32_16x16x32_bf16 v[182:185], v[134:137], v[198:201], v[182:185]
	v_mfma_f32_16x16x32_bf16 v[186:189], v[158:161], v[198:201], v[186:189]
	v_mfma_f32_16x16x32_bf16 v[190:193], v[134:137], v[206:209], v[190:193]
	v_mfma_f32_16x16x32_bf16 v[194:197], v[158:161], v[206:209], v[194:197]
	v_mfma_f32_16x16x32_bf16 v[46:49], v[134:137], v[214:217], v[46:49]
	v_mfma_f32_16x16x32_bf16 v[50:53], v[158:161], v[214:217], v[50:53]
	v_mfma_f32_16x16x32_bf16 v[174:177], v[138:141], v[170:173], v[174:177]
	v_mfma_f32_16x16x32_bf16 v[178:181], v[162:165], v[170:173], v[178:181]
	v_mfma_f32_16x16x32_bf16 v[182:185], v[138:141], v[202:205], v[182:185]
	v_mfma_f32_16x16x32_bf16 v[186:189], v[162:165], v[202:205], v[186:189]
	v_mfma_f32_16x16x32_bf16 v[190:193], v[138:141], v[210:213], v[190:193]
	v_mfma_f32_16x16x32_bf16 v[194:197], v[162:165], v[210:213], v[194:197]
	v_mfma_f32_16x16x32_bf16 v[46:49], v[138:141], v[218:221], v[46:49]
	v_mfma_f32_16x16x32_bf16 v[50:53], v[162:165], v[218:221], v[50:53]
	s_setprio 0
	s_barrier
	s_add_u32 s34, s34, 0x10180
	s_addc_u32 s35, s35, 0
	s_mov_b32 m0, s53
	v_lshl_add_u64 v[134:135], s[34:35], 0, v[2:3]
	global_load_lds_dwordx4 v[134:135], off
	v_lshl_add_u64 v[134:135], s[34:35], 0, v[4:5]
	s_mov_b32 m0, s54
	s_nop 0
	global_load_lds_dwordx4 v[134:135], off
	s_waitcnt vmcnt(6)
	s_barrier
	s_setprio 1
	v_mfma_f32_16x16x32_bf16 v[54:57], v[222:225], v[166:169], v[54:57]
	v_mfma_f32_16x16x32_bf16 v[58:61], v[230:233], v[166:169], v[58:61]
	v_mfma_f32_16x16x32_bf16 v[90:93], v[222:225], v[198:201], v[90:93]
	v_mfma_f32_16x16x32_bf16 v[134:137], v[230:233], v[198:201], v[146:149]
	v_mfma_f32_16x16x32_bf16 v[138:141], v[222:225], v[206:209], v[150:153]
	v_mfma_f32_16x16x32_bf16 v[146:149], v[230:233], v[206:209], v[154:157]
	v_mfma_f32_16x16x32_bf16 v[126:129], v[222:225], v[214:217], v[126:129]
	v_mfma_f32_16x16x32_bf16 v[130:133], v[230:233], v[214:217], v[130:133]
	v_mfma_f32_16x16x32_bf16 v[54:57], v[226:229], v[170:173], v[54:57]
	v_mfma_f32_16x16x32_bf16 v[58:61], v[234:237], v[170:173], v[58:61]
	v_mfma_f32_16x16x32_bf16 v[90:93], v[226:229], v[202:205], v[90:93]
	v_mfma_f32_16x16x32_bf16 v[134:137], v[234:237], v[202:205], v[134:137]
	v_mfma_f32_16x16x32_bf16 v[138:141], v[226:229], v[210:213], v[138:141]
	v_mfma_f32_16x16x32_bf16 v[146:149], v[234:237], v[210:213], v[146:149]
	v_mfma_f32_16x16x32_bf16 v[126:129], v[226:229], v[218:221], v[126:129]
	v_mfma_f32_16x16x32_bf16 v[130:133], v[234:237], v[218:221], v[130:133]
	s_setprio 0
	s_barrier
	ds_read_b128 v[150:153], v40
	ds_read_b128 v[154:157], v40 offset:1024
	ds_read_b128 v[158:161], v40 offset:2048
	ds_read_b128 v[162:165], v40 offset:3072
	s_mov_b32 m0, s45
	ds_read_b128 v[166:169], v41
	ds_read_b128 v[170:173], v41 offset:1024
	ds_read_b128 v[198:201], v41 offset:2048
	ds_read_b128 v[202:205], v41 offset:3072
	ds_read_b128 v[206:209], v41 offset:4096
	ds_read_b128 v[210:213], v41 offset:5120
	ds_read_b128 v[214:217], v41 offset:6144
	ds_read_b128 v[218:221], v41 offset:7168
	global_load_lds_dwordx4 v[34:35], off
	s_mov_b32 m0, s46
	s_nop 0
	global_load_lds_dwordx4 v[36:37], off
	s_waitcnt lgkmcnt(8)
	s_barrier
	s_waitcnt lgkmcnt(0)
	s_setprio 1
	s_waitcnt lgkmcnt(0)
	v_mfma_f32_16x16x32_bf16 v[94:97], v[150:153], v[166:169], v[94:97]
	v_mfma_f32_16x16x32_bf16 v[98:101], v[158:161], v[166:169], v[98:101]
	v_mfma_f32_16x16x32_bf16 v[102:105], v[150:153], v[198:201], v[102:105]
	v_mfma_f32_16x16x32_bf16 v[106:109], v[158:161], v[198:201], v[106:109]
	v_mfma_f32_16x16x32_bf16 v[110:113], v[150:153], v[206:209], v[110:113]
	v_mfma_f32_16x16x32_bf16 v[114:117], v[158:161], v[206:209], v[114:117]
	v_mfma_f32_16x16x32_bf16 v[118:121], v[150:153], v[214:217], v[118:121]
	v_mfma_f32_16x16x32_bf16 v[122:125], v[158:161], v[214:217], v[122:125]
	v_mfma_f32_16x16x32_bf16 v[94:97], v[154:157], v[170:173], v[94:97]
	v_mfma_f32_16x16x32_bf16 v[98:101], v[162:165], v[170:173], v[98:101]
	v_mfma_f32_16x16x32_bf16 v[102:105], v[154:157], v[202:205], v[102:105]
	v_mfma_f32_16x16x32_bf16 v[106:109], v[162:165], v[202:205], v[106:109]
	v_mfma_f32_16x16x32_bf16 v[110:113], v[154:157], v[210:213], v[110:113]
	v_mfma_f32_16x16x32_bf16 v[114:117], v[162:165], v[210:213], v[114:117]
	v_mfma_f32_16x16x32_bf16 v[118:121], v[154:157], v[218:221], v[118:121]
	v_mfma_f32_16x16x32_bf16 v[122:125], v[162:165], v[218:221], v[122:125]
	s_setprio 0
	s_barrier
	s_mov_b32 m0, s47
	v_lshl_add_u64 v[238:239], s[30:31], 0, v[2:3]
	ds_read_b128 v[222:225], v42
	ds_read_b128 v[226:229], v42 offset:1024
	ds_read_b128 v[230:233], v42 offset:2048
	ds_read_b128 v[234:237], v42 offset:3072
	global_load_lds_dwordx4 v[238:239], off
	v_lshl_add_u64 v[240:241], s[30:31], 0, v[4:5]
	s_mov_b32 m0, s48
	s_nop 0
	global_load_lds_dwordx4 v[240:241], off
	s_barrier
	s_waitcnt lgkmcnt(0)
	s_setprio 1
	s_waitcnt lgkmcnt(0)
	v_mfma_f32_16x16x32_bf16 v[142:145], v[222:225], v[166:169], v[142:145]
	v_mfma_f32_16x16x32_bf16 v[62:65], v[230:233], v[166:169], v[62:65]
	v_mfma_f32_16x16x32_bf16 v[66:69], v[222:225], v[198:201], v[66:69]
	v_mfma_f32_16x16x32_bf16 v[70:73], v[230:233], v[198:201], v[70:73]
	v_mfma_f32_16x16x32_bf16 v[74:77], v[222:225], v[206:209], v[74:77]
	v_mfma_f32_16x16x32_bf16 v[78:81], v[230:233], v[206:209], v[78:81]
	v_mfma_f32_16x16x32_bf16 v[82:85], v[222:225], v[214:217], v[82:85]
	v_mfma_f32_16x16x32_bf16 v[86:89], v[230:233], v[214:217], v[86:89]
	v_mfma_f32_16x16x32_bf16 v[142:145], v[226:229], v[170:173], v[142:145]
	v_mfma_f32_16x16x32_bf16 v[62:65], v[234:237], v[170:173], v[62:65]
	v_mfma_f32_16x16x32_bf16 v[66:69], v[226:229], v[202:205], v[66:69]
	v_mfma_f32_16x16x32_bf16 v[70:73], v[234:237], v[202:205], v[70:73]
	v_mfma_f32_16x16x32_bf16 v[74:77], v[226:229], v[210:213], v[74:77]
	v_mfma_f32_16x16x32_bf16 v[78:81], v[234:237], v[210:213], v[78:81]
	v_mfma_f32_16x16x32_bf16 v[82:85], v[226:229], v[218:221], v[82:85]
	v_mfma_f32_16x16x32_bf16 v[86:89], v[234:237], v[218:221], v[86:89]
	s_setprio 0
	s_mov_b32 m0, s33
	s_barrier
	ds_read_b128 v[166:169], v41 offset:16384
	ds_read_b128 v[170:173], v41 offset:17408
	ds_read_b128 v[198:201], v41 offset:18432
	ds_read_b128 v[202:205], v41 offset:19456
	ds_read_b128 v[206:209], v41 offset:20480
	ds_read_b128 v[210:213], v41 offset:21504
	ds_read_b128 v[214:217], v41 offset:22528
	ds_read_b128 v[218:221], v41 offset:23552
	global_load_lds_dwordx4 v[6:7], off
	s_mov_b32 m0, s36
	s_nop 0
	global_load_lds_dwordx4 v[8:9], off
	s_barrier
	s_waitcnt lgkmcnt(0)
	s_setprio 1
	s_waitcnt lgkmcnt(0)
	v_mfma_f32_16x16x32_bf16 v[174:177], v[150:153], v[166:169], v[174:177]
	v_mfma_f32_16x16x32_bf16 v[178:181], v[158:161], v[166:169], v[178:181]
	v_mfma_f32_16x16x32_bf16 v[182:185], v[150:153], v[198:201], v[182:185]
	v_mfma_f32_16x16x32_bf16 v[186:189], v[158:161], v[198:201], v[186:189]
	v_mfma_f32_16x16x32_bf16 v[190:193], v[150:153], v[206:209], v[190:193]
	v_mfma_f32_16x16x32_bf16 v[194:197], v[158:161], v[206:209], v[194:197]
	v_mfma_f32_16x16x32_bf16 v[46:49], v[150:153], v[214:217], v[46:49]
	v_mfma_f32_16x16x32_bf16 v[50:53], v[158:161], v[214:217], v[50:53]
	v_mfma_f32_16x16x32_bf16 v[174:177], v[154:157], v[170:173], v[174:177]
	v_mfma_f32_16x16x32_bf16 v[178:181], v[162:165], v[170:173], v[178:181]
	v_mfma_f32_16x16x32_bf16 v[182:185], v[154:157], v[202:205], v[182:185]
	v_mfma_f32_16x16x32_bf16 v[186:189], v[162:165], v[202:205], v[186:189]
	v_mfma_f32_16x16x32_bf16 v[190:193], v[154:157], v[210:213], v[190:193]
	v_mfma_f32_16x16x32_bf16 v[194:197], v[162:165], v[210:213], v[194:197]
	v_mfma_f32_16x16x32_bf16 v[46:49], v[154:157], v[218:221], v[46:49]
	v_mfma_f32_16x16x32_bf16 v[50:53], v[162:165], v[218:221], v[50:53]
	s_setprio 0
	s_barrier
	s_add_u32 s34, s30, 0x10000
	s_addc_u32 s35, s31, 0
	s_mov_b32 m0, s49
	v_lshl_add_u64 v[150:151], s[34:35], 0, v[2:3]
	global_load_lds_dwordx4 v[150:151], off
	v_lshl_add_u64 v[150:151], s[34:35], 0, v[4:5]
	s_mov_b32 m0, s50
	s_nop 0
	global_load_lds_dwordx4 v[150:151], off
	s_waitcnt vmcnt(6)
	s_barrier
	s_setprio 1
	v_mfma_f32_16x16x32_bf16 v[54:57], v[222:225], v[166:169], v[54:57]
	v_mfma_f32_16x16x32_bf16 v[58:61], v[230:233], v[166:169], v[58:61]
	v_mfma_f32_16x16x32_bf16 v[90:93], v[222:225], v[198:201], v[90:93]
	v_mfma_f32_16x16x32_bf16 v[134:137], v[230:233], v[198:201], v[134:137]
	v_mfma_f32_16x16x32_bf16 v[138:141], v[222:225], v[206:209], v[138:141]
	v_mfma_f32_16x16x32_bf16 v[146:149], v[230:233], v[206:209], v[146:149]
	v_mfma_f32_16x16x32_bf16 v[126:129], v[222:225], v[214:217], v[126:129]
	v_mfma_f32_16x16x32_bf16 v[130:133], v[230:233], v[214:217], v[130:133]
	v_mfma_f32_16x16x32_bf16 v[54:57], v[226:229], v[170:173], v[54:57]
	v_mfma_f32_16x16x32_bf16 v[58:61], v[234:237], v[170:173], v[58:61]
	v_mfma_f32_16x16x32_bf16 v[90:93], v[226:229], v[202:205], v[90:93]
	v_mfma_f32_16x16x32_bf16 v[134:137], v[234:237], v[202:205], v[134:137]
	v_mfma_f32_16x16x32_bf16 v[138:141], v[226:229], v[210:213], v[138:141]
	v_mfma_f32_16x16x32_bf16 v[146:149], v[234:237], v[210:213], v[146:149]
	v_mfma_f32_16x16x32_bf16 v[126:129], v[226:229], v[218:221], v[126:129]
	v_mfma_f32_16x16x32_bf16 v[130:133], v[234:237], v[218:221], v[130:133]
	s_setprio 0
	s_barrier
	ds_read_b128 v[150:153], v43
	ds_read_b128 v[154:157], v43 offset:1024
	ds_read_b128 v[158:161], v43 offset:2048
	ds_read_b128 v[162:165], v43 offset:3072
	s_mov_b32 m0, s37
	ds_read_b128 v[166:169], v41 offset:32768
	ds_read_b128 v[170:173], v41 offset:33792
	ds_read_b128 v[198:201], v41 offset:34816
	ds_read_b128 v[202:205], v41 offset:35840
	ds_read_b128 v[206:209], v41 offset:36864
	ds_read_b128 v[210:213], v41 offset:37888
	ds_read_b128 v[214:217], v41 offset:38912
	ds_read_b128 v[218:221], v41 offset:39936
	global_load_lds_dwordx4 v[10:11], off
	s_mov_b32 m0, s38
	s_nop 0
	global_load_lds_dwordx4 v[16:17], off
	s_waitcnt lgkmcnt(8)
	s_barrier
	s_waitcnt lgkmcnt(0)
	s_setprio 1
	s_waitcnt lgkmcnt(0)
	v_mfma_f32_16x16x32_bf16 v[94:97], v[150:153], v[166:169], v[94:97]
	v_mfma_f32_16x16x32_bf16 v[98:101], v[158:161], v[166:169], v[98:101]
	v_mfma_f32_16x16x32_bf16 v[102:105], v[150:153], v[198:201], v[102:105]
	v_mfma_f32_16x16x32_bf16 v[106:109], v[158:161], v[198:201], v[106:109]
	v_mfma_f32_16x16x32_bf16 v[110:113], v[150:153], v[206:209], v[110:113]
	v_mfma_f32_16x16x32_bf16 v[114:117], v[158:161], v[206:209], v[114:117]
	v_mfma_f32_16x16x32_bf16 v[118:121], v[150:153], v[214:217], v[118:121]
	v_mfma_f32_16x16x32_bf16 v[122:125], v[158:161], v[214:217], v[122:125]
	v_mfma_f32_16x16x32_bf16 v[94:97], v[154:157], v[170:173], v[94:97]
	v_mfma_f32_16x16x32_bf16 v[98:101], v[162:165], v[170:173], v[98:101]
	v_mfma_f32_16x16x32_bf16 v[102:105], v[154:157], v[202:205], v[102:105]
	v_mfma_f32_16x16x32_bf16 v[106:109], v[162:165], v[202:205], v[106:109]
	v_mfma_f32_16x16x32_bf16 v[110:113], v[154:157], v[210:213], v[110:113]
	v_mfma_f32_16x16x32_bf16 v[114:117], v[162:165], v[210:213], v[114:117]
	v_mfma_f32_16x16x32_bf16 v[118:121], v[154:157], v[218:221], v[118:121]
	v_mfma_f32_16x16x32_bf16 v[122:125], v[162:165], v[218:221], v[122:125]
	s_setprio 0
	s_barrier
	s_mov_b32 m0, s51
	v_lshl_add_u64 v[238:239], v[238:239], 0, s[0:1]
	ds_read_b128 v[222:225], v44
	ds_read_b128 v[226:229], v44 offset:1024
	ds_read_b128 v[230:233], v44 offset:2048
	ds_read_b128 v[234:237], v44 offset:3072
	global_load_lds_dwordx4 v[238:239], off
	v_lshl_add_u64 v[238:239], v[240:241], 0, s[0:1]
	s_mov_b32 m0, s52
	s_nop 0
	global_load_lds_dwordx4 v[238:239], off
	s_barrier
	s_waitcnt lgkmcnt(0)
	s_setprio 1
	s_waitcnt lgkmcnt(0)
	v_mfma_f32_16x16x32_bf16 v[142:145], v[222:225], v[166:169], v[142:145]
	v_mfma_f32_16x16x32_bf16 v[62:65], v[230:233], v[166:169], v[62:65]
	v_mfma_f32_16x16x32_bf16 v[66:69], v[222:225], v[198:201], v[66:69]
	v_mfma_f32_16x16x32_bf16 v[70:73], v[230:233], v[198:201], v[70:73]
	v_mfma_f32_16x16x32_bf16 v[74:77], v[222:225], v[206:209], v[74:77]
	v_mfma_f32_16x16x32_bf16 v[78:81], v[230:233], v[206:209], v[78:81]
	v_mfma_f32_16x16x32_bf16 v[82:85], v[222:225], v[214:217], v[82:85]
	v_mfma_f32_16x16x32_bf16 v[86:89], v[230:233], v[214:217], v[86:89]
	v_mfma_f32_16x16x32_bf16 v[142:145], v[226:229], v[170:173], v[142:145]
	v_mfma_f32_16x16x32_bf16 v[62:65], v[234:237], v[170:173], v[62:65]
	v_mfma_f32_16x16x32_bf16 v[66:69], v[226:229], v[202:205], v[66:69]
	v_mfma_f32_16x16x32_bf16 v[70:73], v[234:237], v[202:205], v[70:73]
	v_mfma_f32_16x16x32_bf16 v[74:77], v[226:229], v[210:213], v[74:77]
	v_mfma_f32_16x16x32_bf16 v[78:81], v[234:237], v[210:213], v[78:81]
	v_mfma_f32_16x16x32_bf16 v[82:85], v[226:229], v[218:221], v[82:85]
	v_mfma_f32_16x16x32_bf16 v[86:89], v[234:237], v[218:221], v[86:89]
	s_setprio 0
	s_mov_b32 m0, s40
	s_barrier
	ds_read_b128 v[166:169], v41 offset:49152
	ds_read_b128 v[170:173], v41 offset:50176
	ds_read_b128 v[198:201], v41 offset:51200
	ds_read_b128 v[202:205], v41 offset:52224
	ds_read_b128 v[206:209], v41 offset:53248
	ds_read_b128 v[210:213], v41 offset:54272
	ds_read_b128 v[214:217], v41 offset:55296
	ds_read_b128 v[218:221], v41 offset:56320
	global_load_lds_dwordx4 v[12:13], off
	s_mov_b32 m0, s41
	s_nop 0
	global_load_lds_dwordx4 v[14:15], off
	s_barrier
	s_waitcnt lgkmcnt(0)
	s_setprio 1
	s_waitcnt lgkmcnt(0)
	v_mfma_f32_16x16x32_bf16 v[174:177], v[150:153], v[166:169], v[174:177]
	v_mfma_f32_16x16x32_bf16 v[178:181], v[158:161], v[166:169], v[178:181]
	v_mfma_f32_16x16x32_bf16 v[182:185], v[150:153], v[198:201], v[182:185]
	v_mfma_f32_16x16x32_bf16 v[186:189], v[158:161], v[198:201], v[186:189]
	v_mfma_f32_16x16x32_bf16 v[190:193], v[150:153], v[206:209], v[190:193]
	v_mfma_f32_16x16x32_bf16 v[194:197], v[158:161], v[206:209], v[194:197]
	v_mfma_f32_16x16x32_bf16 v[46:49], v[150:153], v[214:217], v[46:49]
	v_mfma_f32_16x16x32_bf16 v[50:53], v[158:161], v[214:217], v[50:53]
	v_mfma_f32_16x16x32_bf16 v[174:177], v[154:157], v[170:173], v[174:177]
	v_mfma_f32_16x16x32_bf16 v[178:181], v[162:165], v[170:173], v[178:181]
	v_mfma_f32_16x16x32_bf16 v[182:185], v[154:157], v[202:205], v[182:185]
	v_mfma_f32_16x16x32_bf16 v[186:189], v[162:165], v[202:205], v[186:189]
	v_mfma_f32_16x16x32_bf16 v[190:193], v[154:157], v[210:213], v[190:193]
	v_mfma_f32_16x16x32_bf16 v[194:197], v[162:165], v[210:213], v[194:197]
	v_mfma_f32_16x16x32_bf16 v[46:49], v[154:157], v[218:221], v[46:49]
	v_mfma_f32_16x16x32_bf16 v[50:53], v[162:165], v[218:221], v[50:53]
	s_setprio 0
	s_barrier
	s_add_u32 s30, s30, 0x10080
	s_addc_u32 s31, s31, 0
	s_mov_b32 m0, s53
	v_lshl_add_u64 v[150:151], s[30:31], 0, v[2:3]
	global_load_lds_dwordx4 v[150:151], off
	v_lshl_add_u64 v[150:151], s[30:31], 0, v[4:5]
	s_mov_b32 m0, s54
	s_nop 0
	global_load_lds_dwordx4 v[150:151], off
	s_waitcnt vmcnt(6)
	s_barrier
	s_setprio 1
	v_mfma_f32_16x16x32_bf16 v[54:57], v[222:225], v[166:169], v[54:57]
	v_mfma_f32_16x16x32_bf16 v[58:61], v[230:233], v[166:169], v[58:61]
	v_mfma_f32_16x16x32_bf16 v[90:93], v[222:225], v[198:201], v[90:93]
	v_mfma_f32_16x16x32_bf16 v[134:137], v[230:233], v[198:201], v[134:137]
	v_mfma_f32_16x16x32_bf16 v[138:141], v[222:225], v[206:209], v[138:141]
	v_mfma_f32_16x16x32_bf16 v[146:149], v[230:233], v[206:209], v[146:149]
	v_mfma_f32_16x16x32_bf16 v[126:129], v[222:225], v[214:217], v[126:129]
	v_mfma_f32_16x16x32_bf16 v[130:133], v[230:233], v[214:217], v[130:133]
	v_mfma_f32_16x16x32_bf16 v[54:57], v[226:229], v[170:173], v[54:57]
	v_mfma_f32_16x16x32_bf16 v[58:61], v[234:237], v[170:173], v[58:61]
	v_mfma_f32_16x16x32_bf16 v[90:93], v[226:229], v[202:205], v[90:93]
	v_mfma_f32_16x16x32_bf16 v[134:137], v[234:237], v[202:205], v[134:137]
	v_mfma_f32_16x16x32_bf16 v[138:141], v[226:229], v[210:213], v[138:141]
	v_mfma_f32_16x16x32_bf16 v[146:149], v[234:237], v[210:213], v[146:149]
	v_mfma_f32_16x16x32_bf16 v[126:129], v[226:229], v[218:221], v[126:129]
	v_mfma_f32_16x16x32_bf16 v[130:133], v[234:237], v[218:221], v[130:133]
	s_setprio 0
	v_mov_b32_e32 v45, v1
	v_mov_b32_e32 v150, v39
	s_barrier
	v_cvt_pk_bf16_f32 v66, v66, v67
	v_cvt_pk_bf16_f32 v67, v68, v69
	v_cvt_pk_bf16_f32 v68, v70, v71
	v_cvt_pk_bf16_f32 v70, v110, v111
	v_cvt_pk_bf16_f32 v71, v112, v113
	v_add_u32_e32 v110, s44, v45
	v_lshlrev_b32_e32 v112, 3, v150
	v_ashrrev_i32_e32 v111, 31, v110
	v_ashrrev_i32_e32 v113, 31, v112
	v_lshlrev_b64 v[110:111], 11, v[110:111]
	v_lshl_add_u64 v[112:113], s[4:5], 0, v[112:113]
	v_lshl_add_u64 v[110:111], s[24:25], 0, v[110:111]
	v_cvt_pk_bf16_f32 v94, v94, v95
	v_cvt_pk_bf16_f32 v95, v96, v97
	v_cvt_pk_bf16_f32 v96, v98, v99
	v_cvt_pk_bf16_f32 v97, v100, v101
	v_lshl_add_u64 v[110:111], v[112:113], 1, v[110:111]
	v_cvt_pk_bf16_f32 v98, v142, v143
	v_cvt_pk_bf16_f32 v99, v144, v145
	v_cvt_pk_bf16_f32 v100, v62, v63
	v_cvt_pk_bf16_f32 v101, v64, v65
	global_store_dwordx4 v[110:111], v[94:97], off nt
	global_store_dwordx4 v[110:111], v[98:101], off offset:256 nt
	v_cvt_pk_bf16_f32 v69, v72, v73
	v_add_co_u32_e32 v96, vcc, s43, v110
	v_cvt_pk_bf16_f32 v72, v114, v115
	s_nop 0
	v_addc_co_u32_e32 v97, vcc, 0, v111, vcc
	v_add_co_u32_e32 v100, vcc, s39, v110
	v_cvt_pk_bf16_f32 v74, v74, v75
	s_nop 0
	v_addc_co_u32_e32 v101, vcc, 0, v111, vcc
	v_add_co_u32_e32 v114, vcc, s42, v110
	v_cvt_pk_bf16_f32 v75, v76, v77
	s_nop 0
	v_addc_co_u32_e32 v115, vcc, 0, v111, vcc
	v_cvt_pk_bf16_f32 v76, v78, v79
	v_cvt_pk_bf16_f32 v78, v118, v119
	v_add_co_u32_e32 v118, vcc, s55, v110
	v_cvt_pk_bf16_f32 v77, v80, v81
	s_nop 0
	v_addc_co_u32_e32 v119, vcc, 0, v111, vcc
	v_cvt_pk_bf16_f32 v80, v122, v123
	v_add_co_u32_e32 v122, vcc, s56, v110
	v_cvt_pk_bf16_f32 v46, v46, v47
	s_nop 0
	v_addc_co_u32_e32 v123, vcc, 0, v111, vcc
	v_cvt_pk_bf16_f32 v47, v48, v49
	v_cvt_pk_bf16_f32 v48, v50, v51
	v_cvt_pk_bf16_f32 v50, v126, v127
	s_add_u32 s4, s4, 0x100
	v_add_co_u32_e32 v126, vcc, s57, v110
	s_addc_u32 s5, s5, 0
	s_nop 0
	v_addc_co_u32_e32 v127, vcc, 0, v111, vcc
	v_cvt_pk_bf16_f32 v62, v102, v103
	v_cvt_pk_bf16_f32 v63, v104, v105
	v_cvt_pk_bf16_f32 v64, v106, v107
	v_cvt_pk_bf16_f32 v65, v108, v109
	v_cvt_pk_bf16_f32 v73, v116, v117
	v_cvt_pk_bf16_f32 v79, v120, v121
	v_cvt_pk_bf16_f32 v81, v124, v125
	v_cvt_pk_bf16_f32 v49, v52, v53
	v_cvt_pk_bf16_f32 v51, v128, v129
	v_cvt_pk_bf16_f32 v52, v130, v131
	v_cvt_pk_bf16_f32 v53, v132, v133
	s_mov_b32 s31, s59
	s_mov_b32 s30, s59
	s_mov_b64 s[34:35], s[28:29]
	s_cmp_lg_u32 s59, 4
	v_lshl_add_u64 v[94:95], v[110:111], 0, s[12:13]
	v_lshl_add_u64 v[98:99], v[110:111], 0, s[10:11]
	v_lshl_add_u64 v[112:113], v[110:111], 0, s[14:15]
	v_lshl_add_u64 v[116:117], v[110:111], 0, s[16:17]
	v_lshl_add_u64 v[120:121], v[110:111], 0, s[18:19]
	v_lshl_add_u64 v[124:125], v[110:111], 0, s[20:21]
	v_lshl_add_u64 v[128:129], v[110:111], 0, s[22:23]
	v_add_co_u32_e32 v110, vcc, s58, v110
	v_cvt_pk_bf16_f32 v82, v82, v83
	v_cvt_pk_bf16_f32 v83, v84, v85
	v_cvt_pk_bf16_f32 v84, v86, v87
	v_cvt_pk_bf16_f32 v85, v88, v89
	v_cvt_pk_bf16_f32 v86, v174, v175
	v_cvt_pk_bf16_f32 v87, v176, v177
	v_cvt_pk_bf16_f32 v88, v178, v179
	v_cvt_pk_bf16_f32 v89, v180, v181
	v_cvt_pk_bf16_f32 v54, v54, v55
	v_cvt_pk_bf16_f32 v55, v56, v57
	v_cvt_pk_bf16_f32 v56, v58, v59
	v_cvt_pk_bf16_f32 v57, v60, v61
	v_cvt_pk_bf16_f32 v58, v182, v183
	v_cvt_pk_bf16_f32 v59, v184, v185
	v_cvt_pk_bf16_f32 v60, v186, v187
	v_cvt_pk_bf16_f32 v61, v188, v189
	v_cvt_pk_bf16_f32 v90, v90, v91
	v_cvt_pk_bf16_f32 v91, v92, v93
	v_cvt_pk_bf16_f32 v92, v134, v135
	v_cvt_pk_bf16_f32 v93, v136, v137
	v_cvt_pk_bf16_f32 v102, v190, v191
	v_cvt_pk_bf16_f32 v103, v192, v193
	v_cvt_pk_bf16_f32 v104, v194, v195
	v_cvt_pk_bf16_f32 v105, v196, v197
	v_cvt_pk_bf16_f32 v106, v138, v139
	v_cvt_pk_bf16_f32 v107, v140, v141
	v_cvt_pk_bf16_f32 v108, v146, v147
	v_cvt_pk_bf16_f32 v109, v148, v149
	global_store_dwordx4 v[96:97], v[62:65], off nt
	global_store_dwordx4 v[94:95], v[66:69], off offset:256 nt
	global_store_dwordx4 v[100:101], v[70:73], off nt
	global_store_dwordx4 v[98:99], v[74:77], off offset:256 nt
	global_store_dwordx4 v[114:115], v[78:81], off nt
	global_store_dwordx4 v[112:113], v[82:85], off offset:256 nt
	global_store_dwordx4 v[118:119], v[86:89], off nt
	global_store_dwordx4 v[116:117], v[54:57], off offset:256 nt
	global_store_dwordx4 v[122:123], v[58:61], off nt
	global_store_dwordx4 v[120:121], v[90:93], off offset:256 nt
	global_store_dwordx4 v[126:127], v[102:105], off nt
	global_store_dwordx4 v[124:125], v[106:109], off offset:256 nt
	v_addc_co_u32_e32 v111, vcc, 0, v111, vcc
	global_store_dwordx4 v[128:129], v[50:53], off offset:256 nt
	global_store_dwordx4 v[110:111], v[46:49], off nt
	s_cbranch_scc1 .LBB0_517
	s_waitcnt vmcnt(0)
	s_cmpk_gt_u32 s3, 0xff
	s_cbranch_scc1 .LBB0_520
	s_barrier

.LBB0_553:
	s_add_i32 s72, s41, 1
	s_cmp_lt_u32 s41, 3
	s_cselect_b64 s[74:75], -1, 0
	s_and_b64 s[38:39], s[74:75], exec
	s_cselect_b32 s38, s72, s40
	ds_read_b128 v[44:47], v39
	ds_read_b128 v[48:51], v39 offset:1024
	ds_read_b128 v[52:55], v39 offset:2048
	ds_read_b128 v[56:59], v39 offset:3072
	s_ashr_i32 s39, s38, 31
	s_lshl_b64 s[38:39], s[38:39], 17
	s_add_u32 s38, s84, s38
	s_addc_u32 s39, s85, s39
	s_and_b64 s[40:41], s[74:75], exec
	s_cselect_b32 s41, s39, s43
	s_cselect_b32 s40, s38, s42
	s_mov_b32 m0, s58
	ds_read_b128 v[60:63], v40
	ds_read_b128 v[64:67], v40 offset:1024
	ds_read_b128 v[68:71], v40 offset:2048
	ds_read_b128 v[72:75], v40 offset:3072
	ds_read_b128 v[76:79], v40 offset:4096
	ds_read_b128 v[80:83], v40 offset:5120
	ds_read_b128 v[84:87], v40 offset:6144
	ds_read_b128 v[88:91], v40 offset:7168
	global_load_lds_dwordx4 v[18:19], off
	s_mov_b32 m0, s59
	s_nop 0
	global_load_lds_dwordx4 v[20:21], off
	s_waitcnt lgkmcnt(8)
	s_barrier
	s_waitcnt lgkmcnt(0)
	s_setprio 1
	s_waitcnt lgkmcnt(0)
	v_mfma_f32_16x16x32_bf16 v[92:95], v[44:47], v[60:63], 0
	v_mfma_f32_16x16x32_bf16 v[96:99], v[52:55], v[60:63], 0
	v_mfma_f32_16x16x32_bf16 v[100:103], v[44:47], v[68:71], 0
	v_mfma_f32_16x16x32_bf16 v[104:107], v[52:55], v[68:71], 0
	v_mfma_f32_16x16x32_bf16 v[108:111], v[44:47], v[76:79], 0
	v_mfma_f32_16x16x32_bf16 v[112:115], v[52:55], v[76:79], 0
	v_mfma_f32_16x16x32_bf16 v[116:119], v[44:47], v[84:87], 0
	v_mfma_f32_16x16x32_bf16 v[120:123], v[52:55], v[84:87], 0
	v_mfma_f32_16x16x32_bf16 v[92:95], v[48:51], v[64:67], v[92:95]
	v_mfma_f32_16x16x32_bf16 v[96:99], v[56:59], v[64:67], v[96:99]
	v_mfma_f32_16x16x32_bf16 v[100:103], v[48:51], v[72:75], v[100:103]
	v_mfma_f32_16x16x32_bf16 v[104:107], v[56:59], v[72:75], v[104:107]
	v_mfma_f32_16x16x32_bf16 v[108:111], v[48:51], v[80:83], v[108:111]
	v_mfma_f32_16x16x32_bf16 v[112:115], v[56:59], v[80:83], v[112:115]
	v_mfma_f32_16x16x32_bf16 v[116:119], v[48:51], v[88:91], v[116:119]
	v_mfma_f32_16x16x32_bf16 v[120:123], v[56:59], v[88:91], v[120:123]
	s_setprio 0
	s_barrier
	v_lshl_add_u64 v[242:243], s[42:43], 0, v[4:5]
	s_mov_b32 m0, s60
	v_lshl_add_u64 v[140:141], v[242:243], 0, s[12:13]
	v_lshl_add_u64 v[244:245], s[42:43], 0, v[2:3]
	ds_read_b128 v[124:127], v41
	ds_read_b128 v[128:131], v41 offset:1024
	ds_read_b128 v[132:135], v41 offset:2048
	ds_read_b128 v[136:139], v41 offset:3072
	global_load_lds_dwordx4 v[140:141], off
	v_lshl_add_u64 v[140:141], v[244:245], 0, s[12:13]
	s_mov_b32 m0, s61
	s_nop 0
	global_load_lds_dwordx4 v[140:141], off
	s_barrier
	s_waitcnt lgkmcnt(0)
	s_setprio 1
	s_waitcnt lgkmcnt(0)
	v_mfma_f32_16x16x32_bf16 v[140:143], v[124:127], v[60:63], 0
	v_mfma_f32_16x16x32_bf16 v[60:63], v[132:135], v[60:63], 0
	v_mfma_f32_16x16x32_bf16 v[140:143], v[128:131], v[64:67], v[140:143]
	v_mfma_f32_16x16x32_bf16 v[60:63], v[136:139], v[64:67], v[60:63]
	v_mfma_f32_16x16x32_bf16 v[64:67], v[124:127], v[68:71], 0
	v_mfma_f32_16x16x32_bf16 v[68:71], v[132:135], v[68:71], 0
	v_mfma_f32_16x16x32_bf16 v[64:67], v[128:131], v[72:75], v[64:67]
	v_mfma_f32_16x16x32_bf16 v[68:71], v[136:139], v[72:75], v[68:71]
	v_mfma_f32_16x16x32_bf16 v[72:75], v[124:127], v[76:79], 0
	v_mfma_f32_16x16x32_bf16 v[76:79], v[132:135], v[76:79], 0
	v_mfma_f32_16x16x32_bf16 v[72:75], v[128:131], v[80:83], v[72:75]
	v_mfma_f32_16x16x32_bf16 v[76:79], v[136:139], v[80:83], v[76:79]
	v_mfma_f32_16x16x32_bf16 v[80:83], v[124:127], v[84:87], 0
	v_mfma_f32_16x16x32_bf16 v[84:87], v[132:135], v[84:87], 0
	v_mfma_f32_16x16x32_bf16 v[80:83], v[128:131], v[88:91], v[80:83]
	v_mfma_f32_16x16x32_bf16 v[84:87], v[136:139], v[88:91], v[84:87]
	s_setprio 0
	s_mov_b32 m0, s3
	s_barrier
	ds_read_b128 v[88:91], v40 offset:16384
	ds_read_b128 v[144:147], v40 offset:17408
	ds_read_b128 v[148:151], v40 offset:18432
	ds_read_b128 v[152:155], v40 offset:19456
	ds_read_b128 v[156:159], v40 offset:20480
	ds_read_b128 v[160:163], v40 offset:21504
	ds_read_b128 v[164:167], v40 offset:22528
	ds_read_b128 v[168:171], v40 offset:23552
	global_load_lds_dwordx4 v[22:23], off
	s_mov_b32 m0, s49
	s_nop 0
	global_load_lds_dwordx4 v[24:25], off
	s_barrier
	s_waitcnt lgkmcnt(0)
	s_setprio 1
	s_waitcnt lgkmcnt(0)
	v_mfma_f32_16x16x32_bf16 v[172:175], v[44:47], v[88:91], 0
	v_mfma_f32_16x16x32_bf16 v[180:183], v[44:47], v[148:151], 0
	v_mfma_f32_16x16x32_bf16 v[194:197], v[44:47], v[156:159], 0
	v_mfma_f32_16x16x32_bf16 v[44:47], v[44:47], v[164:167], 0
	v_mfma_f32_16x16x32_bf16 v[172:175], v[48:51], v[144:147], v[172:175]
	v_mfma_f32_16x16x32_bf16 v[176:179], v[52:55], v[88:91], 0
	v_mfma_f32_16x16x32_bf16 v[180:183], v[48:51], v[152:155], v[180:183]
	v_mfma_f32_16x16x32_bf16 v[190:193], v[52:55], v[148:151], 0
	v_mfma_f32_16x16x32_bf16 v[194:197], v[48:51], v[160:163], v[194:197]
	v_mfma_f32_16x16x32_bf16 v[198:201], v[52:55], v[156:159], 0
	v_mfma_f32_16x16x32_bf16 v[44:47], v[48:51], v[168:171], v[44:47]
	v_mfma_f32_16x16x32_bf16 v[48:51], v[52:55], v[164:167], 0
	v_mfma_f32_16x16x32_bf16 v[176:179], v[56:59], v[144:147], v[176:179]
	v_mfma_f32_16x16x32_bf16 v[190:193], v[56:59], v[152:155], v[190:193]
	v_mfma_f32_16x16x32_bf16 v[198:201], v[56:59], v[160:163], v[198:201]
	v_mfma_f32_16x16x32_bf16 v[48:51], v[56:59], v[168:171], v[48:51]
	s_setprio 0
	s_barrier
	s_add_u32 s74, s42, 0x10100
	s_addc_u32 s75, s43, 0
	s_mov_b32 m0, s62
	v_lshl_add_u64 v[52:53], s[74:75], 0, v[4:5]
	global_load_lds_dwordx4 v[52:53], off
	v_lshl_add_u64 v[52:53], s[74:75], 0, v[2:3]
	s_mov_b32 m0, s63
	s_nop 0
	global_load_lds_dwordx4 v[52:53], off
	s_waitcnt vmcnt(6)
	s_barrier
	s_setprio 1
	v_mfma_f32_16x16x32_bf16 v[52:55], v[124:127], v[88:91], 0
	v_mfma_f32_16x16x32_bf16 v[56:59], v[132:135], v[88:91], 0
	v_mfma_f32_16x16x32_bf16 v[52:55], v[128:131], v[144:147], v[52:55]
	v_mfma_f32_16x16x32_bf16 v[56:59], v[136:139], v[144:147], v[56:59]
	v_mfma_f32_16x16x32_bf16 v[88:91], v[124:127], v[148:151], 0
	v_mfma_f32_16x16x32_bf16 v[144:147], v[132:135], v[148:151], 0
	v_mfma_f32_16x16x32_bf16 v[148:151], v[124:127], v[156:159], 0
	v_mfma_f32_16x16x32_bf16 v[124:127], v[124:127], v[164:167], 0
	v_mfma_f32_16x16x32_bf16 v[88:91], v[128:131], v[152:155], v[88:91]
	v_mfma_f32_16x16x32_bf16 v[144:147], v[136:139], v[152:155], v[144:147]
	v_mfma_f32_16x16x32_bf16 v[148:151], v[128:131], v[160:163], v[148:151]
	v_mfma_f32_16x16x32_bf16 v[152:155], v[132:135], v[156:159], 0
	v_mfma_f32_16x16x32_bf16 v[124:127], v[128:131], v[168:171], v[124:127]
	v_mfma_f32_16x16x32_bf16 v[128:131], v[132:135], v[164:167], 0
	v_mfma_f32_16x16x32_bf16 v[152:155], v[136:139], v[160:163], v[152:155]
	v_mfma_f32_16x16x32_bf16 v[128:131], v[136:139], v[168:171], v[128:131]
	s_setprio 0
	s_barrier
	ds_read_b128 v[132:135], v42
	ds_read_b128 v[136:139], v42 offset:1024
	ds_read_b128 v[156:159], v42 offset:2048
	ds_read_b128 v[160:163], v42 offset:3072
	s_mov_b32 m0, s50
	ds_read_b128 v[164:167], v40 offset:32768
	ds_read_b128 v[168:171], v40 offset:33792
	ds_read_b128 v[202:205], v40 offset:34816
	ds_read_b128 v[206:209], v40 offset:35840
	ds_read_b128 v[210:213], v40 offset:36864
	ds_read_b128 v[214:217], v40 offset:37888
	ds_read_b128 v[218:221], v40 offset:38912
	ds_read_b128 v[222:225], v40 offset:39936
	global_load_lds_dwordx4 v[26:27], off
	s_mov_b32 m0, s51
	s_nop 0
	global_load_lds_dwordx4 v[28:29], off
	s_waitcnt lgkmcnt(8)
	s_barrier
	s_waitcnt lgkmcnt(0)
	s_setprio 1
	s_waitcnt lgkmcnt(0)
	v_mfma_f32_16x16x32_bf16 v[92:95], v[132:135], v[164:167], v[92:95]
	v_mfma_f32_16x16x32_bf16 v[96:99], v[156:159], v[164:167], v[96:99]
	v_mfma_f32_16x16x32_bf16 v[100:103], v[132:135], v[202:205], v[100:103]
	v_mfma_f32_16x16x32_bf16 v[104:107], v[156:159], v[202:205], v[104:107]
	v_mfma_f32_16x16x32_bf16 v[108:111], v[132:135], v[210:213], v[108:111]
	v_mfma_f32_16x16x32_bf16 v[112:115], v[156:159], v[210:213], v[112:115]
	v_mfma_f32_16x16x32_bf16 v[116:119], v[132:135], v[218:221], v[116:119]
	v_mfma_f32_16x16x32_bf16 v[120:123], v[156:159], v[218:221], v[120:123]
	v_mfma_f32_16x16x32_bf16 v[92:95], v[136:139], v[168:171], v[92:95]
	v_mfma_f32_16x16x32_bf16 v[96:99], v[160:163], v[168:171], v[96:99]
	v_mfma_f32_16x16x32_bf16 v[100:103], v[136:139], v[206:209], v[100:103]
	v_mfma_f32_16x16x32_bf16 v[104:107], v[160:163], v[206:209], v[104:107]
	v_mfma_f32_16x16x32_bf16 v[108:111], v[136:139], v[214:217], v[108:111]
	v_mfma_f32_16x16x32_bf16 v[112:115], v[160:163], v[214:217], v[112:115]
	v_mfma_f32_16x16x32_bf16 v[116:119], v[136:139], v[222:225], v[116:119]
	v_mfma_f32_16x16x32_bf16 v[120:123], v[160:163], v[222:225], v[120:123]
	s_setprio 0
	s_barrier
	s_mov_b32 m0, s64
	v_lshl_add_u64 v[242:243], v[242:243], 0, s[14:15]
	ds_read_b128 v[226:229], v43
	ds_read_b128 v[230:233], v43 offset:1024
	ds_read_b128 v[234:237], v43 offset:2048
	ds_read_b128 v[238:241], v43 offset:3072
	global_load_lds_dwordx4 v[242:243], off
	v_lshl_add_u64 v[242:243], v[244:245], 0, s[14:15]
	s_mov_b32 m0, s65
	s_nop 0
	global_load_lds_dwordx4 v[242:243], off
	s_barrier
	s_waitcnt lgkmcnt(0)
	s_setprio 1
	s_waitcnt lgkmcnt(0)
	v_mfma_f32_16x16x32_bf16 v[140:143], v[226:229], v[164:167], v[140:143]
	v_mfma_f32_16x16x32_bf16 v[60:63], v[234:237], v[164:167], v[60:63]
	v_mfma_f32_16x16x32_bf16 v[64:67], v[226:229], v[202:205], v[64:67]
	v_mfma_f32_16x16x32_bf16 v[68:71], v[234:237], v[202:205], v[68:71]
	v_mfma_f32_16x16x32_bf16 v[72:75], v[226:229], v[210:213], v[72:75]
	v_mfma_f32_16x16x32_bf16 v[76:79], v[234:237], v[210:213], v[76:79]
	v_mfma_f32_16x16x32_bf16 v[80:83], v[226:229], v[218:221], v[80:83]
	v_mfma_f32_16x16x32_bf16 v[84:87], v[234:237], v[218:221], v[84:87]
	v_mfma_f32_16x16x32_bf16 v[140:143], v[230:233], v[168:171], v[140:143]
	v_mfma_f32_16x16x32_bf16 v[60:63], v[238:241], v[168:171], v[60:63]
	v_mfma_f32_16x16x32_bf16 v[64:67], v[230:233], v[206:209], v[64:67]
	v_mfma_f32_16x16x32_bf16 v[68:71], v[238:241], v[206:209], v[68:71]
	v_mfma_f32_16x16x32_bf16 v[72:75], v[230:233], v[214:217], v[72:75]
	v_mfma_f32_16x16x32_bf16 v[76:79], v[238:241], v[214:217], v[76:79]
	v_mfma_f32_16x16x32_bf16 v[80:83], v[230:233], v[222:225], v[80:83]
	v_mfma_f32_16x16x32_bf16 v[84:87], v[238:241], v[222:225], v[84:87]
	s_setprio 0
	s_mov_b32 m0, s53
	s_barrier
	ds_read_b128 v[164:167], v40 offset:49152
	ds_read_b128 v[168:171], v40 offset:50176
	ds_read_b128 v[202:205], v40 offset:51200
	ds_read_b128 v[206:209], v40 offset:52224
	ds_read_b128 v[210:213], v40 offset:53248
	ds_read_b128 v[214:217], v40 offset:54272
	ds_read_b128 v[218:221], v40 offset:55296
	ds_read_b128 v[222:225], v40 offset:56320
	global_load_lds_dwordx4 v[30:31], off
	s_mov_b32 m0, s54
	s_nop 0
	global_load_lds_dwordx4 v[32:33], off
	s_barrier
	s_waitcnt lgkmcnt(0)
	s_setprio 1
	s_waitcnt lgkmcnt(0)
	v_mfma_f32_16x16x32_bf16 v[172:175], v[132:135], v[164:167], v[172:175]
	v_mfma_f32_16x16x32_bf16 v[176:179], v[156:159], v[164:167], v[176:179]
	v_mfma_f32_16x16x32_bf16 v[180:183], v[132:135], v[202:205], v[180:183]
	v_mfma_f32_16x16x32_bf16 v[190:193], v[156:159], v[202:205], v[190:193]
	v_mfma_f32_16x16x32_bf16 v[194:197], v[132:135], v[210:213], v[194:197]
	v_mfma_f32_16x16x32_bf16 v[198:201], v[156:159], v[210:213], v[198:201]
	v_mfma_f32_16x16x32_bf16 v[44:47], v[132:135], v[218:221], v[44:47]
	v_mfma_f32_16x16x32_bf16 v[48:51], v[156:159], v[218:221], v[48:51]
	v_mfma_f32_16x16x32_bf16 v[172:175], v[136:139], v[168:171], v[172:175]
	v_mfma_f32_16x16x32_bf16 v[176:179], v[160:163], v[168:171], v[176:179]
	v_mfma_f32_16x16x32_bf16 v[180:183], v[136:139], v[206:209], v[180:183]
	v_mfma_f32_16x16x32_bf16 v[190:193], v[160:163], v[206:209], v[190:193]
	v_mfma_f32_16x16x32_bf16 v[194:197], v[136:139], v[214:217], v[194:197]
	v_mfma_f32_16x16x32_bf16 v[198:201], v[160:163], v[214:217], v[198:201]
	v_mfma_f32_16x16x32_bf16 v[44:47], v[136:139], v[222:225], v[44:47]
	v_mfma_f32_16x16x32_bf16 v[48:51], v[160:163], v[222:225], v[48:51]
	s_setprio 0
	s_barrier
	s_add_u32 s42, s42, 0x10180
	s_addc_u32 s43, s43, 0
	s_mov_b32 m0, s66
	v_lshl_add_u64 v[132:133], s[42:43], 0, v[4:5]
	global_load_lds_dwordx4 v[132:133], off
	v_lshl_add_u64 v[132:133], s[42:43], 0, v[2:3]
	s_mov_b32 m0, s67
	s_nop 0
	global_load_lds_dwordx4 v[132:133], off
	s_waitcnt vmcnt(6)
	s_barrier
	s_setprio 1
	v_mfma_f32_16x16x32_bf16 v[52:55], v[226:229], v[164:167], v[52:55]
	v_mfma_f32_16x16x32_bf16 v[56:59], v[234:237], v[164:167], v[56:59]
	v_mfma_f32_16x16x32_bf16 v[88:91], v[226:229], v[202:205], v[88:91]
	v_mfma_f32_16x16x32_bf16 v[132:135], v[234:237], v[202:205], v[144:147]
	v_mfma_f32_16x16x32_bf16 v[136:139], v[226:229], v[210:213], v[148:151]
	v_mfma_f32_16x16x32_bf16 v[144:147], v[234:237], v[210:213], v[152:155]
	v_mfma_f32_16x16x32_bf16 v[124:127], v[226:229], v[218:221], v[124:127]
	v_mfma_f32_16x16x32_bf16 v[128:131], v[234:237], v[218:221], v[128:131]
	v_mfma_f32_16x16x32_bf16 v[52:55], v[230:233], v[168:171], v[52:55]
	v_mfma_f32_16x16x32_bf16 v[56:59], v[238:241], v[168:171], v[56:59]
	v_mfma_f32_16x16x32_bf16 v[88:91], v[230:233], v[206:209], v[88:91]
	v_mfma_f32_16x16x32_bf16 v[132:135], v[238:241], v[206:209], v[132:135]
	v_mfma_f32_16x16x32_bf16 v[136:139], v[230:233], v[214:217], v[136:139]
	v_mfma_f32_16x16x32_bf16 v[144:147], v[238:241], v[214:217], v[144:147]
	v_mfma_f32_16x16x32_bf16 v[124:127], v[230:233], v[222:225], v[124:127]
	v_mfma_f32_16x16x32_bf16 v[128:131], v[238:241], v[222:225], v[128:131]
	s_setprio 0
	s_barrier
	ds_read_b128 v[148:151], v39
	ds_read_b128 v[152:155], v39 offset:1024
	ds_read_b128 v[156:159], v39 offset:2048
	ds_read_b128 v[160:163], v39 offset:3072
	s_mov_b32 m0, s58
	ds_read_b128 v[164:167], v40
	ds_read_b128 v[168:171], v40 offset:1024
	ds_read_b128 v[202:205], v40 offset:2048
	ds_read_b128 v[206:209], v40 offset:3072
	ds_read_b128 v[210:213], v40 offset:4096
	ds_read_b128 v[214:217], v40 offset:5120
	ds_read_b128 v[218:221], v40 offset:6144
	ds_read_b128 v[222:225], v40 offset:7168
	global_load_lds_dwordx4 v[34:35], off
	s_mov_b32 m0, s59
	s_nop 0
	global_load_lds_dwordx4 v[36:37], off
	s_waitcnt lgkmcnt(8)
	s_barrier
	s_waitcnt lgkmcnt(0)
	s_setprio 1
	s_waitcnt lgkmcnt(0)
	v_mfma_f32_16x16x32_bf16 v[92:95], v[148:151], v[164:167], v[92:95]
	v_mfma_f32_16x16x32_bf16 v[96:99], v[156:159], v[164:167], v[96:99]
	v_mfma_f32_16x16x32_bf16 v[100:103], v[148:151], v[202:205], v[100:103]
	v_mfma_f32_16x16x32_bf16 v[104:107], v[156:159], v[202:205], v[104:107]
	v_mfma_f32_16x16x32_bf16 v[108:111], v[148:151], v[210:213], v[108:111]
	v_mfma_f32_16x16x32_bf16 v[112:115], v[156:159], v[210:213], v[112:115]
	v_mfma_f32_16x16x32_bf16 v[116:119], v[148:151], v[218:221], v[116:119]
	v_mfma_f32_16x16x32_bf16 v[120:123], v[156:159], v[218:221], v[120:123]
	v_mfma_f32_16x16x32_bf16 v[92:95], v[152:155], v[168:171], v[92:95]
	v_mfma_f32_16x16x32_bf16 v[96:99], v[160:163], v[168:171], v[96:99]
	v_mfma_f32_16x16x32_bf16 v[100:103], v[152:155], v[206:209], v[100:103]
	v_mfma_f32_16x16x32_bf16 v[104:107], v[160:163], v[206:209], v[104:107]
	v_mfma_f32_16x16x32_bf16 v[108:111], v[152:155], v[214:217], v[108:111]
	v_mfma_f32_16x16x32_bf16 v[112:115], v[160:163], v[214:217], v[112:115]
	v_mfma_f32_16x16x32_bf16 v[116:119], v[152:155], v[222:225], v[116:119]
	v_mfma_f32_16x16x32_bf16 v[120:123], v[160:163], v[222:225], v[120:123]
	s_setprio 0
	s_barrier
	s_mov_b32 m0, s60
	v_lshl_add_u64 v[242:243], s[40:41], 0, v[4:5]
	ds_read_b128 v[226:229], v41
	ds_read_b128 v[230:233], v41 offset:1024
	ds_read_b128 v[234:237], v41 offset:2048
	ds_read_b128 v[238:241], v41 offset:3072
	global_load_lds_dwordx4 v[242:243], off
	v_lshl_add_u64 v[244:245], s[40:41], 0, v[2:3]
	s_mov_b32 m0, s61
	s_nop 0
	global_load_lds_dwordx4 v[244:245], off
	s_barrier
	s_waitcnt lgkmcnt(0)
	s_setprio 1
	s_waitcnt lgkmcnt(0)
	v_mfma_f32_16x16x32_bf16 v[140:143], v[226:229], v[164:167], v[140:143]
	v_mfma_f32_16x16x32_bf16 v[60:63], v[234:237], v[164:167], v[60:63]
	v_mfma_f32_16x16x32_bf16 v[64:67], v[226:229], v[202:205], v[64:67]
	v_mfma_f32_16x16x32_bf16 v[68:71], v[234:237], v[202:205], v[68:71]
	v_mfma_f32_16x16x32_bf16 v[72:75], v[226:229], v[210:213], v[72:75]
	v_mfma_f32_16x16x32_bf16 v[76:79], v[234:237], v[210:213], v[76:79]
	v_mfma_f32_16x16x32_bf16 v[80:83], v[226:229], v[218:221], v[80:83]
	v_mfma_f32_16x16x32_bf16 v[84:87], v[234:237], v[218:221], v[84:87]
	v_mfma_f32_16x16x32_bf16 v[140:143], v[230:233], v[168:171], v[140:143]
	v_mfma_f32_16x16x32_bf16 v[60:63], v[238:241], v[168:171], v[60:63]
	v_mfma_f32_16x16x32_bf16 v[64:67], v[230:233], v[206:209], v[64:67]
	v_mfma_f32_16x16x32_bf16 v[68:71], v[238:241], v[206:209], v[68:71]
	v_mfma_f32_16x16x32_bf16 v[72:75], v[230:233], v[214:217], v[72:75]
	v_mfma_f32_16x16x32_bf16 v[76:79], v[238:241], v[214:217], v[76:79]
	v_mfma_f32_16x16x32_bf16 v[80:83], v[230:233], v[222:225], v[80:83]
	v_mfma_f32_16x16x32_bf16 v[84:87], v[238:241], v[222:225], v[84:87]
	s_setprio 0
	s_mov_b32 m0, s3
	s_barrier
	ds_read_b128 v[164:167], v40 offset:16384
	ds_read_b128 v[168:171], v40 offset:17408
	ds_read_b128 v[202:205], v40 offset:18432
	ds_read_b128 v[206:209], v40 offset:19456
	ds_read_b128 v[210:213], v40 offset:20480
	ds_read_b128 v[214:217], v40 offset:21504
	ds_read_b128 v[218:221], v40 offset:22528
	ds_read_b128 v[222:225], v40 offset:23552
	global_load_lds_dwordx4 v[6:7], off
	s_mov_b32 m0, s49
	s_nop 0
	global_load_lds_dwordx4 v[8:9], off
	s_barrier
	s_waitcnt lgkmcnt(0)
	s_setprio 1
	s_waitcnt lgkmcnt(0)
	v_mfma_f32_16x16x32_bf16 v[172:175], v[148:151], v[164:167], v[172:175]
	v_mfma_f32_16x16x32_bf16 v[176:179], v[156:159], v[164:167], v[176:179]
	v_mfma_f32_16x16x32_bf16 v[180:183], v[148:151], v[202:205], v[180:183]
	v_mfma_f32_16x16x32_bf16 v[190:193], v[156:159], v[202:205], v[190:193]
	v_mfma_f32_16x16x32_bf16 v[194:197], v[148:151], v[210:213], v[194:197]
	v_mfma_f32_16x16x32_bf16 v[198:201], v[156:159], v[210:213], v[198:201]
	v_mfma_f32_16x16x32_bf16 v[44:47], v[148:151], v[218:221], v[44:47]
	v_mfma_f32_16x16x32_bf16 v[48:51], v[156:159], v[218:221], v[48:51]
	v_mfma_f32_16x16x32_bf16 v[172:175], v[152:155], v[168:171], v[172:175]
	v_mfma_f32_16x16x32_bf16 v[176:179], v[160:163], v[168:171], v[176:179]
	v_mfma_f32_16x16x32_bf16 v[180:183], v[152:155], v[206:209], v[180:183]
	v_mfma_f32_16x16x32_bf16 v[190:193], v[160:163], v[206:209], v[190:193]
	v_mfma_f32_16x16x32_bf16 v[194:197], v[152:155], v[214:217], v[194:197]
	v_mfma_f32_16x16x32_bf16 v[198:201], v[160:163], v[214:217], v[198:201]
	v_mfma_f32_16x16x32_bf16 v[44:47], v[152:155], v[222:225], v[44:47]
	v_mfma_f32_16x16x32_bf16 v[48:51], v[160:163], v[222:225], v[48:51]
	s_setprio 0
	s_barrier
	s_add_u32 s42, s40, 0x10000
	s_addc_u32 s43, s41, 0
	s_mov_b32 m0, s62
	v_lshl_add_u64 v[148:149], s[42:43], 0, v[4:5]
	global_load_lds_dwordx4 v[148:149], off
	v_lshl_add_u64 v[148:149], s[42:43], 0, v[2:3]
	s_mov_b32 m0, s63
	s_nop 0
	global_load_lds_dwordx4 v[148:149], off
	s_waitcnt vmcnt(6)
	s_barrier
	s_setprio 1
	v_mfma_f32_16x16x32_bf16 v[52:55], v[226:229], v[164:167], v[52:55]
	v_mfma_f32_16x16x32_bf16 v[56:59], v[234:237], v[164:167], v[56:59]
	v_mfma_f32_16x16x32_bf16 v[88:91], v[226:229], v[202:205], v[88:91]
	v_mfma_f32_16x16x32_bf16 v[132:135], v[234:237], v[202:205], v[132:135]
	v_mfma_f32_16x16x32_bf16 v[136:139], v[226:229], v[210:213], v[136:139]
	v_mfma_f32_16x16x32_bf16 v[144:147], v[234:237], v[210:213], v[144:147]
	v_mfma_f32_16x16x32_bf16 v[124:127], v[226:229], v[218:221], v[124:127]
	v_mfma_f32_16x16x32_bf16 v[128:131], v[234:237], v[218:221], v[128:131]
	v_mfma_f32_16x16x32_bf16 v[52:55], v[230:233], v[168:171], v[52:55]
	v_mfma_f32_16x16x32_bf16 v[56:59], v[238:241], v[168:171], v[56:59]
	v_mfma_f32_16x16x32_bf16 v[88:91], v[230:233], v[206:209], v[88:91]
	v_mfma_f32_16x16x32_bf16 v[132:135], v[238:241], v[206:209], v[132:135]
	v_mfma_f32_16x16x32_bf16 v[136:139], v[230:233], v[214:217], v[136:139]
	v_mfma_f32_16x16x32_bf16 v[144:147], v[238:241], v[214:217], v[144:147]
	v_mfma_f32_16x16x32_bf16 v[124:127], v[230:233], v[222:225], v[124:127]
	v_mfma_f32_16x16x32_bf16 v[128:131], v[238:241], v[222:225], v[128:131]
	s_setprio 0
	s_barrier
	ds_read_b128 v[148:151], v42
	ds_read_b128 v[152:155], v42 offset:1024
	ds_read_b128 v[156:159], v42 offset:2048
	ds_read_b128 v[160:163], v42 offset:3072
	s_mov_b32 m0, s50
	ds_read_b128 v[164:167], v40 offset:32768
	ds_read_b128 v[168:171], v40 offset:33792
	ds_read_b128 v[202:205], v40 offset:34816
	ds_read_b128 v[206:209], v40 offset:35840
	ds_read_b128 v[210:213], v40 offset:36864
	ds_read_b128 v[214:217], v40 offset:37888
	ds_read_b128 v[218:221], v40 offset:38912
	ds_read_b128 v[222:225], v40 offset:39936
	global_load_lds_dwordx4 v[14:15], off
	s_mov_b32 m0, s51
	s_nop 0
	global_load_lds_dwordx4 v[16:17], off
	s_waitcnt lgkmcnt(8)
	s_barrier
	s_waitcnt lgkmcnt(0)
	s_setprio 1
	s_waitcnt lgkmcnt(0)
	v_mfma_f32_16x16x32_bf16 v[92:95], v[148:151], v[164:167], v[92:95]
	v_mfma_f32_16x16x32_bf16 v[96:99], v[156:159], v[164:167], v[96:99]
	v_mfma_f32_16x16x32_bf16 v[100:103], v[148:151], v[202:205], v[100:103]
	v_mfma_f32_16x16x32_bf16 v[104:107], v[156:159], v[202:205], v[104:107]
	v_mfma_f32_16x16x32_bf16 v[108:111], v[148:151], v[210:213], v[108:111]
	v_mfma_f32_16x16x32_bf16 v[112:115], v[156:159], v[210:213], v[112:115]
	v_mfma_f32_16x16x32_bf16 v[116:119], v[148:151], v[218:221], v[116:119]
	v_mfma_f32_16x16x32_bf16 v[120:123], v[156:159], v[218:221], v[120:123]
	v_mfma_f32_16x16x32_bf16 v[92:95], v[152:155], v[168:171], v[92:95]
	v_mfma_f32_16x16x32_bf16 v[96:99], v[160:163], v[168:171], v[96:99]
	v_mfma_f32_16x16x32_bf16 v[100:103], v[152:155], v[206:209], v[100:103]
	v_mfma_f32_16x16x32_bf16 v[104:107], v[160:163], v[206:209], v[104:107]
	v_mfma_f32_16x16x32_bf16 v[108:111], v[152:155], v[214:217], v[108:111]
	v_mfma_f32_16x16x32_bf16 v[112:115], v[160:163], v[214:217], v[112:115]
	v_mfma_f32_16x16x32_bf16 v[116:119], v[152:155], v[222:225], v[116:119]
	v_mfma_f32_16x16x32_bf16 v[120:123], v[160:163], v[222:225], v[120:123]
	s_setprio 0
	s_barrier
	s_mov_b32 m0, s64
	v_lshl_add_u64 v[242:243], v[242:243], 0, s[0:1]
	ds_read_b128 v[226:229], v43
	ds_read_b128 v[230:233], v43 offset:1024
	ds_read_b128 v[234:237], v43 offset:2048
	ds_read_b128 v[238:241], v43 offset:3072
	global_load_lds_dwordx4 v[242:243], off
	v_lshl_add_u64 v[242:243], v[244:245], 0, s[0:1]
	s_mov_b32 m0, s65
	s_nop 0
	global_load_lds_dwordx4 v[242:243], off
	s_barrier
	s_waitcnt lgkmcnt(0)
	s_setprio 1
	s_waitcnt lgkmcnt(0)
	v_mfma_f32_16x16x32_bf16 v[140:143], v[226:229], v[164:167], v[140:143]
	v_mfma_f32_16x16x32_bf16 v[60:63], v[234:237], v[164:167], v[60:63]
	v_mfma_f32_16x16x32_bf16 v[64:67], v[226:229], v[202:205], v[64:67]
	v_mfma_f32_16x16x32_bf16 v[68:71], v[234:237], v[202:205], v[68:71]
	v_mfma_f32_16x16x32_bf16 v[72:75], v[226:229], v[210:213], v[72:75]
	v_mfma_f32_16x16x32_bf16 v[76:79], v[234:237], v[210:213], v[76:79]
	v_mfma_f32_16x16x32_bf16 v[80:83], v[226:229], v[218:221], v[80:83]
	v_mfma_f32_16x16x32_bf16 v[84:87], v[234:237], v[218:221], v[84:87]
	v_mfma_f32_16x16x32_bf16 v[140:143], v[230:233], v[168:171], v[140:143]
	v_mfma_f32_16x16x32_bf16 v[60:63], v[238:241], v[168:171], v[60:63]
	v_mfma_f32_16x16x32_bf16 v[64:67], v[230:233], v[206:209], v[64:67]
	v_mfma_f32_16x16x32_bf16 v[68:71], v[238:241], v[206:209], v[68:71]
	v_mfma_f32_16x16x32_bf16 v[72:75], v[230:233], v[214:217], v[72:75]
	v_mfma_f32_16x16x32_bf16 v[76:79], v[238:241], v[214:217], v[76:79]
	v_mfma_f32_16x16x32_bf16 v[80:83], v[230:233], v[222:225], v[80:83]
	v_mfma_f32_16x16x32_bf16 v[84:87], v[238:241], v[222:225], v[84:87]
	s_setprio 0
	s_mov_b32 m0, s53
	s_barrier
	ds_read_b128 v[164:167], v40 offset:49152
	ds_read_b128 v[168:171], v40 offset:50176
	ds_read_b128 v[202:205], v40 offset:51200
	ds_read_b128 v[206:209], v40 offset:52224
	ds_read_b128 v[210:213], v40 offset:53248
	ds_read_b128 v[214:217], v40 offset:54272
	ds_read_b128 v[218:221], v40 offset:55296
	ds_read_b128 v[222:225], v40 offset:56320
	global_load_lds_dwordx4 v[10:11], off
	s_mov_b32 m0, s54
	s_nop 0
	global_load_lds_dwordx4 v[12:13], off
	s_barrier
	s_waitcnt lgkmcnt(0)
	s_setprio 1
	s_waitcnt lgkmcnt(0)
	v_mfma_f32_16x16x32_bf16 v[172:175], v[148:151], v[164:167], v[172:175]
	v_mfma_f32_16x16x32_bf16 v[176:179], v[156:159], v[164:167], v[176:179]
	v_mfma_f32_16x16x32_bf16 v[180:183], v[148:151], v[202:205], v[180:183]
	v_mfma_f32_16x16x32_bf16 v[190:193], v[156:159], v[202:205], v[190:193]
	v_mfma_f32_16x16x32_bf16 v[194:197], v[148:151], v[210:213], v[194:197]
	v_mfma_f32_16x16x32_bf16 v[198:201], v[156:159], v[210:213], v[198:201]
	v_mfma_f32_16x16x32_bf16 v[44:47], v[148:151], v[218:221], v[44:47]
	v_mfma_f32_16x16x32_bf16 v[48:51], v[156:159], v[218:221], v[48:51]
	v_mfma_f32_16x16x32_bf16 v[172:175], v[152:155], v[168:171], v[172:175]
	v_mfma_f32_16x16x32_bf16 v[176:179], v[160:163], v[168:171], v[176:179]
	v_mfma_f32_16x16x32_bf16 v[180:183], v[152:155], v[206:209], v[180:183]
	v_mfma_f32_16x16x32_bf16 v[190:193], v[160:163], v[206:209], v[190:193]
	v_mfma_f32_16x16x32_bf16 v[194:197], v[152:155], v[214:217], v[194:197]
	v_mfma_f32_16x16x32_bf16 v[198:201], v[160:163], v[214:217], v[198:201]
	v_mfma_f32_16x16x32_bf16 v[44:47], v[152:155], v[222:225], v[44:47]
	v_mfma_f32_16x16x32_bf16 v[48:51], v[160:163], v[222:225], v[48:51]
	s_setprio 0
	s_barrier
	s_add_u32 s40, s40, 0x10080
	s_addc_u32 s41, s41, 0
	s_mov_b32 m0, s66
	v_lshl_add_u64 v[148:149], s[40:41], 0, v[4:5]
	global_load_lds_dwordx4 v[148:149], off
	v_lshl_add_u64 v[148:149], s[40:41], 0, v[2:3]
	s_mov_b32 m0, s67
	s_nop 0
	global_load_lds_dwordx4 v[148:149], off
	s_waitcnt vmcnt(6)
	s_barrier
	s_setprio 1
	v_mfma_f32_16x16x32_bf16 v[52:55], v[226:229], v[164:167], v[52:55]
	v_mfma_f32_16x16x32_bf16 v[56:59], v[234:237], v[164:167], v[56:59]
	v_mfma_f32_16x16x32_bf16 v[88:91], v[226:229], v[202:205], v[88:91]
	v_mfma_f32_16x16x32_bf16 v[132:135], v[234:237], v[202:205], v[132:135]
	v_mfma_f32_16x16x32_bf16 v[136:139], v[226:229], v[210:213], v[136:139]
	v_mfma_f32_16x16x32_bf16 v[144:147], v[234:237], v[210:213], v[144:147]
	v_mfma_f32_16x16x32_bf16 v[124:127], v[226:229], v[218:221], v[124:127]
	v_mfma_f32_16x16x32_bf16 v[128:131], v[234:237], v[218:221], v[128:131]
	v_mfma_f32_16x16x32_bf16 v[52:55], v[230:233], v[168:171], v[52:55]
	v_mfma_f32_16x16x32_bf16 v[56:59], v[238:241], v[168:171], v[56:59]
	v_mfma_f32_16x16x32_bf16 v[88:91], v[230:233], v[206:209], v[88:91]
	v_mfma_f32_16x16x32_bf16 v[132:135], v[238:241], v[206:209], v[132:135]
	v_mfma_f32_16x16x32_bf16 v[136:139], v[230:233], v[214:217], v[136:139]
	v_mfma_f32_16x16x32_bf16 v[144:147], v[238:241], v[214:217], v[144:147]
	v_mfma_f32_16x16x32_bf16 v[124:127], v[230:233], v[222:225], v[124:127]
	v_mfma_f32_16x16x32_bf16 v[128:131], v[238:241], v[222:225], v[128:131]
	s_setprio 0
	v_mov_b32_e32 v148, v1
	v_mov_b32_e32 v149, v38
	s_barrier
	v_cvt_pk_bf16_f32 v64, v64, v65
	v_cvt_pk_bf16_f32 v65, v66, v67
	v_cvt_pk_bf16_f32 v66, v68, v69
	v_cvt_pk_bf16_f32 v68, v108, v109
	v_cvt_pk_bf16_f32 v69, v110, v111
	v_add_u32_e32 v108, s57, v148
	v_lshlrev_b32_e32 v110, 3, v149
	v_ashrrev_i32_e32 v109, 31, v108
	v_ashrrev_i32_e32 v111, 31, v110
	v_lshlrev_b64 v[108:109], 11, v[108:109]
	v_lshl_add_u64 v[110:111], s[36:37], 0, v[110:111]
	v_lshl_add_u64 v[108:109], s[24:25], 0, v[108:109]
	v_cvt_pk_bf16_f32 v92, v92, v93
	v_cvt_pk_bf16_f32 v93, v94, v95
	v_cvt_pk_bf16_f32 v94, v96, v97
	v_cvt_pk_bf16_f32 v95, v98, v99
	v_lshl_add_u64 v[108:109], v[110:111], 1, v[108:109]
	v_cvt_pk_bf16_f32 v96, v140, v141
	v_cvt_pk_bf16_f32 v97, v142, v143
	v_cvt_pk_bf16_f32 v98, v60, v61
	v_cvt_pk_bf16_f32 v99, v62, v63
	global_store_dwordx4 v[108:109], v[92:95], off nt
	global_store_dwordx4 v[108:109], v[96:99], off offset:256 nt
	v_cvt_pk_bf16_f32 v67, v70, v71
	v_add_co_u32_e32 v94, vcc, s56, v108
	v_cvt_pk_bf16_f32 v70, v112, v113
	s_nop 0
	v_addc_co_u32_e32 v95, vcc, 0, v109, vcc
	v_add_co_u32_e32 v98, vcc, s52, v108
	v_cvt_pk_bf16_f32 v72, v72, v73
	s_nop 0
	v_addc_co_u32_e32 v99, vcc, 0, v109, vcc
	v_add_co_u32_e32 v112, vcc, s55, v108
	v_cvt_pk_bf16_f32 v73, v74, v75
	s_nop 0
	v_addc_co_u32_e32 v113, vcc, 0, v109, vcc
	v_cvt_pk_bf16_f32 v74, v76, v77
	v_cvt_pk_bf16_f32 v76, v116, v117
	v_add_co_u32_e32 v116, vcc, s68, v108
	v_cvt_pk_bf16_f32 v75, v78, v79
	s_nop 0
	v_addc_co_u32_e32 v117, vcc, 0, v109, vcc
	v_cvt_pk_bf16_f32 v78, v120, v121
	v_add_co_u32_e32 v120, vcc, s69, v108
	v_cvt_pk_bf16_f32 v44, v44, v45
	s_nop 0
	v_addc_co_u32_e32 v121, vcc, 0, v109, vcc
	v_cvt_pk_bf16_f32 v45, v46, v47
	v_cvt_pk_bf16_f32 v46, v48, v49
	v_cvt_pk_bf16_f32 v48, v124, v125
	s_add_u32 s36, s36, 0x100
	v_add_co_u32_e32 v124, vcc, s70, v108
	s_addc_u32 s37, s37, 0
	s_nop 0
	v_addc_co_u32_e32 v125, vcc, 0, v109, vcc
	v_cvt_pk_bf16_f32 v60, v100, v101
	v_cvt_pk_bf16_f32 v61, v102, v103
	v_cvt_pk_bf16_f32 v62, v104, v105
	v_cvt_pk_bf16_f32 v63, v106, v107
	v_cvt_pk_bf16_f32 v71, v114, v115
	v_cvt_pk_bf16_f32 v77, v118, v119
	v_cvt_pk_bf16_f32 v79, v122, v123
	v_cvt_pk_bf16_f32 v47, v50, v51
	v_cvt_pk_bf16_f32 v49, v126, v127
	v_cvt_pk_bf16_f32 v50, v128, v129
	v_cvt_pk_bf16_f32 v51, v130, v131
	s_mov_b32 s41, s72
	s_mov_b32 s40, s72
	s_mov_b64 s[42:43], s[38:39]
	s_cmp_lg_u32 s72, 4
	v_lshl_add_u64 v[92:93], v[108:109], 0, s[18:19]
	v_lshl_add_u64 v[96:97], v[108:109], 0, s[16:17]
	v_lshl_add_u64 v[110:111], v[108:109], 0, s[20:21]
	v_lshl_add_u64 v[114:115], v[108:109], 0, s[22:23]
	v_lshl_add_u64 v[118:119], v[108:109], 0, s[28:29]
	v_lshl_add_u64 v[122:123], v[108:109], 0, s[30:31]
	v_lshl_add_u64 v[126:127], v[108:109], 0, s[34:35]
	v_add_co_u32_e32 v108, vcc, s71, v108
	v_cvt_pk_bf16_f32 v80, v80, v81
	v_cvt_pk_bf16_f32 v81, v82, v83
	v_cvt_pk_bf16_f32 v82, v84, v85
	v_cvt_pk_bf16_f32 v83, v86, v87
	v_cvt_pk_bf16_f32 v84, v172, v173
	v_cvt_pk_bf16_f32 v85, v174, v175
	v_cvt_pk_bf16_f32 v86, v176, v177
	v_cvt_pk_bf16_f32 v87, v178, v179
	v_cvt_pk_bf16_f32 v52, v52, v53
	v_cvt_pk_bf16_f32 v53, v54, v55
	v_cvt_pk_bf16_f32 v54, v56, v57
	v_cvt_pk_bf16_f32 v55, v58, v59
	v_cvt_pk_bf16_f32 v56, v180, v181
	v_cvt_pk_bf16_f32 v57, v182, v183
	v_cvt_pk_bf16_f32 v58, v190, v191
	v_cvt_pk_bf16_f32 v59, v192, v193
	v_cvt_pk_bf16_f32 v88, v88, v89
	v_cvt_pk_bf16_f32 v89, v90, v91
	v_cvt_pk_bf16_f32 v90, v132, v133
	v_cvt_pk_bf16_f32 v91, v134, v135
	v_cvt_pk_bf16_f32 v100, v194, v195
	v_cvt_pk_bf16_f32 v101, v196, v197
	v_cvt_pk_bf16_f32 v102, v198, v199
	v_cvt_pk_bf16_f32 v103, v200, v201
	v_cvt_pk_bf16_f32 v104, v136, v137
	v_cvt_pk_bf16_f32 v105, v138, v139
	v_cvt_pk_bf16_f32 v106, v144, v145
	v_cvt_pk_bf16_f32 v107, v146, v147
	global_store_dwordx4 v[94:95], v[60:63], off nt
	global_store_dwordx4 v[92:93], v[64:67], off offset:256 nt
	global_store_dwordx4 v[98:99], v[68:71], off nt
	global_store_dwordx4 v[96:97], v[72:75], off offset:256 nt
	global_store_dwordx4 v[112:113], v[76:79], off nt
	global_store_dwordx4 v[110:111], v[80:83], off offset:256 nt
	global_store_dwordx4 v[116:117], v[84:87], off nt
	global_store_dwordx4 v[114:115], v[52:55], off offset:256 nt
	global_store_dwordx4 v[120:121], v[56:59], off nt
	global_store_dwordx4 v[118:119], v[88:91], off offset:256 nt
	global_store_dwordx4 v[124:125], v[100:103], off nt
	global_store_dwordx4 v[122:123], v[104:107], off offset:256 nt
	v_addc_co_u32_e32 v109, vcc, 0, v109, vcc
	global_store_dwordx4 v[126:127], v[48:51], off offset:256 nt
	global_store_dwordx4 v[108:109], v[44:47], off nt
	s_cbranch_scc1 .LBB0_553
	s_waitcnt vmcnt(0)
	s_cmpk_gt_u32 s2, 0xff
	s_cbranch_scc1 .LBB0_556
	s_barrier

.LBB0_562:
	s_add_u32 s40, s6, s0
	ds_read_b128 v[112:115], v211
	ds_read_b128 v[116:119], v211 offset:1024
	ds_read_b128 v[128:131], v211 offset:2048
	ds_read_b128 v[132:135], v211 offset:3072
	s_addc_u32 s41, s7, s1
	s_add_u32 s40, s40, 0x10000100
	s_addc_u32 s41, s41, 0
	s_add_u32 s65, s62, s0
	s_addc_u32 s66, s63, s1
	s_cmpk_eq_i32 s0, 0x700
	s_cselect_b32 s43, s15, s41
	s_cselect_b32 s42, s14, s40
	s_cselect_b32 s41, s60, s66
	s_cselect_b32 s40, s61, s65
	v_lshl_add_u64 v[176:177], v[198:199], 0, s[0:1]
	s_add_i32 m0, s49, 0xc000
	ds_read_b128 v[144:147], v212
	ds_read_b128 v[148:151], v212 offset:1024
	ds_read_b128 v[152:155], v212 offset:2048
	ds_read_b128 v[156:159], v212 offset:3072
	ds_read_b128 v[160:163], v212 offset:4096
	ds_read_b128 v[164:167], v212 offset:5120
	ds_read_b128 v[168:171], v212 offset:6144
	ds_read_b128 v[172:175], v212 offset:7168
	global_load_lds_dwordx4 v[176:177], off
	v_lshl_add_u64 v[176:177], v[200:201], 0, s[0:1]
	s_add_i32 m0, s49, 0xe000
	s_nop 0
	global_load_lds_dwordx4 v[176:177], off
	s_waitcnt lgkmcnt(8)
	s_barrier
	s_waitcnt lgkmcnt(0)
	s_setprio 1
	s_waitcnt lgkmcnt(0)
	v_mfma_f32_16x16x32_bf16 v[140:143], v[112:115], v[144:147], v[140:143]
	v_mfma_f32_16x16x32_bf16 v[136:139], v[128:131], v[144:147], v[136:139]
	v_mfma_f32_16x16x32_bf16 v[108:111], v[112:115], v[152:155], v[108:111]
	v_mfma_f32_16x16x32_bf16 v[104:107], v[128:131], v[152:155], v[104:107]
	v_mfma_f32_16x16x32_bf16 v[92:95], v[112:115], v[160:163], v[92:95]
	v_mfma_f32_16x16x32_bf16 v[88:91], v[128:131], v[160:163], v[88:91]
	v_mfma_f32_16x16x32_bf16 v[76:79], v[112:115], v[168:171], v[76:79]
	v_mfma_f32_16x16x32_bf16 v[72:75], v[128:131], v[168:171], v[72:75]
	v_mfma_f32_16x16x32_bf16 v[140:143], v[116:119], v[148:151], v[140:143]
	v_mfma_f32_16x16x32_bf16 v[136:139], v[132:135], v[148:151], v[136:139]
	v_mfma_f32_16x16x32_bf16 v[108:111], v[116:119], v[156:159], v[108:111]
	v_mfma_f32_16x16x32_bf16 v[104:107], v[132:135], v[156:159], v[104:107]
	v_mfma_f32_16x16x32_bf16 v[92:95], v[116:119], v[164:167], v[92:95]
	v_mfma_f32_16x16x32_bf16 v[88:91], v[132:135], v[164:167], v[88:91]
	v_mfma_f32_16x16x32_bf16 v[76:79], v[116:119], v[172:175], v[76:79]
	v_mfma_f32_16x16x32_bf16 v[72:75], v[132:135], v[172:175], v[72:75]
	s_setprio 0
	s_barrier
	s_add_i32 s65, s45, s3
	v_lshl_add_u64 v[206:207], s[40:41], 0, v[194:195]
	s_mov_b32 m0, s65
	ds_read_b128 v[176:179], v213
	ds_read_b128 v[180:183], v213 offset:1024
	ds_read_b128 v[202:205], v213 offset:2048
	ds_read_b128 v[216:219], v213 offset:3072
	global_load_lds_dwordx4 v[206:207], off
	v_lshl_add_u64 v[220:221], s[40:41], 0, v[190:191]
	s_add_i32 m0, s65, 0x2000
	s_nop 0
	global_load_lds_dwordx4 v[220:221], off
	s_barrier
	s_waitcnt lgkmcnt(0)
	s_setprio 1
	s_waitcnt lgkmcnt(0)
	v_mfma_f32_16x16x32_bf16 v[124:127], v[176:179], v[144:147], v[124:127]
	v_mfma_f32_16x16x32_bf16 v[120:123], v[202:205], v[144:147], v[120:123]
	v_mfma_f32_16x16x32_bf16 v[100:103], v[176:179], v[152:155], v[100:103]
	v_mfma_f32_16x16x32_bf16 v[96:99], v[202:205], v[152:155], v[96:99]
	v_mfma_f32_16x16x32_bf16 v[84:87], v[176:179], v[160:163], v[84:87]
	v_mfma_f32_16x16x32_bf16 v[80:83], v[202:205], v[160:163], v[80:83]
	v_mfma_f32_16x16x32_bf16 v[68:71], v[176:179], v[168:171], v[68:71]
	v_mfma_f32_16x16x32_bf16 v[64:67], v[202:205], v[168:171], v[64:67]
	v_mfma_f32_16x16x32_bf16 v[124:127], v[180:183], v[148:151], v[124:127]
	v_mfma_f32_16x16x32_bf16 v[120:123], v[216:219], v[148:151], v[120:123]
	v_mfma_f32_16x16x32_bf16 v[100:103], v[180:183], v[156:159], v[100:103]
	v_mfma_f32_16x16x32_bf16 v[96:99], v[216:219], v[156:159], v[96:99]
	v_mfma_f32_16x16x32_bf16 v[84:87], v[180:183], v[164:167], v[84:87]
	v_mfma_f32_16x16x32_bf16 v[80:83], v[216:219], v[164:167], v[80:83]
	v_mfma_f32_16x16x32_bf16 v[68:71], v[180:183], v[172:175], v[68:71]
	v_mfma_f32_16x16x32_bf16 v[64:67], v[216:219], v[172:175], v[64:67]
	s_setprio 0
	s_mov_b32 m0, s49
	v_lshl_add_u64 v[222:223], s[42:43], 0, v[196:197]
	s_barrier
	ds_read_b128 v[144:147], v212 offset:16384
	ds_read_b128 v[148:151], v212 offset:17408
	ds_read_b128 v[152:155], v212 offset:18432
	ds_read_b128 v[156:159], v212 offset:19456
	ds_read_b128 v[160:163], v212 offset:20480
	ds_read_b128 v[164:167], v212 offset:21504
	ds_read_b128 v[168:171], v212 offset:22528
	ds_read_b128 v[172:175], v212 offset:23552
	global_load_lds_dwordx4 v[222:223], off
	v_lshl_add_u64 v[224:225], s[42:43], 0, v[192:193]
	s_mov_b32 m0, s50
	s_nop 0
	global_load_lds_dwordx4 v[224:225], off
	s_barrier
	s_waitcnt lgkmcnt(0)
	s_setprio 1
	s_waitcnt lgkmcnt(0)
	v_mfma_f32_16x16x32_bf16 v[60:63], v[112:115], v[144:147], v[60:63]
	v_mfma_f32_16x16x32_bf16 v[56:59], v[128:131], v[144:147], v[56:59]
	v_mfma_f32_16x16x32_bf16 v[44:47], v[112:115], v[152:155], v[44:47]
	v_mfma_f32_16x16x32_bf16 v[40:43], v[128:131], v[152:155], v[40:43]
	v_mfma_f32_16x16x32_bf16 v[28:31], v[112:115], v[160:163], v[28:31]
	v_mfma_f32_16x16x32_bf16 v[24:27], v[128:131], v[160:163], v[24:27]
	v_mfma_f32_16x16x32_bf16 v[12:15], v[112:115], v[168:171], v[12:15]
	v_mfma_f32_16x16x32_bf16 v[8:11], v[128:131], v[168:171], v[8:11]
	v_mfma_f32_16x16x32_bf16 v[60:63], v[116:119], v[148:151], v[60:63]
	v_mfma_f32_16x16x32_bf16 v[56:59], v[132:135], v[148:151], v[56:59]
	v_mfma_f32_16x16x32_bf16 v[44:47], v[116:119], v[156:159], v[44:47]
	v_mfma_f32_16x16x32_bf16 v[40:43], v[132:135], v[156:159], v[40:43]
	v_mfma_f32_16x16x32_bf16 v[28:31], v[116:119], v[164:167], v[28:31]
	v_mfma_f32_16x16x32_bf16 v[24:27], v[132:135], v[164:167], v[24:27]
	v_mfma_f32_16x16x32_bf16 v[12:15], v[116:119], v[172:175], v[12:15]
	v_mfma_f32_16x16x32_bf16 v[8:11], v[132:135], v[172:175], v[8:11]
	s_setprio 0
	s_barrier
	s_add_u32 s66, s40, 0x40000
	s_addc_u32 s67, s41, 0
	s_add_i32 s65, s46, s3
	v_lshl_add_u64 v[112:113], s[66:67], 0, v[194:195]
	s_mov_b32 m0, s65
	s_nop 0
	global_load_lds_dwordx4 v[112:113], off
	v_lshl_add_u64 v[112:113], s[66:67], 0, v[190:191]
	s_add_i32 m0, s65, 0x2000
	s_nop 0
	global_load_lds_dwordx4 v[112:113], off
	s_waitcnt vmcnt(6)
	s_barrier
	s_setprio 1
	v_mfma_f32_16x16x32_bf16 v[52:55], v[176:179], v[144:147], v[52:55]
	v_mfma_f32_16x16x32_bf16 v[48:51], v[202:205], v[144:147], v[48:51]
	v_mfma_f32_16x16x32_bf16 v[36:39], v[176:179], v[152:155], v[36:39]
	v_mfma_f32_16x16x32_bf16 v[32:35], v[202:205], v[152:155], v[32:35]
	v_mfma_f32_16x16x32_bf16 v[20:23], v[176:179], v[160:163], v[20:23]
	v_mfma_f32_16x16x32_bf16 v[16:19], v[202:205], v[160:163], v[16:19]
	v_mfma_f32_16x16x32_bf16 v[4:7], v[176:179], v[168:171], v[4:7]
	v_mfma_f32_16x16x32_bf16 v[0:3], v[202:205], v[168:171], v[0:3]
	v_mfma_f32_16x16x32_bf16 v[52:55], v[180:183], v[148:151], v[52:55]
	v_mfma_f32_16x16x32_bf16 v[48:51], v[216:219], v[148:151], v[48:51]
	v_mfma_f32_16x16x32_bf16 v[36:39], v[180:183], v[156:159], v[36:39]
	v_mfma_f32_16x16x32_bf16 v[32:35], v[216:219], v[156:159], v[32:35]
	v_mfma_f32_16x16x32_bf16 v[20:23], v[180:183], v[164:167], v[20:23]
	v_mfma_f32_16x16x32_bf16 v[16:19], v[216:219], v[164:167], v[16:19]
	v_mfma_f32_16x16x32_bf16 v[4:7], v[180:183], v[172:175], v[4:7]
	v_mfma_f32_16x16x32_bf16 v[0:3], v[216:219], v[172:175], v[0:3]
	s_setprio 0
	v_add_u32_e32 v132, s47, v210
	s_barrier
	ds_read_b128 v[112:115], v132
	ds_read_b128 v[116:119], v132 offset:1024
	ds_read_b128 v[128:131], v132 offset:2048
	ds_read_b128 v[132:135], v132 offset:3072
	s_add_u32 s42, s42, 0x40000
	s_addc_u32 s43, s43, 0
	s_mov_b32 m0, s51
	v_lshl_add_u64 v[176:177], s[42:43], 0, v[196:197]
	ds_read_b128 v[144:147], v212 offset:32768
	ds_read_b128 v[148:151], v212 offset:33792
	ds_read_b128 v[152:155], v212 offset:34816
	ds_read_b128 v[156:159], v212 offset:35840
	ds_read_b128 v[160:163], v212 offset:36864
	ds_read_b128 v[164:167], v212 offset:37888
	ds_read_b128 v[168:171], v212 offset:38912
	ds_read_b128 v[172:175], v212 offset:39936
	global_load_lds_dwordx4 v[176:177], off
	v_lshl_add_u64 v[176:177], s[42:43], 0, v[192:193]
	s_mov_b32 m0, s52
	s_nop 0
	global_load_lds_dwordx4 v[176:177], off
	s_waitcnt lgkmcnt(8)
	s_barrier
	s_waitcnt lgkmcnt(0)
	s_setprio 1
	s_waitcnt lgkmcnt(0)
	v_mfma_f32_16x16x32_bf16 v[140:143], v[112:115], v[144:147], v[140:143]
	v_mfma_f32_16x16x32_bf16 v[136:139], v[128:131], v[144:147], v[136:139]
	v_mfma_f32_16x16x32_bf16 v[108:111], v[112:115], v[152:155], v[108:111]
	v_mfma_f32_16x16x32_bf16 v[104:107], v[128:131], v[152:155], v[104:107]
	v_mfma_f32_16x16x32_bf16 v[92:95], v[112:115], v[160:163], v[92:95]
	v_mfma_f32_16x16x32_bf16 v[88:91], v[128:131], v[160:163], v[88:91]
	v_mfma_f32_16x16x32_bf16 v[76:79], v[112:115], v[168:171], v[76:79]
	v_mfma_f32_16x16x32_bf16 v[72:75], v[128:131], v[168:171], v[72:75]
	v_mfma_f32_16x16x32_bf16 v[140:143], v[116:119], v[148:151], v[140:143]
	v_mfma_f32_16x16x32_bf16 v[136:139], v[132:135], v[148:151], v[136:139]
	v_mfma_f32_16x16x32_bf16 v[108:111], v[116:119], v[156:159], v[108:111]
	v_mfma_f32_16x16x32_bf16 v[104:107], v[132:135], v[156:159], v[104:107]
	v_mfma_f32_16x16x32_bf16 v[92:95], v[116:119], v[164:167], v[92:95]
	v_mfma_f32_16x16x32_bf16 v[88:91], v[132:135], v[164:167], v[88:91]
	v_mfma_f32_16x16x32_bf16 v[76:79], v[116:119], v[172:175], v[76:79]
	v_mfma_f32_16x16x32_bf16 v[72:75], v[132:135], v[172:175], v[72:75]
	s_setprio 0
	s_barrier
	s_add_i32 s42, s47, s3
	v_add_u32_e32 v215, s48, v210
	v_lshl_add_u64 v[206:207], v[206:207], 0, s[20:21]
	s_mov_b32 m0, s42
	ds_read_b128 v[176:179], v215
	ds_read_b128 v[180:183], v215 offset:1024
	ds_read_b128 v[202:205], v215 offset:2048
	ds_read_b128 v[216:219], v215 offset:3072
	global_load_lds_dwordx4 v[206:207], off
	v_lshl_add_u64 v[206:207], v[220:221], 0, s[20:21]
	s_add_i32 m0, s42, 0x2000
	s_nop 0
	global_load_lds_dwordx4 v[206:207], off
	s_barrier
	s_waitcnt lgkmcnt(0)
	s_setprio 1
	s_waitcnt lgkmcnt(0)
	v_mfma_f32_16x16x32_bf16 v[124:127], v[176:179], v[144:147], v[124:127]
	v_mfma_f32_16x16x32_bf16 v[120:123], v[202:205], v[144:147], v[120:123]
	v_mfma_f32_16x16x32_bf16 v[100:103], v[176:179], v[152:155], v[100:103]
	v_mfma_f32_16x16x32_bf16 v[96:99], v[202:205], v[152:155], v[96:99]
	v_mfma_f32_16x16x32_bf16 v[84:87], v[176:179], v[160:163], v[84:87]
	v_mfma_f32_16x16x32_bf16 v[80:83], v[202:205], v[160:163], v[80:83]
	v_mfma_f32_16x16x32_bf16 v[68:71], v[176:179], v[168:171], v[68:71]
	v_mfma_f32_16x16x32_bf16 v[64:67], v[202:205], v[168:171], v[64:67]
	v_mfma_f32_16x16x32_bf16 v[124:127], v[180:183], v[148:151], v[124:127]
	v_mfma_f32_16x16x32_bf16 v[120:123], v[216:219], v[148:151], v[120:123]
	v_mfma_f32_16x16x32_bf16 v[100:103], v[180:183], v[156:159], v[100:103]
	v_mfma_f32_16x16x32_bf16 v[96:99], v[216:219], v[156:159], v[96:99]
	v_mfma_f32_16x16x32_bf16 v[84:87], v[180:183], v[164:167], v[84:87]
	v_mfma_f32_16x16x32_bf16 v[80:83], v[216:219], v[164:167], v[80:83]
	v_mfma_f32_16x16x32_bf16 v[68:71], v[180:183], v[172:175], v[68:71]
	v_mfma_f32_16x16x32_bf16 v[64:67], v[216:219], v[172:175], v[64:67]
	s_setprio 0
	s_mov_b32 m0, s56
	v_lshl_add_u64 v[206:207], v[222:223], 0, s[20:21]
	s_barrier
	ds_read_b128 v[144:147], v212 offset:49152
	ds_read_b128 v[148:151], v212 offset:50176
	ds_read_b128 v[152:155], v212 offset:51200
	ds_read_b128 v[156:159], v212 offset:52224
	ds_read_b128 v[160:163], v212 offset:53248
	ds_read_b128 v[164:167], v212 offset:54272
	ds_read_b128 v[168:171], v212 offset:55296
	ds_read_b128 v[172:175], v212 offset:56320
	global_load_lds_dwordx4 v[206:207], off
	v_lshl_add_u64 v[206:207], v[224:225], 0, s[20:21]
	s_mov_b32 m0, s57
	s_nop 0
	global_load_lds_dwordx4 v[206:207], off
	s_barrier
	s_waitcnt lgkmcnt(0)
	s_setprio 1
	s_waitcnt lgkmcnt(0)
	v_mfma_f32_16x16x32_bf16 v[60:63], v[112:115], v[144:147], v[60:63]
	v_mfma_f32_16x16x32_bf16 v[56:59], v[128:131], v[144:147], v[56:59]
	v_mfma_f32_16x16x32_bf16 v[44:47], v[112:115], v[152:155], v[44:47]
	v_mfma_f32_16x16x32_bf16 v[40:43], v[128:131], v[152:155], v[40:43]
	v_mfma_f32_16x16x32_bf16 v[28:31], v[112:115], v[160:163], v[28:31]
	v_mfma_f32_16x16x32_bf16 v[24:27], v[128:131], v[160:163], v[24:27]
	v_mfma_f32_16x16x32_bf16 v[12:15], v[112:115], v[168:171], v[12:15]
	v_mfma_f32_16x16x32_bf16 v[8:11], v[128:131], v[168:171], v[8:11]
	v_mfma_f32_16x16x32_bf16 v[60:63], v[116:119], v[148:151], v[60:63]
	v_mfma_f32_16x16x32_bf16 v[56:59], v[132:135], v[148:151], v[56:59]
	v_mfma_f32_16x16x32_bf16 v[44:47], v[116:119], v[156:159], v[44:47]
	v_mfma_f32_16x16x32_bf16 v[40:43], v[132:135], v[156:159], v[40:43]
	v_mfma_f32_16x16x32_bf16 v[28:31], v[116:119], v[164:167], v[28:31]
	v_mfma_f32_16x16x32_bf16 v[24:27], v[132:135], v[164:167], v[24:27]
	v_mfma_f32_16x16x32_bf16 v[12:15], v[116:119], v[172:175], v[12:15]
	v_mfma_f32_16x16x32_bf16 v[8:11], v[132:135], v[172:175], v[8:11]
	s_setprio 0
	s_barrier
	s_add_u32 s40, s40, 0x40080
	s_addc_u32 s41, s41, 0
	s_add_i32 s42, s48, s3
	v_lshl_add_u64 v[112:113], s[40:41], 0, v[194:195]
	s_mov_b32 m0, s42
	s_nop 0
	global_load_lds_dwordx4 v[112:113], off
	v_lshl_add_u64 v[112:113], s[40:41], 0, v[190:191]
	s_add_i32 m0, s42, 0x2000
	s_nop 0
	global_load_lds_dwordx4 v[112:113], off
	s_waitcnt vmcnt(6)
	s_barrier
	s_setprio 1
	v_mfma_f32_16x16x32_bf16 v[52:55], v[176:179], v[144:147], v[52:55]
	v_mfma_f32_16x16x32_bf16 v[48:51], v[202:205], v[144:147], v[48:51]
	v_mfma_f32_16x16x32_bf16 v[36:39], v[176:179], v[152:155], v[36:39]
	v_mfma_f32_16x16x32_bf16 v[32:35], v[202:205], v[152:155], v[32:35]
	v_mfma_f32_16x16x32_bf16 v[20:23], v[176:179], v[160:163], v[20:23]
	v_mfma_f32_16x16x32_bf16 v[16:19], v[202:205], v[160:163], v[16:19]
	v_mfma_f32_16x16x32_bf16 v[4:7], v[176:179], v[168:171], v[4:7]
	v_mfma_f32_16x16x32_bf16 v[0:3], v[202:205], v[168:171], v[0:3]
	v_mfma_f32_16x16x32_bf16 v[52:55], v[180:183], v[148:151], v[52:55]
	v_mfma_f32_16x16x32_bf16 v[48:51], v[216:219], v[148:151], v[48:51]
	v_mfma_f32_16x16x32_bf16 v[36:39], v[180:183], v[156:159], v[36:39]
	v_mfma_f32_16x16x32_bf16 v[32:35], v[216:219], v[156:159], v[32:35]
	v_mfma_f32_16x16x32_bf16 v[20:23], v[180:183], v[164:167], v[20:23]
	v_mfma_f32_16x16x32_bf16 v[16:19], v[216:219], v[164:167], v[16:19]
	v_mfma_f32_16x16x32_bf16 v[4:7], v[180:183], v[172:175], v[4:7]
	v_mfma_f32_16x16x32_bf16 v[0:3], v[216:219], v[172:175], v[0:3]
	s_setprio 0
	s_add_i32 s64, s64, 2
	s_add_u32 s0, s0, 0x100
	s_addc_u32 s1, s1, 0
	s_cmp_gt_u32 s64, 13
	s_barrier
	s_cbranch_scc0 .LBB0_562
	v_mov_b32_e32 v112, v208
	v_mov_b32_e32 v118, v209
	s_lshl_b32 s0, s59, 8
	v_add_u32_e32 v215, s54, v112
	v_add_u32_e32 v204, s44, v215
	s_or_b32 s0, s0, s55
	v_lshl_add_u32 v202, v118, 3, s0
	v_ashrrev_i32_e32 v205, 31, v204
	v_ashrrev_i32_e32 v203, 31, v202
	v_lshlrev_b64 v[112:113], 10, v[204:205]
	v_lshl_add_u64 v[112:113], v[112:113], 0, v[202:203]
	v_lshlrev_b64 v[112:113], 1, v[112:113]
	v_lshl_add_u64 v[114:115], s[24:25], 0, v[112:113]
	global_load_dwordx4 v[218:221], v[114:115], off
	v_lshl_add_u64 v[116:117], s[26:27], 0, v[112:113]
	global_load_dwordx4 v[222:225], v[116:117], off
	v_lshl_add_u32 v217, v215, 2, 0
	v_add_u32_e32 v216, 0x20000, v217
	ds_read_b32 v130, v216
	global_load_dwordx4 v[176:179], v[116:117], off offset:256
	global_load_dwordx4 v[180:183], v[114:115], off offset:256
	v_cmp_eq_u32_e32 vcc, 0, v118
	v_lshl_add_u64 v[118:119], v[112:113], 0, s[8:9]
	v_lshl_add_u64 v[128:129], v[112:113], 0, s[22:23]
	v_lshl_add_u64 v[114:115], s[26:27], 0, v[118:119]
	v_lshl_add_u64 v[112:113], v[112:113], 0, s[28:29]
	v_lshl_add_u64 v[116:117], s[24:25], 0, v[118:119]
	v_lshl_add_u64 v[118:119], s[26:27], 0, v[128:129]
	v_lshl_add_u64 v[128:129], s[24:25], 0, v[128:129]
	global_load_dwordx4 v[168:171], v[114:115], off
	global_load_dwordx4 v[160:163], v[114:115], off offset:256
	global_load_dwordx4 v[172:175], v[116:117], off
	global_load_dwordx4 v[164:167], v[116:117], off offset:256
	global_load_dwordx4 v[152:155], v[118:119], off
	global_load_dwordx4 v[144:147], v[118:119], off offset:256
	global_load_dwordx4 v[156:159], v[128:129], off
	global_load_dwordx4 v[148:151], v[128:129], off offset:256
	v_lshl_add_u64 v[132:133], s[26:27], 0, v[112:113]
	v_lshl_add_u64 v[226:227], s[24:25], 0, v[112:113]
	s_waitcnt lgkmcnt(0)
	v_fmamk_f32 v112, v130, 0x3a800000, v214
	v_mul_f32_e32 v113, 0x4b800000, v112
	v_cmp_gt_f32_e64 s[0:1], s58, v112
	v_lshlrev_b64 v[206:207], 11, v[204:205]
	s_waitcnt vmcnt(0)
	v_and_b32_e32 v229, 0xffff0000, v220
	v_cndmask_b32_e64 v112, v112, v113, s[0:1]
	v_rsq_f32_e32 v228, v112
	global_load_dwordx4 v[128:131], v[132:133], off
	global_load_dwordx4 v[112:115], v[132:133], off offset:256
	s_nop 0
	global_load_dwordx4 v[132:135], v[226:227], off
	global_load_dwordx4 v[116:119], v[226:227], off offset:256
	v_and_b32_e32 v227, 0xffff0000, v222
	v_lshlrev_b32_e32 v230, 16, v224
	v_mul_f32_e32 v226, 0x45800000, v228
	v_cndmask_b32_e64 v232, v228, v226, s[0:1]
	v_mul_f32_e32 v140, v140, v232
	v_mul_f32_e32 v136, v136, v232
	v_mul_f32_e32 v141, v141, v232
	v_mul_f32_e32 v142, v142, v232
	v_mul_f32_e32 v140, 0xbfb8aa3b, v140
	v_mul_f32_e32 v136, 0xbfb8aa3b, v136
	v_mul_f32_e32 v137, v137, v232
	v_mul_f32_e32 v141, 0xbfb8aa3b, v141
	v_mul_f32_e32 v142, 0xbfb8aa3b, v142
	v_exp_f32_e32 v140, v140
	v_exp_f32_e32 v136, v136
	v_mul_f32_e32 v137, 0xbfb8aa3b, v137
	v_exp_f32_e32 v141, v141
	v_exp_f32_e32 v142, v142
	v_exp_f32_e32 v137, v137
	v_mul_f32_e32 v143, v143, v232
	v_mul_f32_e32 v138, v138, v232
	v_mul_f32_e32 v233, 0xbfb8aa3b, v143
	v_add_f32_e32 v140, 1.0, v140
	v_add_f32_e32 v143, 1.0, v136
	v_mul_f32_e32 v139, v139, v232
	v_mul_f32_e32 v138, 0xbfb8aa3b, v138
	v_add_f32_e32 v141, 1.0, v141
	v_add_f32_e32 v234, 1.0, v142
	v_rcp_f32_e32 v136, v140
	v_rcp_f32_e32 v140, v143
	v_lshlrev_b32_e32 v142, 16, v218
	v_and_b32_e32 v143, 0xffff0000, v218
	v_exp_f32_e32 v218, v233
	v_mul_f32_e32 v139, 0xbfb8aa3b, v139
	v_exp_f32_e32 v138, v138
	v_add_f32_e32 v226, 1.0, v137
	v_rcp_f32_e32 v137, v141
	v_exp_f32_e32 v139, v139
	v_mul_f32_e32 v124, v124, v232
	v_mul_f32_e32 v125, v125, v232
	v_mul_f32_e32 v124, 0xbfb8aa3b, v124
	v_mul_f32_e32 v120, v120, v232
	v_mul_f32_e32 v125, 0xbfb8aa3b, v125
	v_mul_f32_e32 v121, v121, v232
	v_rcp_f32_e32 v141, v226
	v_lshlrev_b32_e32 v226, 16, v222
	v_add_f32_e32 v218, 1.0, v218
	v_exp_f32_e32 v124, v124
	v_mul_f32_e32 v120, 0xbfb8aa3b, v120
	v_exp_f32_e32 v125, v125
	v_mul_f32_e32 v121, 0xbfb8aa3b, v121
	v_mul_f32_e32 v126, v126, v232
	v_mul_f32_e32 v127, v127, v232
	v_pk_fma_f32 v[136:137], v[136:137], v[142:143], v[226:227]
	v_rcp_f32_e32 v226, v234
	v_add_f32_e32 v138, 1.0, v138
	v_rcp_f32_e32 v227, v218
	v_add_f32_e32 v139, 1.0, v139
	v_exp_f32_e32 v120, v120
	v_exp_f32_e32 v121, v121
	v_mul_f32_e32 v126, 0xbfb8aa3b, v126
	v_mul_f32_e32 v122, v122, v232
	v_mul_f32_e32 v127, 0xbfb8aa3b, v127
	v_mul_f32_e32 v123, v123, v232
	v_rcp_f32_e32 v138, v138
	v_rcp_f32_e32 v139, v139
	v_exp_f32_e32 v126, v126
	v_mul_f32_e32 v122, 0xbfb8aa3b, v122
	v_exp_f32_e32 v127, v127
	v_mul_f32_e32 v123, 0xbfb8aa3b, v123
	v_exp_f32_e32 v122, v122
	v_exp_f32_e32 v123, v123
	v_lshlrev_b32_e32 v218, 16, v219
	v_and_b32_e32 v219, 0xffff0000, v219
	v_lshlrev_b32_e32 v222, 16, v223
	v_and_b32_e32 v223, 0xffff0000, v223
	v_add_f32_e32 v124, 1.0, v124
	v_add_f32_e32 v125, 1.0, v125
	v_lshlrev_b32_e32 v228, 16, v220
	v_and_b32_e32 v231, 0xffff0000, v224
	v_pk_fma_f32 v[218:219], v[226:227], v[218:219], v[222:223]
	v_lshlrev_b32_e32 v220, 16, v221
	v_and_b32_e32 v221, 0xffff0000, v221
	v_lshlrev_b32_e32 v222, 16, v225
	v_and_b32_e32 v223, 0xffff0000, v225
	v_rcp_f32_e32 v124, v124
	v_add_f32_e32 v120, 1.0, v120
	v_rcp_f32_e32 v125, v125
	v_add_f32_e32 v121, 1.0, v121
	v_pk_fma_f32 v[140:141], v[140:141], v[228:229], v[230:231]
	v_pk_fma_f32 v[220:221], v[138:139], v[220:221], v[222:223]
	v_rcp_f32_e32 v120, v120
	v_rcp_f32_e32 v121, v121
	v_add_f32_e32 v126, 1.0, v126
	v_add_f32_e32 v127, 1.0, v127
	v_pk_mul_f32 v[142:143], v[140:141], v[140:141]
	v_pk_mul_f32 v[138:139], v[220:221], v[220:221]
	v_rcp_f32_e32 v126, v126
	v_add_f32_e32 v122, 1.0, v122
	v_rcp_f32_e32 v127, v127
	v_add_f32_e32 v123, 1.0, v123
	v_pk_fma_f32 v[142:143], v[136:137], v[136:137], v[142:143]
	v_pk_fma_f32 v[222:223], v[218:219], v[218:219], v[138:139]
	v_cvt_pk_bf16_f32 v136, v136, v137
	v_cvt_pk_bf16_f32 v137, v218, v219
	v_cvt_pk_bf16_f32 v138, v140, v141
	v_lshlrev_b32_e32 v140, 16, v180
	v_and_b32_e32 v141, 0xffff0000, v180
	v_lshlrev_b32_e32 v218, 16, v176
	v_and_b32_e32 v219, 0xffff0000, v176
	v_rcp_f32_e32 v122, v122
	v_rcp_f32_e32 v123, v123
	v_pk_fma_f32 v[124:125], v[124:125], v[140:141], v[218:219]
	v_lshlrev_b32_e32 v140, 16, v182
	v_and_b32_e32 v141, 0xffff0000, v182
	v_lshlrev_b32_e32 v218, 16, v178
	v_and_b32_e32 v219, 0xffff0000, v178
	v_pk_fma_f32 v[140:141], v[120:121], v[140:141], v[218:219]
	v_lshlrev_b32_e32 v180, 16, v181
	v_and_b32_e32 v181, 0xffff0000, v181
	v_lshlrev_b32_e32 v176, 16, v177
	v_and_b32_e32 v177, 0xffff0000, v177
	v_add_f32_e32 v142, v142, v143
	v_pk_mul_f32 v[120:121], v[140:141], v[140:141]
	v_pk_fma_f32 v[126:127], v[126:127], v[180:181], v[176:177]
	v_lshlrev_b32_e32 v176, 16, v183
	v_and_b32_e32 v177, 0xffff0000, v183
	v_lshlrev_b32_e32 v178, 16, v179
	v_and_b32_e32 v179, 0xffff0000, v179
	v_add_f32_e32 v142, v222, v142
	v_pk_fma_f32 v[120:121], v[124:125], v[124:125], v[120:121]
	v_pk_fma_f32 v[176:177], v[122:123], v[176:177], v[178:179]
	v_add_f32_e32 v142, v223, v142
	v_pk_mul_f32 v[122:123], v[176:177], v[176:177]
	v_add_f32_e32 v120, v120, v142
	v_pk_fma_f32 v[122:123], v[126:127], v[126:127], v[122:123]
	v_add_f32_e32 v120, v121, v120
	v_add_f32_e32 v120, v122, v120
	v_add_f32_e32 v123, v123, v120
	ds_bpermute_b32 v178, v187, v123
	v_lshl_add_u64 v[120:121], s[18:19], 0, v[206:207]
	v_lshl_add_u64 v[142:143], v[202:203], 1, v[120:121]
	v_cvt_pk_bf16_f32 v139, v220, v221
	v_cvt_pk_bf16_f32 v122, v124, v125
	s_waitcnt lgkmcnt(0)
	v_add_f32_e32 v120, v123, v178
	ds_bpermute_b32 v121, v189, v120
	v_cvt_pk_bf16_f32 v123, v126, v127
	v_cvt_pk_bf16_f32 v124, v140, v141
	v_cvt_pk_bf16_f32 v125, v176, v177
	global_store_dwordx4 v[142:143], v[136:139], off nt
	global_store_dwordx4 v[142:143], v[122:125], off offset:256 nt
	s_and_saveexec_b64 s[0:1], vcc
	s_cbranch_execz .LBB0_565
	s_waitcnt lgkmcnt(0)
	v_add_f32_e32 v120, v120, v121
	v_add_u32_e32 v121, 0x20400, v217
	ds_add_f32 v121, v120
.LBB0_565:
	s_or_b64 exec, exec, s[0:1]
	s_waitcnt lgkmcnt(0)
	ds_read_b32 v121, v216 offset:64
	v_and_b32_e32 v125, 0xffff0000, v172
	v_lshlrev_b32_e32 v126, 16, v168
	v_and_b32_e32 v127, 0xffff0000, v168
	v_lshlrev_b32_e32 v136, 16, v169
	s_waitcnt lgkmcnt(0)
	v_fmamk_f32 v121, v121, 0x3a800000, v214
	v_mul_f32_e32 v122, 0x4b800000, v121
	v_cmp_gt_f32_e64 s[0:1], s58, v121
	v_and_b32_e32 v137, 0xffff0000, v169
	v_add_u32_e32 v120, 16, v215
	v_cndmask_b32_e64 v121, v121, v122, s[0:1]
	v_rsq_f32_e32 v121, v121
	v_add_u32_e32 v122, s44, v120
	v_ashrrev_i32_e32 v123, 31, v122
	v_lshlrev_b64 v[122:123], 11, v[122:123]
	v_mul_f32_e32 v124, 0x45800000, v121
	v_cndmask_b32_e64 v121, v121, v124, s[0:1]
	v_mul_f32_e32 v108, v108, v121
	v_mul_f32_e32 v109, v109, v121
	v_mul_f32_e32 v104, v104, v121
	v_mul_f32_e32 v108, 0xbfb8aa3b, v108
	v_mul_f32_e32 v109, 0xbfb8aa3b, v109
	v_mul_f32_e32 v105, v105, v121
	v_exp_f32_e32 v108, v108
	v_mul_f32_e32 v104, 0xbfb8aa3b, v104
	v_exp_f32_e32 v109, v109
	v_mul_f32_e32 v105, 0xbfb8aa3b, v105
	v_exp_f32_e32 v104, v104
	v_exp_f32_e32 v105, v105
	v_add_f32_e32 v108, 1.0, v108
	v_add_f32_e32 v109, 1.0, v109
	v_rcp_f32_e32 v108, v108
	v_add_f32_e32 v104, 1.0, v104
	v_rcp_f32_e32 v109, v109
	v_add_f32_e32 v105, 1.0, v105
	v_rcp_f32_e32 v104, v104
	v_rcp_f32_e32 v105, v105
	v_lshlrev_b32_e32 v124, 16, v172
	v_pk_fma_f32 v[108:109], v[108:109], v[124:125], v[126:127]
	v_lshlrev_b32_e32 v124, 16, v174
	v_and_b32_e32 v125, 0xffff0000, v174
	v_lshlrev_b32_e32 v126, 16, v170
	v_and_b32_e32 v127, 0xffff0000, v170
	v_mul_f32_e32 v110, v110, v121
	v_mul_f32_e32 v110, 0xbfb8aa3b, v110
	v_pk_fma_f32 v[124:125], v[104:105], v[124:125], v[126:127]
	v_exp_f32_e32 v110, v110
	v_pk_mul_f32 v[104:105], v[124:125], v[124:125]
	v_mul_f32_e32 v107, v107, v121
	v_pk_fma_f32 v[126:127], v[108:109], v[108:109], v[104:105]
	v_mul_f32_e32 v105, v106, v121
	v_mul_f32_e32 v105, 0xbfb8aa3b, v105
	v_mul_f32_e32 v106, v111, v121
	v_exp_f32_e32 v105, v105
	v_mul_f32_e32 v106, 0xbfb8aa3b, v106
	v_add_f32_e32 v104, 1.0, v110
	v_exp_f32_e32 v110, v106
	v_add_f32_e32 v105, 1.0, v105
	v_rcp_f32_e32 v106, v105
	v_mul_f32_e32 v107, 0xbfb8aa3b, v107
	v_add_f32_e32 v105, 1.0, v110
	v_rcp_f32_e32 v104, v104
	v_rcp_f32_e32 v105, v105
	v_exp_f32_e32 v107, v107
	v_mul_f32_e32 v100, v100, v121
	v_mul_f32_e32 v101, v101, v121
	v_mul_f32_e32 v100, 0xbfb8aa3b, v100
	v_mul_f32_e32 v96, v96, v121
	v_mul_f32_e32 v101, 0xbfb8aa3b, v101
	v_mul_f32_e32 v97, v97, v121
	v_lshlrev_b32_e32 v110, 16, v173
	v_and_b32_e32 v111, 0xffff0000, v173
	v_exp_f32_e32 v100, v100
	v_mul_f32_e32 v96, 0xbfb8aa3b, v96
	v_exp_f32_e32 v101, v101
	v_mul_f32_e32 v97, 0xbfb8aa3b, v97
	v_mul_f32_e32 v102, v102, v121
	v_mul_f32_e32 v103, v103, v121
	v_pk_fma_f32 v[110:111], v[104:105], v[110:111], v[136:137]
	v_add_f32_e32 v104, 1.0, v107
	v_exp_f32_e32 v96, v96
	v_exp_f32_e32 v97, v97
	v_mul_f32_e32 v102, 0xbfb8aa3b, v102
	v_mul_f32_e32 v98, v98, v121
	v_mul_f32_e32 v103, 0xbfb8aa3b, v103
	v_mul_f32_e32 v99, v99, v121
	v_rcp_f32_e32 v107, v104
	v_exp_f32_e32 v102, v102
	v_mul_f32_e32 v98, 0xbfb8aa3b, v98
	v_exp_f32_e32 v103, v103
	v_mul_f32_e32 v99, 0xbfb8aa3b, v99
	v_exp_f32_e32 v98, v98
	v_exp_f32_e32 v99, v99
	v_add_f32_e32 v100, 1.0, v100
	v_add_f32_e32 v101, 1.0, v101
	v_lshlrev_b32_e32 v104, 16, v175
	v_and_b32_e32 v105, 0xffff0000, v175
	v_lshlrev_b32_e32 v136, 16, v171
	v_and_b32_e32 v137, 0xffff0000, v171
	v_rcp_f32_e32 v100, v100
	v_add_f32_e32 v96, 1.0, v96
	v_rcp_f32_e32 v101, v101
	v_add_f32_e32 v97, 1.0, v97
	v_pk_fma_f32 v[136:137], v[106:107], v[104:105], v[136:137]
	v_rcp_f32_e32 v96, v96
	v_rcp_f32_e32 v97, v97
	v_add_f32_e32 v102, 1.0, v102
	v_add_f32_e32 v103, 1.0, v103
	v_pk_mul_f32 v[104:105], v[136:137], v[136:137]
	v_rcp_f32_e32 v102, v102
	v_add_f32_e32 v98, 1.0, v98
	v_rcp_f32_e32 v103, v103
	v_add_f32_e32 v99, 1.0, v99
	v_pk_fma_f32 v[138:139], v[110:111], v[110:111], v[104:105]
	v_cvt_pk_bf16_f32 v104, v108, v109
	v_cvt_pk_bf16_f32 v105, v110, v111
	v_lshlrev_b32_e32 v108, 16, v164
	v_and_b32_e32 v109, 0xffff0000, v164
	v_lshlrev_b32_e32 v110, 16, v160
	v_and_b32_e32 v111, 0xffff0000, v160
	v_rcp_f32_e32 v98, v98
	v_rcp_f32_e32 v99, v99
	v_pk_fma_f32 v[100:101], v[100:101], v[108:109], v[110:111]
	v_lshlrev_b32_e32 v108, 16, v166
	v_and_b32_e32 v109, 0xffff0000, v166
	v_lshlrev_b32_e32 v110, 16, v162
	v_and_b32_e32 v111, 0xffff0000, v162
	v_cvt_pk_bf16_f32 v106, v124, v125
	v_pk_fma_f32 v[108:109], v[96:97], v[108:109], v[110:111]
	v_lshlrev_b32_e32 v110, 16, v165
	v_and_b32_e32 v111, 0xffff0000, v165
	v_lshlrev_b32_e32 v124, 16, v161
	v_and_b32_e32 v125, 0xffff0000, v161
	v_add_f32_e32 v121, v126, v127
	v_pk_mul_f32 v[96:97], v[108:109], v[108:109]
	v_pk_fma_f32 v[102:103], v[102:103], v[110:111], v[124:125]
	v_lshlrev_b32_e32 v110, 16, v167
	v_and_b32_e32 v111, 0xffff0000, v167
	v_lshlrev_b32_e32 v124, 16, v163
	v_and_b32_e32 v125, 0xffff0000, v163
	v_add_f32_e32 v121, v138, v121
	v_pk_fma_f32 v[96:97], v[100:101], v[100:101], v[96:97]
	v_pk_fma_f32 v[110:111], v[98:99], v[110:111], v[124:125]
	v_add_f32_e32 v121, v139, v121
	v_pk_mul_f32 v[98:99], v[110:111], v[110:111]
	v_add_f32_e32 v96, v96, v121
	v_pk_fma_f32 v[98:99], v[102:103], v[102:103], v[98:99]
	v_add_f32_e32 v96, v97, v96
	v_add_f32_e32 v96, v98, v96
	v_add_f32_e32 v99, v99, v96
	ds_bpermute_b32 v121, v187, v99
	v_lshl_add_u64 v[96:97], s[18:19], 0, v[122:123]
	v_lshl_add_u64 v[122:123], v[202:203], 1, v[96:97]
	v_cvt_pk_bf16_f32 v107, v136, v137
	v_cvt_pk_bf16_f32 v98, v100, v101
	s_waitcnt lgkmcnt(0)
	v_add_f32_e32 v96, v99, v121
	ds_bpermute_b32 v97, v189, v96
	v_cvt_pk_bf16_f32 v99, v102, v103
	v_cvt_pk_bf16_f32 v100, v108, v109
	v_cvt_pk_bf16_f32 v101, v110, v111
	global_store_dwordx4 v[122:123], v[104:107], off nt
	global_store_dwordx4 v[122:123], v[98:101], off offset:256 nt
	s_and_saveexec_b64 s[0:1], vcc
	s_cbranch_execz .LBB0_567
	s_waitcnt lgkmcnt(0)
	v_add_f32_e32 v96, v96, v97
	v_lshl_add_u32 v97, v120, 2, 0
	v_add_u32_e32 v97, 0x20400, v97
	ds_add_f32 v97, v96
.LBB0_567:
	s_or_b64 exec, exec, s[0:1]
	s_waitcnt lgkmcnt(0)
	ds_read_b32 v97, v216 offset:128
	v_and_b32_e32 v101, 0xffff0000, v156
	v_lshlrev_b32_e32 v102, 16, v152
	v_and_b32_e32 v103, 0xffff0000, v152
	v_lshlrev_b32_e32 v104, 16, v153
	s_waitcnt lgkmcnt(0)
	v_fmamk_f32 v97, v97, 0x3a800000, v214
	v_mul_f32_e32 v98, 0x4b800000, v97
	v_cmp_gt_f32_e64 s[0:1], s58, v97
	v_and_b32_e32 v105, 0xffff0000, v153
	v_add_u32_e32 v96, 32, v215
	v_cndmask_b32_e64 v97, v97, v98, s[0:1]
	v_rsq_f32_e32 v97, v97
	v_add_u32_e32 v98, s44, v96
	v_ashrrev_i32_e32 v99, 31, v98
	v_lshlrev_b64 v[98:99], 11, v[98:99]
	v_mul_f32_e32 v100, 0x45800000, v97
	v_cndmask_b32_e64 v97, v97, v100, s[0:1]
	v_mul_f32_e32 v92, v92, v97
	v_mul_f32_e32 v93, v93, v97
	v_mul_f32_e32 v88, v88, v97
	v_mul_f32_e32 v92, 0xbfb8aa3b, v92
	v_mul_f32_e32 v93, 0xbfb8aa3b, v93
	v_mul_f32_e32 v89, v89, v97
	v_exp_f32_e32 v92, v92
	v_mul_f32_e32 v88, 0xbfb8aa3b, v88
	v_exp_f32_e32 v93, v93
	v_mul_f32_e32 v89, 0xbfb8aa3b, v89
	v_exp_f32_e32 v88, v88
	v_exp_f32_e32 v89, v89
	v_add_f32_e32 v92, 1.0, v92
	v_add_f32_e32 v93, 1.0, v93
	v_rcp_f32_e32 v92, v92
	v_add_f32_e32 v88, 1.0, v88
	v_rcp_f32_e32 v93, v93
	v_add_f32_e32 v89, 1.0, v89
	v_rcp_f32_e32 v88, v88
	v_rcp_f32_e32 v89, v89
	v_lshlrev_b32_e32 v100, 16, v156
	v_pk_fma_f32 v[92:93], v[92:93], v[100:101], v[102:103]
	v_lshlrev_b32_e32 v100, 16, v158
	v_and_b32_e32 v101, 0xffff0000, v158
	v_lshlrev_b32_e32 v102, 16, v154
	v_and_b32_e32 v103, 0xffff0000, v154
	v_mul_f32_e32 v94, v94, v97
	v_mul_f32_e32 v94, 0xbfb8aa3b, v94
	v_pk_fma_f32 v[100:101], v[88:89], v[100:101], v[102:103]
	v_exp_f32_e32 v94, v94
	v_pk_mul_f32 v[88:89], v[100:101], v[100:101]
	v_mul_f32_e32 v91, v91, v97
	v_pk_fma_f32 v[102:103], v[92:93], v[92:93], v[88:89]
	v_mul_f32_e32 v89, v90, v97
	v_mul_f32_e32 v89, 0xbfb8aa3b, v89
	v_mul_f32_e32 v90, v95, v97
	v_exp_f32_e32 v89, v89
	v_mul_f32_e32 v90, 0xbfb8aa3b, v90
	v_add_f32_e32 v88, 1.0, v94
	v_exp_f32_e32 v94, v90
	v_add_f32_e32 v89, 1.0, v89
	v_rcp_f32_e32 v90, v89
	v_mul_f32_e32 v91, 0xbfb8aa3b, v91
	v_add_f32_e32 v89, 1.0, v94
	v_rcp_f32_e32 v88, v88
	v_rcp_f32_e32 v89, v89
	v_exp_f32_e32 v91, v91
	v_mul_f32_e32 v84, v84, v97
	v_mul_f32_e32 v85, v85, v97
	v_mul_f32_e32 v84, 0xbfb8aa3b, v84
	v_mul_f32_e32 v80, v80, v97
	v_mul_f32_e32 v85, 0xbfb8aa3b, v85
	v_mul_f32_e32 v81, v81, v97
	v_lshlrev_b32_e32 v94, 16, v157
	v_and_b32_e32 v95, 0xffff0000, v157
	v_exp_f32_e32 v84, v84
	v_mul_f32_e32 v80, 0xbfb8aa3b, v80
	v_exp_f32_e32 v85, v85
	v_mul_f32_e32 v81, 0xbfb8aa3b, v81
	v_mul_f32_e32 v86, v86, v97
	v_mul_f32_e32 v87, v87, v97
	v_pk_fma_f32 v[94:95], v[88:89], v[94:95], v[104:105]
	v_add_f32_e32 v88, 1.0, v91
	v_exp_f32_e32 v80, v80
	v_exp_f32_e32 v81, v81
	v_mul_f32_e32 v86, 0xbfb8aa3b, v86
	v_mul_f32_e32 v82, v82, v97
	v_mul_f32_e32 v87, 0xbfb8aa3b, v87
	v_mul_f32_e32 v83, v83, v97
	v_rcp_f32_e32 v91, v88
	v_exp_f32_e32 v86, v86
	v_mul_f32_e32 v82, 0xbfb8aa3b, v82
	v_exp_f32_e32 v87, v87
	v_mul_f32_e32 v83, 0xbfb8aa3b, v83
	v_exp_f32_e32 v82, v82
	v_exp_f32_e32 v83, v83
	v_add_f32_e32 v84, 1.0, v84
	v_add_f32_e32 v85, 1.0, v85
	v_lshlrev_b32_e32 v88, 16, v159
	v_and_b32_e32 v89, 0xffff0000, v159
	v_lshlrev_b32_e32 v104, 16, v155
	v_and_b32_e32 v105, 0xffff0000, v155
	v_rcp_f32_e32 v84, v84
	v_add_f32_e32 v80, 1.0, v80
	v_rcp_f32_e32 v85, v85
	v_add_f32_e32 v81, 1.0, v81
	v_pk_fma_f32 v[104:105], v[90:91], v[88:89], v[104:105]
	v_rcp_f32_e32 v80, v80
	v_rcp_f32_e32 v81, v81
	v_add_f32_e32 v86, 1.0, v86
	v_add_f32_e32 v87, 1.0, v87
	v_pk_mul_f32 v[88:89], v[104:105], v[104:105]
	v_rcp_f32_e32 v86, v86
	v_add_f32_e32 v82, 1.0, v82
	v_rcp_f32_e32 v87, v87
	v_add_f32_e32 v83, 1.0, v83
	v_pk_fma_f32 v[106:107], v[94:95], v[94:95], v[88:89]
	v_cvt_pk_bf16_f32 v88, v92, v93
	v_cvt_pk_bf16_f32 v89, v94, v95
	v_lshlrev_b32_e32 v92, 16, v148
	v_and_b32_e32 v93, 0xffff0000, v148
	v_lshlrev_b32_e32 v94, 16, v144
	v_and_b32_e32 v95, 0xffff0000, v144
	v_rcp_f32_e32 v82, v82
	v_rcp_f32_e32 v83, v83
	v_pk_fma_f32 v[84:85], v[84:85], v[92:93], v[94:95]
	v_lshlrev_b32_e32 v92, 16, v150
	v_and_b32_e32 v93, 0xffff0000, v150
	v_lshlrev_b32_e32 v94, 16, v146
	v_and_b32_e32 v95, 0xffff0000, v146
	v_cvt_pk_bf16_f32 v90, v100, v101
	v_pk_fma_f32 v[92:93], v[80:81], v[92:93], v[94:95]
	v_lshlrev_b32_e32 v94, 16, v149
	v_and_b32_e32 v95, 0xffff0000, v149
	v_lshlrev_b32_e32 v100, 16, v145
	v_and_b32_e32 v101, 0xffff0000, v145
	v_add_f32_e32 v97, v102, v103
	v_pk_mul_f32 v[80:81], v[92:93], v[92:93]
	v_pk_fma_f32 v[86:87], v[86:87], v[94:95], v[100:101]
	v_lshlrev_b32_e32 v94, 16, v151
	v_and_b32_e32 v95, 0xffff0000, v151
	v_lshlrev_b32_e32 v100, 16, v147
	v_and_b32_e32 v101, 0xffff0000, v147
	v_add_f32_e32 v97, v106, v97
	v_pk_fma_f32 v[80:81], v[84:85], v[84:85], v[80:81]
	v_pk_fma_f32 v[94:95], v[82:83], v[94:95], v[100:101]
	v_add_f32_e32 v97, v107, v97
	v_pk_mul_f32 v[82:83], v[94:95], v[94:95]
	v_add_f32_e32 v80, v80, v97
	v_pk_fma_f32 v[82:83], v[86:87], v[86:87], v[82:83]
	v_add_f32_e32 v80, v81, v80
	v_add_f32_e32 v80, v82, v80
	v_add_f32_e32 v83, v83, v80
	ds_bpermute_b32 v97, v187, v83
	v_lshl_add_u64 v[80:81], s[18:19], 0, v[98:99]
	v_lshl_add_u64 v[98:99], v[202:203], 1, v[80:81]
	v_cvt_pk_bf16_f32 v91, v104, v105
	v_cvt_pk_bf16_f32 v82, v84, v85
	s_waitcnt lgkmcnt(0)
	v_add_f32_e32 v80, v83, v97
	ds_bpermute_b32 v81, v189, v80
	v_cvt_pk_bf16_f32 v83, v86, v87
	v_cvt_pk_bf16_f32 v84, v92, v93
	v_cvt_pk_bf16_f32 v85, v94, v95
	global_store_dwordx4 v[98:99], v[88:91], off nt
	global_store_dwordx4 v[98:99], v[82:85], off offset:256 nt
	s_and_saveexec_b64 s[0:1], vcc
	s_cbranch_execz .LBB0_569
	s_waitcnt lgkmcnt(0)
	v_add_f32_e32 v80, v80, v81
	v_lshl_add_u32 v81, v96, 2, 0
	v_add_u32_e32 v81, 0x20400, v81
	ds_add_f32 v81, v80
.LBB0_569:
	s_or_b64 exec, exec, s[0:1]
	s_waitcnt lgkmcnt(0)
	ds_read_b32 v81, v216 offset:192
	s_waitcnt vmcnt(7)
	v_and_b32_e32 v85, 0xffff0000, v132
	v_lshlrev_b32_e32 v86, 16, v128
	v_and_b32_e32 v87, 0xffff0000, v128
	v_lshlrev_b32_e32 v88, 16, v129
	s_waitcnt lgkmcnt(0)
	v_fmamk_f32 v81, v81, 0x3a800000, v214
	v_mul_f32_e32 v82, 0x4b800000, v81
	v_cmp_gt_f32_e64 s[0:1], s58, v81
	v_and_b32_e32 v89, 0xffff0000, v129
	v_add_u32_e32 v80, 48, v215
	v_cndmask_b32_e64 v81, v81, v82, s[0:1]
	v_rsq_f32_e32 v81, v81
	v_add_u32_e32 v82, s44, v80
	v_ashrrev_i32_e32 v83, 31, v82
	v_lshlrev_b64 v[82:83], 11, v[82:83]
	v_mul_f32_e32 v84, 0x45800000, v81
	v_cndmask_b32_e64 v81, v81, v84, s[0:1]
	v_mul_f32_e32 v76, v76, v81
	v_mul_f32_e32 v77, v77, v81
	v_mul_f32_e32 v72, v72, v81
	v_mul_f32_e32 v76, 0xbfb8aa3b, v76
	v_mul_f32_e32 v77, 0xbfb8aa3b, v77
	v_mul_f32_e32 v73, v73, v81
	v_exp_f32_e32 v76, v76
	v_mul_f32_e32 v72, 0xbfb8aa3b, v72
	v_exp_f32_e32 v77, v77
	v_mul_f32_e32 v73, 0xbfb8aa3b, v73
	v_exp_f32_e32 v72, v72
	v_exp_f32_e32 v73, v73
	v_add_f32_e32 v76, 1.0, v76
	v_add_f32_e32 v77, 1.0, v77
	v_rcp_f32_e32 v76, v76
	v_add_f32_e32 v72, 1.0, v72
	v_rcp_f32_e32 v77, v77
	v_add_f32_e32 v73, 1.0, v73
	v_rcp_f32_e32 v72, v72
	v_rcp_f32_e32 v73, v73
	v_lshlrev_b32_e32 v84, 16, v132
	v_pk_fma_f32 v[76:77], v[76:77], v[84:85], v[86:87]
	v_lshlrev_b32_e32 v84, 16, v134
	v_and_b32_e32 v85, 0xffff0000, v134
	v_lshlrev_b32_e32 v86, 16, v130
	v_and_b32_e32 v87, 0xffff0000, v130
	v_mul_f32_e32 v78, v78, v81
	v_mul_f32_e32 v78, 0xbfb8aa3b, v78
	v_pk_fma_f32 v[84:85], v[72:73], v[84:85], v[86:87]
	v_exp_f32_e32 v78, v78
	v_pk_mul_f32 v[72:73], v[84:85], v[84:85]
	v_mul_f32_e32 v75, v75, v81
	v_pk_fma_f32 v[86:87], v[76:77], v[76:77], v[72:73]
	v_mul_f32_e32 v73, v74, v81
	v_mul_f32_e32 v73, 0xbfb8aa3b, v73
	v_mul_f32_e32 v74, v79, v81
	v_exp_f32_e32 v73, v73
	v_mul_f32_e32 v74, 0xbfb8aa3b, v74
	v_add_f32_e32 v72, 1.0, v78
	v_exp_f32_e32 v78, v74
	v_add_f32_e32 v73, 1.0, v73
	v_rcp_f32_e32 v74, v73
	v_mul_f32_e32 v75, 0xbfb8aa3b, v75
	v_add_f32_e32 v73, 1.0, v78
	v_rcp_f32_e32 v72, v72
	v_rcp_f32_e32 v73, v73
	v_exp_f32_e32 v75, v75
	v_mul_f32_e32 v68, v68, v81
	v_mul_f32_e32 v69, v69, v81
	v_mul_f32_e32 v68, 0xbfb8aa3b, v68
	v_mul_f32_e32 v64, v64, v81
	v_mul_f32_e32 v69, 0xbfb8aa3b, v69
	v_mul_f32_e32 v65, v65, v81
	v_lshlrev_b32_e32 v78, 16, v133
	v_and_b32_e32 v79, 0xffff0000, v133
	v_exp_f32_e32 v68, v68
	v_mul_f32_e32 v64, 0xbfb8aa3b, v64
	v_exp_f32_e32 v69, v69
	v_mul_f32_e32 v65, 0xbfb8aa3b, v65
	v_mul_f32_e32 v70, v70, v81
	v_mul_f32_e32 v71, v71, v81
	v_pk_fma_f32 v[78:79], v[72:73], v[78:79], v[88:89]
	v_add_f32_e32 v72, 1.0, v75
	v_exp_f32_e32 v64, v64
	v_exp_f32_e32 v65, v65
	v_mul_f32_e32 v70, 0xbfb8aa3b, v70
	v_mul_f32_e32 v66, v66, v81
	v_mul_f32_e32 v71, 0xbfb8aa3b, v71
	v_mul_f32_e32 v67, v67, v81
	v_rcp_f32_e32 v75, v72
	v_exp_f32_e32 v70, v70
	v_mul_f32_e32 v66, 0xbfb8aa3b, v66
	v_exp_f32_e32 v71, v71
	v_mul_f32_e32 v67, 0xbfb8aa3b, v67
	v_exp_f32_e32 v66, v66
	v_exp_f32_e32 v67, v67
	v_add_f32_e32 v68, 1.0, v68
	v_add_f32_e32 v69, 1.0, v69
	v_lshlrev_b32_e32 v72, 16, v135
	v_and_b32_e32 v73, 0xffff0000, v135
	v_lshlrev_b32_e32 v88, 16, v131
	v_and_b32_e32 v89, 0xffff0000, v131
	v_rcp_f32_e32 v68, v68
	v_add_f32_e32 v64, 1.0, v64
	v_rcp_f32_e32 v69, v69
	v_add_f32_e32 v65, 1.0, v65
	v_pk_fma_f32 v[88:89], v[74:75], v[72:73], v[88:89]
	v_rcp_f32_e32 v64, v64
	v_rcp_f32_e32 v65, v65
	v_add_f32_e32 v70, 1.0, v70
	v_add_f32_e32 v71, 1.0, v71
	v_pk_mul_f32 v[72:73], v[88:89], v[88:89]
	v_rcp_f32_e32 v70, v70
	v_add_f32_e32 v66, 1.0, v66
	v_rcp_f32_e32 v71, v71
	v_add_f32_e32 v67, 1.0, v67
	v_pk_fma_f32 v[90:91], v[78:79], v[78:79], v[72:73]
	v_cvt_pk_bf16_f32 v72, v76, v77
	v_cvt_pk_bf16_f32 v73, v78, v79
	s_waitcnt vmcnt(6)
	v_lshlrev_b32_e32 v76, 16, v116
	v_and_b32_e32 v77, 0xffff0000, v116
	v_lshlrev_b32_e32 v78, 16, v112
	v_and_b32_e32 v79, 0xffff0000, v112
	v_rcp_f32_e32 v66, v66
	v_rcp_f32_e32 v67, v67
	v_pk_fma_f32 v[68:69], v[68:69], v[76:77], v[78:79]
	v_lshlrev_b32_e32 v76, 16, v118
	v_and_b32_e32 v77, 0xffff0000, v118
	v_lshlrev_b32_e32 v78, 16, v114
	v_and_b32_e32 v79, 0xffff0000, v114
	v_cvt_pk_bf16_f32 v74, v84, v85
	v_pk_fma_f32 v[76:77], v[64:65], v[76:77], v[78:79]
	v_lshlrev_b32_e32 v78, 16, v117
	v_and_b32_e32 v79, 0xffff0000, v117
	v_lshlrev_b32_e32 v84, 16, v113
	v_and_b32_e32 v85, 0xffff0000, v113
	v_add_f32_e32 v81, v86, v87
	v_pk_mul_f32 v[64:65], v[76:77], v[76:77]
	v_pk_fma_f32 v[70:71], v[70:71], v[78:79], v[84:85]
	v_lshlrev_b32_e32 v78, 16, v119
	v_and_b32_e32 v79, 0xffff0000, v119
	v_lshlrev_b32_e32 v84, 16, v115
	v_and_b32_e32 v85, 0xffff0000, v115
	v_add_f32_e32 v81, v90, v81
	v_pk_fma_f32 v[64:65], v[68:69], v[68:69], v[64:65]
	v_pk_fma_f32 v[78:79], v[66:67], v[78:79], v[84:85]
	v_add_f32_e32 v81, v91, v81
	v_pk_mul_f32 v[66:67], v[78:79], v[78:79]
	v_add_f32_e32 v64, v64, v81
	v_pk_fma_f32 v[66:67], v[70:71], v[70:71], v[66:67]
	v_add_f32_e32 v64, v65, v64
	v_add_f32_e32 v64, v66, v64
	v_add_f32_e32 v67, v67, v64
	ds_bpermute_b32 v81, v187, v67
	v_lshl_add_u64 v[64:65], s[18:19], 0, v[82:83]
	v_lshl_add_u64 v[82:83], v[202:203], 1, v[64:65]
	v_cvt_pk_bf16_f32 v75, v88, v89
	v_cvt_pk_bf16_f32 v66, v68, v69
	s_waitcnt lgkmcnt(0)
	v_add_f32_e32 v64, v67, v81
	ds_bpermute_b32 v65, v189, v64
	v_cvt_pk_bf16_f32 v67, v70, v71
	v_cvt_pk_bf16_f32 v68, v76, v77
	v_cvt_pk_bf16_f32 v69, v78, v79
	global_store_dwordx4 v[82:83], v[72:75], off nt
	global_store_dwordx4 v[82:83], v[66:69], off offset:256 nt
	s_and_saveexec_b64 s[0:1], vcc
	s_cbranch_execz .LBB0_571
	s_waitcnt lgkmcnt(0)
	v_add_f32_e32 v64, v64, v65
	v_lshl_add_u32 v65, v80, 2, 0
	v_add_u32_e32 v65, 0x20400, v65
	ds_add_f32 v65, v64
.LBB0_571:
	s_or_b64 exec, exec, s[0:1]
	s_waitcnt lgkmcnt(0)
	v_lshlrev_b64 v[64:65], 10, v[204:205]
	v_lshl_add_u64 v[64:65], v[64:65], 0, v[202:203]
	v_lshlrev_b64 v[64:65], 1, v[64:65]
	v_lshl_add_u64 v[66:67], v[64:65], 0, s[16:17]
	v_lshl_add_u64 v[68:69], s[24:25], 0, v[66:67]
	v_lshl_add_u64 v[66:67], s[26:27], 0, v[66:67]
	global_load_dwordx4 v[120:123], v[68:69], off
	global_load_dwordx4 v[124:127], v[66:67], off
	v_add_u32_e32 v118, 0x80, v215
	v_add_u32_e32 v70, s44, v118
	v_ashrrev_i32_e32 v71, 31, v70
	v_lshl_add_u64 v[72:73], v[64:65], 0, s[30:31]
	v_lshl_add_u64 v[74:75], v[64:65], 0, s[34:35]
	ds_read_b32 v119, v216 offset:512
	v_lshlrev_b64 v[116:117], 11, v[70:71]
	v_lshl_add_u64 v[70:71], s[26:27], 0, v[72:73]
	v_lshl_add_u64 v[72:73], s[24:25], 0, v[72:73]
	v_lshl_add_u64 v[76:77], s[26:27], 0, v[74:75]
	v_lshl_add_u64 v[74:75], s[24:25], 0, v[74:75]
	global_load_dwordx4 v[112:115], v[66:67], off offset:256
	global_load_dwordx4 v[128:131], v[68:69], off offset:256
	global_load_dwordx4 v[104:107], v[70:71], off
	global_load_dwordx4 v[96:99], v[70:71], off offset:256
	global_load_dwordx4 v[108:111], v[72:73], off
	global_load_dwordx4 v[100:103], v[72:73], off offset:256
	global_load_dwordx4 v[88:91], v[76:77], off
	global_load_dwordx4 v[80:83], v[76:77], off offset:256
	global_load_dwordx4 v[92:95], v[74:75], off
	global_load_dwordx4 v[84:87], v[74:75], off offset:256
	v_lshl_add_u64 v[64:65], v[64:65], 0, s[36:37]
	v_lshl_add_u64 v[78:79], s[26:27], 0, v[64:65]
	v_lshl_add_u64 v[132:133], s[24:25], 0, v[64:65]
	s_waitcnt lgkmcnt(0)
	v_fmamk_f32 v64, v119, 0x3a800000, v214
	v_mul_f32_e32 v65, 0x4b800000, v64
	v_cmp_gt_f32_e64 s[0:1], s58, v64
	s_waitcnt vmcnt(11)
	v_lshlrev_b32_e32 v136, 16, v122
	v_cndmask_b32_e64 v64, v64, v65, s[0:1]
	v_rsq_f32_e32 v119, v64
	global_load_dwordx4 v[72:75], v[78:79], off
	global_load_dwordx4 v[64:67], v[78:79], off offset:256
	s_nop 0
	global_load_dwordx4 v[76:79], v[132:133], off
	global_load_dwordx4 v[68:71], v[132:133], off offset:256
	s_waitcnt vmcnt(14)
	v_lshlrev_b32_e32 v134, 16, v124
	v_and_b32_e32 v135, 0xffff0000, v124
	v_mul_f32_e32 v132, 0x45800000, v119
	v_cndmask_b32_e64 v119, v119, v132, s[0:1]
	v_mul_f32_e32 v62, v62, v119
	v_mul_f32_e32 v63, v63, v119
	v_mul_f32_e32 v60, v60, v119
	v_mul_f32_e32 v56, v56, v119
	v_mul_f32_e32 v61, v61, v119
	v_mul_f32_e32 v57, v57, v119
	v_mul_f32_e32 v58, v58, v119
	v_mul_f32_e32 v62, 0xbfb8aa3b, v62
	v_mul_f32_e32 v63, 0xbfb8aa3b, v63
	v_mul_f32_e32 v59, v59, v119
	v_mul_f32_e32 v60, 0xbfb8aa3b, v60
	v_mul_f32_e32 v56, 0xbfb8aa3b, v56
	v_mul_f32_e32 v61, 0xbfb8aa3b, v61
	v_mul_f32_e32 v57, 0xbfb8aa3b, v57
	v_mul_f32_e32 v58, 0xbfb8aa3b, v58
	v_exp_f32_e32 v62, v62
	v_exp_f32_e32 v63, v63
	v_mul_f32_e32 v59, 0xbfb8aa3b, v59
	v_exp_f32_e32 v60, v60
	v_exp_f32_e32 v56, v56
	v_exp_f32_e32 v61, v61
	v_exp_f32_e32 v57, v57
	v_exp_f32_e32 v58, v58
	v_exp_f32_e32 v59, v59
	v_mul_f32_e32 v52, v52, v119
	v_mul_f32_e32 v53, v53, v119
	v_mul_f32_e32 v52, 0xbfb8aa3b, v52
	v_mul_f32_e32 v48, v48, v119
	v_mul_f32_e32 v53, 0xbfb8aa3b, v53
	v_mul_f32_e32 v49, v49, v119
	v_add_f32_e32 v62, 1.0, v62
	v_add_f32_e32 v63, 1.0, v63
	v_exp_f32_e32 v52, v52
	v_mul_f32_e32 v48, 0xbfb8aa3b, v48
	v_exp_f32_e32 v53, v53
	v_mul_f32_e32 v49, 0xbfb8aa3b, v49
	v_mul_f32_e32 v54, v54, v119
	v_mul_f32_e32 v55, v55, v119
	v_add_f32_e32 v60, 1.0, v60
	v_add_f32_e32 v132, 1.0, v56
	v_add_f32_e32 v61, 1.0, v61
	v_add_f32_e32 v133, 1.0, v57
	v_add_f32_e32 v58, 1.0, v58
	v_rcp_f32_e32 v62, v62
	v_rcp_f32_e32 v63, v63
	v_add_f32_e32 v59, 1.0, v59
	v_exp_f32_e32 v48, v48
	v_exp_f32_e32 v49, v49
	v_mul_f32_e32 v54, 0xbfb8aa3b, v54
	v_mul_f32_e32 v50, v50, v119
	v_mul_f32_e32 v55, 0xbfb8aa3b, v55
	v_mul_f32_e32 v51, v51, v119
	v_rcp_f32_e32 v56, v60
	v_rcp_f32_e32 v60, v132
	v_rcp_f32_e32 v57, v61
	v_rcp_f32_e32 v61, v133
	v_rcp_f32_e32 v58, v58
	v_rcp_f32_e32 v59, v59
	v_exp_f32_e32 v54, v54
	v_mul_f32_e32 v50, 0xbfb8aa3b, v50
	v_exp_f32_e32 v55, v55
	v_mul_f32_e32 v51, 0xbfb8aa3b, v51
	v_exp_f32_e32 v50, v50
	v_exp_f32_e32 v51, v51
	v_lshlrev_b32_e32 v132, 16, v120
	v_and_b32_e32 v133, 0xffff0000, v120
	v_lshlrev_b32_e32 v120, 16, v121
	v_and_b32_e32 v121, 0xffff0000, v121
	v_lshlrev_b32_e32 v124, 16, v125
	v_and_b32_e32 v125, 0xffff0000, v125
	v_add_f32_e32 v52, 1.0, v52
	v_add_f32_e32 v53, 1.0, v53
	v_and_b32_e32 v137, 0xffff0000, v122
	v_lshlrev_b32_e32 v138, 16, v126
	v_and_b32_e32 v139, 0xffff0000, v126
	v_pk_fma_f32 v[62:63], v[62:63], v[120:121], v[124:125]
	v_lshlrev_b32_e32 v120, 16, v123
	v_and_b32_e32 v121, 0xffff0000, v123
	v_lshlrev_b32_e32 v122, 16, v127
	v_and_b32_e32 v123, 0xffff0000, v127
	v_rcp_f32_e32 v52, v52
	v_add_f32_e32 v48, 1.0, v48
	v_rcp_f32_e32 v53, v53
	v_add_f32_e32 v49, 1.0, v49
	v_pk_fma_f32 v[60:61], v[60:61], v[136:137], v[138:139]
	v_pk_fma_f32 v[120:121], v[58:59], v[120:121], v[122:123]
	v_rcp_f32_e32 v48, v48
	v_rcp_f32_e32 v49, v49
	v_add_f32_e32 v54, 1.0, v54
	v_add_f32_e32 v55, 1.0, v55
	v_pk_fma_f32 v[56:57], v[56:57], v[132:133], v[134:135]
	v_pk_mul_f32 v[132:133], v[60:61], v[60:61]
	v_pk_mul_f32 v[58:59], v[120:121], v[120:121]
	v_rcp_f32_e32 v54, v54
	v_add_f32_e32 v50, 1.0, v50
	v_rcp_f32_e32 v55, v55
	v_add_f32_e32 v51, 1.0, v51
	v_pk_fma_f32 v[132:133], v[56:57], v[56:57], v[132:133]
	v_pk_fma_f32 v[122:123], v[62:63], v[62:63], v[58:59]
	v_cvt_pk_bf16_f32 v56, v56, v57
	v_cvt_pk_bf16_f32 v57, v62, v63
	v_cvt_pk_bf16_f32 v58, v60, v61
	s_waitcnt vmcnt(12)
	v_lshlrev_b32_e32 v60, 16, v128
	v_and_b32_e32 v61, 0xffff0000, v128
	v_lshlrev_b32_e32 v62, 16, v112
	v_and_b32_e32 v63, 0xffff0000, v112
	v_rcp_f32_e32 v50, v50
	v_rcp_f32_e32 v51, v51
	v_pk_fma_f32 v[52:53], v[52:53], v[60:61], v[62:63]
	v_lshlrev_b32_e32 v60, 16, v130
	v_and_b32_e32 v61, 0xffff0000, v130
	v_lshlrev_b32_e32 v62, 16, v114
	v_and_b32_e32 v63, 0xffff0000, v114
	v_pk_fma_f32 v[60:61], v[48:49], v[60:61], v[62:63]
	v_lshlrev_b32_e32 v62, 16, v129
	v_and_b32_e32 v63, 0xffff0000, v129
	v_lshlrev_b32_e32 v112, 16, v113
	v_and_b32_e32 v113, 0xffff0000, v113
	v_pk_fma_f32 v[54:55], v[54:55], v[62:63], v[112:113]
	v_lshlrev_b32_e32 v62, 16, v131
	v_and_b32_e32 v63, 0xffff0000, v131
	v_lshlrev_b32_e32 v112, 16, v115
	v_and_b32_e32 v113, 0xffff0000, v115
	v_pk_fma_f32 v[62:63], v[50:51], v[62:63], v[112:113]
	v_add_f32_e32 v112, v132, v133
	v_pk_mul_f32 v[48:49], v[60:61], v[60:61]
	v_add_f32_e32 v112, v122, v112
	v_pk_fma_f32 v[48:49], v[52:53], v[52:53], v[48:49]
	v_add_f32_e32 v112, v123, v112
	v_pk_mul_f32 v[50:51], v[62:63], v[62:63]
	v_add_f32_e32 v48, v48, v112
	v_pk_fma_f32 v[50:51], v[54:55], v[54:55], v[50:51]
	v_add_f32_e32 v48, v49, v48
	v_add_f32_e32 v48, v50, v48
	v_add_f32_e32 v51, v51, v48
	ds_bpermute_b32 v114, v187, v51
	v_lshl_add_u64 v[48:49], s[18:19], 0, v[116:117]
	v_lshl_add_u64 v[112:113], v[202:203], 1, v[48:49]
	v_cvt_pk_bf16_f32 v59, v120, v121
	v_cvt_pk_bf16_f32 v50, v52, v53
	s_waitcnt lgkmcnt(0)
	v_add_f32_e32 v48, v51, v114
	ds_bpermute_b32 v49, v189, v48
	v_cvt_pk_bf16_f32 v51, v54, v55
	v_cvt_pk_bf16_f32 v52, v60, v61
	v_cvt_pk_bf16_f32 v53, v62, v63
	global_store_dwordx4 v[112:113], v[56:59], off nt
	global_store_dwordx4 v[112:113], v[50:53], off offset:256 nt
	s_and_saveexec_b64 s[0:1], vcc
	s_cbranch_execz .LBB0_573
	s_waitcnt lgkmcnt(0)
	v_add_f32_e32 v48, v48, v49
	v_lshl_add_u32 v49, v118, 2, 0
	v_add_u32_e32 v49, 0x20400, v49
	ds_add_f32 v49, v48
.LBB0_573:
	s_or_b64 exec, exec, s[0:1]
	s_waitcnt lgkmcnt(0)
	ds_read_b32 v49, v216 offset:576
	s_waitcnt vmcnt(11)
	v_and_b32_e32 v53, 0xffff0000, v108
	v_lshlrev_b32_e32 v54, 16, v104
	v_and_b32_e32 v55, 0xffff0000, v104
	v_lshlrev_b32_e32 v56, 16, v105
	s_waitcnt lgkmcnt(0)
	v_fmamk_f32 v49, v49, 0x3a800000, v214
	v_mul_f32_e32 v50, 0x4b800000, v49
	v_cmp_gt_f32_e64 s[0:1], s58, v49
	v_and_b32_e32 v57, 0xffff0000, v105
	v_add_u32_e32 v48, 0x90, v215
	v_cndmask_b32_e64 v49, v49, v50, s[0:1]
	v_rsq_f32_e32 v49, v49
	v_add_u32_e32 v50, s44, v48
	v_ashrrev_i32_e32 v51, 31, v50
	v_lshlrev_b64 v[50:51], 11, v[50:51]
	v_mul_f32_e32 v52, 0x45800000, v49
	v_cndmask_b32_e64 v49, v49, v52, s[0:1]
	v_mul_f32_e32 v44, v44, v49
	v_mul_f32_e32 v45, v45, v49
	v_mul_f32_e32 v40, v40, v49
	v_mul_f32_e32 v44, 0xbfb8aa3b, v44
	v_mul_f32_e32 v45, 0xbfb8aa3b, v45
	v_mul_f32_e32 v41, v41, v49
	v_exp_f32_e32 v44, v44
	v_mul_f32_e32 v40, 0xbfb8aa3b, v40
	v_exp_f32_e32 v45, v45
	v_mul_f32_e32 v41, 0xbfb8aa3b, v41
	v_exp_f32_e32 v40, v40
	v_exp_f32_e32 v41, v41
	v_add_f32_e32 v44, 1.0, v44
	v_add_f32_e32 v45, 1.0, v45
	v_rcp_f32_e32 v44, v44
	v_add_f32_e32 v40, 1.0, v40
	v_rcp_f32_e32 v45, v45
	v_add_f32_e32 v41, 1.0, v41
	v_rcp_f32_e32 v40, v40
	v_rcp_f32_e32 v41, v41
	v_lshlrev_b32_e32 v52, 16, v108
	v_pk_fma_f32 v[44:45], v[44:45], v[52:53], v[54:55]
	v_lshlrev_b32_e32 v52, 16, v110
	v_and_b32_e32 v53, 0xffff0000, v110
	v_lshlrev_b32_e32 v54, 16, v106
	v_and_b32_e32 v55, 0xffff0000, v106
	v_mul_f32_e32 v46, v46, v49
	v_mul_f32_e32 v46, 0xbfb8aa3b, v46
	v_pk_fma_f32 v[52:53], v[40:41], v[52:53], v[54:55]
	v_exp_f32_e32 v46, v46
	v_pk_mul_f32 v[40:41], v[52:53], v[52:53]
	v_mul_f32_e32 v43, v43, v49
	v_pk_fma_f32 v[54:55], v[44:45], v[44:45], v[40:41]
	v_mul_f32_e32 v41, v42, v49
	v_mul_f32_e32 v41, 0xbfb8aa3b, v41
	v_mul_f32_e32 v42, v47, v49
	v_exp_f32_e32 v41, v41
	v_mul_f32_e32 v42, 0xbfb8aa3b, v42
	v_add_f32_e32 v40, 1.0, v46
	v_exp_f32_e32 v46, v42
	v_add_f32_e32 v41, 1.0, v41
	v_rcp_f32_e32 v42, v41
	v_mul_f32_e32 v43, 0xbfb8aa3b, v43
	v_add_f32_e32 v41, 1.0, v46
	v_rcp_f32_e32 v40, v40
	v_rcp_f32_e32 v41, v41
	v_exp_f32_e32 v43, v43
	v_mul_f32_e32 v36, v36, v49
	v_mul_f32_e32 v37, v37, v49
	v_mul_f32_e32 v36, 0xbfb8aa3b, v36
	v_mul_f32_e32 v32, v32, v49
	v_mul_f32_e32 v37, 0xbfb8aa3b, v37
	v_mul_f32_e32 v33, v33, v49
	v_lshlrev_b32_e32 v46, 16, v109
	v_and_b32_e32 v47, 0xffff0000, v109
	v_exp_f32_e32 v36, v36
	v_mul_f32_e32 v32, 0xbfb8aa3b, v32
	v_exp_f32_e32 v37, v37
	v_mul_f32_e32 v33, 0xbfb8aa3b, v33
	v_mul_f32_e32 v38, v38, v49
	v_mul_f32_e32 v39, v39, v49
	v_pk_fma_f32 v[46:47], v[40:41], v[46:47], v[56:57]
	v_add_f32_e32 v40, 1.0, v43
	v_exp_f32_e32 v32, v32
	v_exp_f32_e32 v33, v33
	v_mul_f32_e32 v38, 0xbfb8aa3b, v38
	v_mul_f32_e32 v34, v34, v49
	v_mul_f32_e32 v39, 0xbfb8aa3b, v39
	v_mul_f32_e32 v35, v35, v49
	v_rcp_f32_e32 v43, v40
	v_exp_f32_e32 v38, v38
	v_mul_f32_e32 v34, 0xbfb8aa3b, v34
	v_exp_f32_e32 v39, v39
	v_mul_f32_e32 v35, 0xbfb8aa3b, v35
	v_exp_f32_e32 v34, v34
	v_exp_f32_e32 v35, v35
	v_add_f32_e32 v36, 1.0, v36
	v_add_f32_e32 v37, 1.0, v37
	v_lshlrev_b32_e32 v40, 16, v111
	v_and_b32_e32 v41, 0xffff0000, v111
	v_lshlrev_b32_e32 v56, 16, v107
	v_and_b32_e32 v57, 0xffff0000, v107
	v_rcp_f32_e32 v36, v36
	v_add_f32_e32 v32, 1.0, v32
	v_rcp_f32_e32 v37, v37
	v_add_f32_e32 v33, 1.0, v33
	v_pk_fma_f32 v[56:57], v[42:43], v[40:41], v[56:57]
	v_rcp_f32_e32 v32, v32
	v_rcp_f32_e32 v33, v33
	v_add_f32_e32 v38, 1.0, v38
	v_add_f32_e32 v39, 1.0, v39
	v_pk_mul_f32 v[40:41], v[56:57], v[56:57]
	v_rcp_f32_e32 v38, v38
	v_add_f32_e32 v34, 1.0, v34
	v_rcp_f32_e32 v39, v39
	v_add_f32_e32 v35, 1.0, v35
	v_pk_fma_f32 v[58:59], v[46:47], v[46:47], v[40:41]
	v_cvt_pk_bf16_f32 v40, v44, v45
	v_cvt_pk_bf16_f32 v41, v46, v47
	s_waitcnt vmcnt(10)
	v_lshlrev_b32_e32 v44, 16, v100
	v_and_b32_e32 v45, 0xffff0000, v100
	v_lshlrev_b32_e32 v46, 16, v96
	v_and_b32_e32 v47, 0xffff0000, v96
	v_rcp_f32_e32 v34, v34
	v_rcp_f32_e32 v35, v35
	v_pk_fma_f32 v[36:37], v[36:37], v[44:45], v[46:47]
	v_lshlrev_b32_e32 v44, 16, v102
	v_and_b32_e32 v45, 0xffff0000, v102
	v_lshlrev_b32_e32 v46, 16, v98
	v_and_b32_e32 v47, 0xffff0000, v98
	v_cvt_pk_bf16_f32 v42, v52, v53
	v_pk_fma_f32 v[44:45], v[32:33], v[44:45], v[46:47]
	v_lshlrev_b32_e32 v46, 16, v101
	v_and_b32_e32 v47, 0xffff0000, v101
	v_lshlrev_b32_e32 v52, 16, v97
	v_and_b32_e32 v53, 0xffff0000, v97
	v_add_f32_e32 v49, v54, v55
	v_pk_mul_f32 v[32:33], v[44:45], v[44:45]
	v_pk_fma_f32 v[38:39], v[38:39], v[46:47], v[52:53]
	v_lshlrev_b32_e32 v46, 16, v103
	v_and_b32_e32 v47, 0xffff0000, v103
	v_lshlrev_b32_e32 v52, 16, v99
	v_and_b32_e32 v53, 0xffff0000, v99
	v_add_f32_e32 v49, v58, v49
	v_pk_fma_f32 v[32:33], v[36:37], v[36:37], v[32:33]
	v_pk_fma_f32 v[46:47], v[34:35], v[46:47], v[52:53]
	v_add_f32_e32 v49, v59, v49
	v_pk_mul_f32 v[34:35], v[46:47], v[46:47]
	v_add_f32_e32 v32, v32, v49
	v_pk_fma_f32 v[34:35], v[38:39], v[38:39], v[34:35]
	v_add_f32_e32 v32, v33, v32
	v_add_f32_e32 v32, v34, v32
	v_add_f32_e32 v35, v35, v32
	ds_bpermute_b32 v49, v187, v35
	v_lshl_add_u64 v[32:33], s[18:19], 0, v[50:51]
	v_lshl_add_u64 v[50:51], v[202:203], 1, v[32:33]
	v_cvt_pk_bf16_f32 v43, v56, v57
	v_cvt_pk_bf16_f32 v34, v36, v37
	s_waitcnt lgkmcnt(0)
	v_add_f32_e32 v32, v35, v49
	ds_bpermute_b32 v33, v189, v32
	v_cvt_pk_bf16_f32 v35, v38, v39
	v_cvt_pk_bf16_f32 v36, v44, v45
	v_cvt_pk_bf16_f32 v37, v46, v47
	global_store_dwordx4 v[50:51], v[40:43], off nt
	global_store_dwordx4 v[50:51], v[34:37], off offset:256 nt
	s_and_saveexec_b64 s[0:1], vcc
	s_cbranch_execz .LBB0_575
	s_waitcnt lgkmcnt(0)
	v_add_f32_e32 v32, v32, v33
	v_lshl_add_u32 v33, v48, 2, 0
	v_add_u32_e32 v33, 0x20400, v33
	ds_add_f32 v33, v32
.LBB0_575:
	s_or_b64 exec, exec, s[0:1]
	s_waitcnt lgkmcnt(0)
	ds_read_b32 v33, v216 offset:640
	s_waitcnt vmcnt(9)
	v_and_b32_e32 v37, 0xffff0000, v92
	v_lshlrev_b32_e32 v38, 16, v88
	v_and_b32_e32 v39, 0xffff0000, v88
	v_lshlrev_b32_e32 v40, 16, v89
	s_waitcnt lgkmcnt(0)
	v_fmamk_f32 v33, v33, 0x3a800000, v214
	v_mul_f32_e32 v34, 0x4b800000, v33
	v_cmp_gt_f32_e64 s[0:1], s58, v33
	v_and_b32_e32 v41, 0xffff0000, v89
	v_add_u32_e32 v32, 0xa0, v215
	v_cndmask_b32_e64 v33, v33, v34, s[0:1]
	v_rsq_f32_e32 v33, v33
	v_add_u32_e32 v34, s44, v32
	v_ashrrev_i32_e32 v35, 31, v34
	v_lshlrev_b64 v[34:35], 11, v[34:35]
	v_mul_f32_e32 v36, 0x45800000, v33
	v_cndmask_b32_e64 v33, v33, v36, s[0:1]
	v_mul_f32_e32 v28, v28, v33
	v_mul_f32_e32 v29, v29, v33
	v_mul_f32_e32 v24, v24, v33
	v_mul_f32_e32 v28, 0xbfb8aa3b, v28
	v_mul_f32_e32 v29, 0xbfb8aa3b, v29
	v_mul_f32_e32 v25, v25, v33
	v_exp_f32_e32 v28, v28
	v_mul_f32_e32 v24, 0xbfb8aa3b, v24
	v_exp_f32_e32 v29, v29
	v_mul_f32_e32 v25, 0xbfb8aa3b, v25
	v_exp_f32_e32 v24, v24
	v_exp_f32_e32 v25, v25
	v_add_f32_e32 v28, 1.0, v28
	v_add_f32_e32 v29, 1.0, v29
	v_rcp_f32_e32 v28, v28
	v_add_f32_e32 v24, 1.0, v24
	v_rcp_f32_e32 v29, v29
	v_add_f32_e32 v25, 1.0, v25
	v_rcp_f32_e32 v24, v24
	v_rcp_f32_e32 v25, v25
	v_lshlrev_b32_e32 v36, 16, v92
	v_pk_fma_f32 v[28:29], v[28:29], v[36:37], v[38:39]
	v_lshlrev_b32_e32 v36, 16, v94
	v_and_b32_e32 v37, 0xffff0000, v94
	v_lshlrev_b32_e32 v38, 16, v90
	v_and_b32_e32 v39, 0xffff0000, v90
	v_mul_f32_e32 v30, v30, v33
	v_mul_f32_e32 v30, 0xbfb8aa3b, v30
	v_pk_fma_f32 v[36:37], v[24:25], v[36:37], v[38:39]
	v_exp_f32_e32 v30, v30
	v_pk_mul_f32 v[24:25], v[36:37], v[36:37]
	v_mul_f32_e32 v27, v27, v33
	v_pk_fma_f32 v[38:39], v[28:29], v[28:29], v[24:25]
	v_mul_f32_e32 v25, v26, v33
	v_mul_f32_e32 v25, 0xbfb8aa3b, v25
	v_mul_f32_e32 v26, v31, v33
	v_exp_f32_e32 v25, v25
	v_mul_f32_e32 v26, 0xbfb8aa3b, v26
	v_add_f32_e32 v24, 1.0, v30
	v_exp_f32_e32 v30, v26
	v_add_f32_e32 v25, 1.0, v25
	v_rcp_f32_e32 v26, v25
	v_mul_f32_e32 v27, 0xbfb8aa3b, v27
	v_add_f32_e32 v25, 1.0, v30
	v_rcp_f32_e32 v24, v24
	v_rcp_f32_e32 v25, v25
	v_exp_f32_e32 v27, v27
	v_mul_f32_e32 v20, v20, v33
	v_mul_f32_e32 v21, v21, v33
	v_mul_f32_e32 v20, 0xbfb8aa3b, v20
	v_mul_f32_e32 v16, v16, v33
	v_mul_f32_e32 v21, 0xbfb8aa3b, v21
	v_mul_f32_e32 v17, v17, v33
	v_lshlrev_b32_e32 v30, 16, v93
	v_and_b32_e32 v31, 0xffff0000, v93
	v_exp_f32_e32 v20, v20
	v_mul_f32_e32 v16, 0xbfb8aa3b, v16
	v_exp_f32_e32 v21, v21
	v_mul_f32_e32 v17, 0xbfb8aa3b, v17
	v_mul_f32_e32 v22, v22, v33
	v_mul_f32_e32 v23, v23, v33
	v_pk_fma_f32 v[30:31], v[24:25], v[30:31], v[40:41]
	v_add_f32_e32 v24, 1.0, v27
	v_exp_f32_e32 v16, v16
	v_exp_f32_e32 v17, v17
	v_mul_f32_e32 v22, 0xbfb8aa3b, v22
	v_mul_f32_e32 v18, v18, v33
	v_mul_f32_e32 v23, 0xbfb8aa3b, v23
	v_mul_f32_e32 v19, v19, v33
	v_rcp_f32_e32 v27, v24
	v_exp_f32_e32 v22, v22
	v_mul_f32_e32 v18, 0xbfb8aa3b, v18
	v_exp_f32_e32 v23, v23
	v_mul_f32_e32 v19, 0xbfb8aa3b, v19
	v_exp_f32_e32 v18, v18
	v_exp_f32_e32 v19, v19
	v_add_f32_e32 v20, 1.0, v20
	v_add_f32_e32 v21, 1.0, v21
	v_lshlrev_b32_e32 v24, 16, v95
	v_and_b32_e32 v25, 0xffff0000, v95
	v_lshlrev_b32_e32 v40, 16, v91
	v_and_b32_e32 v41, 0xffff0000, v91
	v_rcp_f32_e32 v20, v20
	v_add_f32_e32 v16, 1.0, v16
	v_rcp_f32_e32 v21, v21
	v_add_f32_e32 v17, 1.0, v17
	v_pk_fma_f32 v[40:41], v[26:27], v[24:25], v[40:41]
	v_rcp_f32_e32 v16, v16
	v_rcp_f32_e32 v17, v17
	v_add_f32_e32 v22, 1.0, v22
	v_add_f32_e32 v23, 1.0, v23
	v_pk_mul_f32 v[24:25], v[40:41], v[40:41]
	v_rcp_f32_e32 v22, v22
	v_add_f32_e32 v18, 1.0, v18
	v_rcp_f32_e32 v23, v23
	v_add_f32_e32 v19, 1.0, v19
	v_pk_fma_f32 v[42:43], v[30:31], v[30:31], v[24:25]
	v_cvt_pk_bf16_f32 v24, v28, v29
	v_cvt_pk_bf16_f32 v25, v30, v31
	s_waitcnt vmcnt(8)
	v_lshlrev_b32_e32 v28, 16, v84
	v_and_b32_e32 v29, 0xffff0000, v84
	v_lshlrev_b32_e32 v30, 16, v80
	v_and_b32_e32 v31, 0xffff0000, v80
	v_rcp_f32_e32 v18, v18
	v_rcp_f32_e32 v19, v19
	v_pk_fma_f32 v[20:21], v[20:21], v[28:29], v[30:31]
	v_lshlrev_b32_e32 v28, 16, v86
	v_and_b32_e32 v29, 0xffff0000, v86
	v_lshlrev_b32_e32 v30, 16, v82
	v_and_b32_e32 v31, 0xffff0000, v82
	v_cvt_pk_bf16_f32 v26, v36, v37
	v_pk_fma_f32 v[28:29], v[16:17], v[28:29], v[30:31]
	v_lshlrev_b32_e32 v30, 16, v85
	v_and_b32_e32 v31, 0xffff0000, v85
	v_lshlrev_b32_e32 v36, 16, v81
	v_and_b32_e32 v37, 0xffff0000, v81
	v_add_f32_e32 v33, v38, v39
	v_pk_mul_f32 v[16:17], v[28:29], v[28:29]
	v_pk_fma_f32 v[22:23], v[22:23], v[30:31], v[36:37]
	v_lshlrev_b32_e32 v30, 16, v87
	v_and_b32_e32 v31, 0xffff0000, v87
	v_lshlrev_b32_e32 v36, 16, v83
	v_and_b32_e32 v37, 0xffff0000, v83
	v_add_f32_e32 v33, v42, v33
	v_pk_fma_f32 v[16:17], v[20:21], v[20:21], v[16:17]
	v_pk_fma_f32 v[30:31], v[18:19], v[30:31], v[36:37]
	v_add_f32_e32 v33, v43, v33
	v_pk_mul_f32 v[18:19], v[30:31], v[30:31]
	v_add_f32_e32 v16, v16, v33
	v_pk_fma_f32 v[18:19], v[22:23], v[22:23], v[18:19]
	v_add_f32_e32 v16, v17, v16
	v_add_f32_e32 v16, v18, v16
	v_add_f32_e32 v19, v19, v16
	ds_bpermute_b32 v33, v187, v19
	v_lshl_add_u64 v[16:17], s[18:19], 0, v[34:35]
	v_lshl_add_u64 v[34:35], v[202:203], 1, v[16:17]
	v_cvt_pk_bf16_f32 v27, v40, v41
	v_cvt_pk_bf16_f32 v18, v20, v21
	s_waitcnt lgkmcnt(0)
	v_add_f32_e32 v16, v19, v33
	ds_bpermute_b32 v17, v189, v16
	v_cvt_pk_bf16_f32 v19, v22, v23
	v_cvt_pk_bf16_f32 v20, v28, v29
	v_cvt_pk_bf16_f32 v21, v30, v31
	global_store_dwordx4 v[34:35], v[24:27], off nt
	global_store_dwordx4 v[34:35], v[18:21], off offset:256 nt
	s_and_saveexec_b64 s[0:1], vcc
	s_cbranch_execz .LBB0_577
	s_waitcnt lgkmcnt(0)
	v_add_f32_e32 v16, v16, v17
	v_lshl_add_u32 v17, v32, 2, 0
	v_add_u32_e32 v17, 0x20400, v17
	ds_add_f32 v17, v16
.LBB0_577:
	s_or_b64 exec, exec, s[0:1]
	s_waitcnt lgkmcnt(0)
	ds_read_b32 v17, v216 offset:704
	s_waitcnt vmcnt(7)
	v_and_b32_e32 v21, 0xffff0000, v76
	v_lshlrev_b32_e32 v22, 16, v72
	v_and_b32_e32 v23, 0xffff0000, v72
	v_lshlrev_b32_e32 v24, 16, v73
	s_waitcnt lgkmcnt(0)
	v_fmamk_f32 v17, v17, 0x3a800000, v214
	v_mul_f32_e32 v18, 0x4b800000, v17
	v_cmp_gt_f32_e64 s[0:1], s58, v17
	v_and_b32_e32 v25, 0xffff0000, v73
	v_add_u32_e32 v16, 0xb0, v215
	v_cndmask_b32_e64 v17, v17, v18, s[0:1]
	v_rsq_f32_e32 v17, v17
	v_add_u32_e32 v18, s44, v16
	v_ashrrev_i32_e32 v19, 31, v18
	v_lshlrev_b64 v[18:19], 11, v[18:19]
	v_mul_f32_e32 v20, 0x45800000, v17
	v_cndmask_b32_e64 v17, v17, v20, s[0:1]
	v_mul_f32_e32 v12, v12, v17
	v_mul_f32_e32 v13, v13, v17
	v_mul_f32_e32 v8, v8, v17
	v_mul_f32_e32 v12, 0xbfb8aa3b, v12
	v_mul_f32_e32 v13, 0xbfb8aa3b, v13
	v_mul_f32_e32 v9, v9, v17
	v_exp_f32_e32 v12, v12
	v_mul_f32_e32 v8, 0xbfb8aa3b, v8
	v_exp_f32_e32 v13, v13
	v_mul_f32_e32 v9, 0xbfb8aa3b, v9
	v_exp_f32_e32 v8, v8
	v_exp_f32_e32 v9, v9
	v_add_f32_e32 v12, 1.0, v12
	v_add_f32_e32 v13, 1.0, v13
	v_rcp_f32_e32 v12, v12
	v_add_f32_e32 v8, 1.0, v8
	v_rcp_f32_e32 v13, v13
	v_add_f32_e32 v9, 1.0, v9
	v_rcp_f32_e32 v8, v8
	v_rcp_f32_e32 v9, v9
	v_lshlrev_b32_e32 v20, 16, v76
	v_pk_fma_f32 v[12:13], v[12:13], v[20:21], v[22:23]
	v_lshlrev_b32_e32 v20, 16, v78
	v_and_b32_e32 v21, 0xffff0000, v78
	v_lshlrev_b32_e32 v22, 16, v74
	v_and_b32_e32 v23, 0xffff0000, v74
	v_mul_f32_e32 v14, v14, v17
	v_mul_f32_e32 v14, 0xbfb8aa3b, v14
	v_pk_fma_f32 v[20:21], v[8:9], v[20:21], v[22:23]
	v_exp_f32_e32 v14, v14
	v_pk_mul_f32 v[8:9], v[20:21], v[20:21]
	v_mul_f32_e32 v11, v11, v17
	v_pk_fma_f32 v[22:23], v[12:13], v[12:13], v[8:9]
	v_mul_f32_e32 v9, v10, v17
	v_mul_f32_e32 v9, 0xbfb8aa3b, v9
	v_mul_f32_e32 v10, v15, v17
	v_exp_f32_e32 v9, v9
	v_mul_f32_e32 v10, 0xbfb8aa3b, v10
	v_add_f32_e32 v8, 1.0, v14
	v_exp_f32_e32 v14, v10
	v_add_f32_e32 v9, 1.0, v9
	v_rcp_f32_e32 v10, v9
	v_mul_f32_e32 v11, 0xbfb8aa3b, v11
	v_add_f32_e32 v9, 1.0, v14
	v_rcp_f32_e32 v8, v8
	v_rcp_f32_e32 v9, v9
	v_exp_f32_e32 v11, v11
	v_mul_f32_e32 v4, v4, v17
	v_mul_f32_e32 v5, v5, v17
	v_mul_f32_e32 v4, 0xbfb8aa3b, v4
	v_mul_f32_e32 v0, v0, v17
	v_mul_f32_e32 v5, 0xbfb8aa3b, v5
	v_mul_f32_e32 v1, v1, v17
	v_lshlrev_b32_e32 v14, 16, v77
	v_and_b32_e32 v15, 0xffff0000, v77
	v_exp_f32_e32 v4, v4
	v_mul_f32_e32 v0, 0xbfb8aa3b, v0
	v_exp_f32_e32 v5, v5
	v_mul_f32_e32 v1, 0xbfb8aa3b, v1
	v_mul_f32_e32 v6, v6, v17
	v_mul_f32_e32 v7, v7, v17
	v_pk_fma_f32 v[14:15], v[8:9], v[14:15], v[24:25]
	v_add_f32_e32 v8, 1.0, v11
	v_exp_f32_e32 v0, v0
	v_exp_f32_e32 v1, v1
	v_mul_f32_e32 v6, 0xbfb8aa3b, v6
	v_mul_f32_e32 v2, v2, v17
	v_mul_f32_e32 v7, 0xbfb8aa3b, v7
	v_mul_f32_e32 v3, v3, v17
	v_rcp_f32_e32 v11, v8
	v_exp_f32_e32 v6, v6
	v_mul_f32_e32 v2, 0xbfb8aa3b, v2
	v_exp_f32_e32 v7, v7
	v_mul_f32_e32 v3, 0xbfb8aa3b, v3
	v_exp_f32_e32 v2, v2
	v_exp_f32_e32 v3, v3
	v_add_f32_e32 v4, 1.0, v4
	v_add_f32_e32 v5, 1.0, v5
	v_lshlrev_b32_e32 v8, 16, v79
	v_and_b32_e32 v9, 0xffff0000, v79
	v_lshlrev_b32_e32 v24, 16, v75
	v_and_b32_e32 v25, 0xffff0000, v75
	v_rcp_f32_e32 v4, v4
	v_add_f32_e32 v0, 1.0, v0
	v_rcp_f32_e32 v5, v5
	v_add_f32_e32 v1, 1.0, v1
	v_pk_fma_f32 v[24:25], v[10:11], v[8:9], v[24:25]
	v_rcp_f32_e32 v0, v0
	v_rcp_f32_e32 v1, v1
	v_add_f32_e32 v6, 1.0, v6
	v_add_f32_e32 v7, 1.0, v7
	v_pk_mul_f32 v[8:9], v[24:25], v[24:25]
	v_rcp_f32_e32 v6, v6
	v_add_f32_e32 v2, 1.0, v2
	v_rcp_f32_e32 v7, v7
	v_add_f32_e32 v3, 1.0, v3
	v_pk_fma_f32 v[26:27], v[14:15], v[14:15], v[8:9]
	v_cvt_pk_bf16_f32 v8, v12, v13
	v_cvt_pk_bf16_f32 v9, v14, v15
	s_waitcnt vmcnt(6)
	v_lshlrev_b32_e32 v12, 16, v68
	v_and_b32_e32 v13, 0xffff0000, v68
	v_lshlrev_b32_e32 v14, 16, v64
	v_and_b32_e32 v15, 0xffff0000, v64
	v_rcp_f32_e32 v2, v2
	v_rcp_f32_e32 v3, v3
	v_pk_fma_f32 v[4:5], v[4:5], v[12:13], v[14:15]
	v_lshlrev_b32_e32 v12, 16, v70
	v_and_b32_e32 v13, 0xffff0000, v70
	v_lshlrev_b32_e32 v14, 16, v66
	v_and_b32_e32 v15, 0xffff0000, v66
	v_cvt_pk_bf16_f32 v10, v20, v21
	v_pk_fma_f32 v[12:13], v[0:1], v[12:13], v[14:15]
	v_lshlrev_b32_e32 v14, 16, v69
	v_and_b32_e32 v15, 0xffff0000, v69
	v_lshlrev_b32_e32 v20, 16, v65
	v_and_b32_e32 v21, 0xffff0000, v65
	v_add_f32_e32 v17, v22, v23
	v_pk_mul_f32 v[0:1], v[12:13], v[12:13]
	v_pk_fma_f32 v[6:7], v[6:7], v[14:15], v[20:21]
	v_lshlrev_b32_e32 v14, 16, v71
	v_and_b32_e32 v15, 0xffff0000, v71
	v_lshlrev_b32_e32 v20, 16, v67
	v_and_b32_e32 v21, 0xffff0000, v67
	v_add_f32_e32 v17, v26, v17
	v_pk_fma_f32 v[0:1], v[4:5], v[4:5], v[0:1]
	v_pk_fma_f32 v[14:15], v[2:3], v[14:15], v[20:21]
	v_add_f32_e32 v17, v27, v17
	v_pk_mul_f32 v[2:3], v[14:15], v[14:15]
	v_add_f32_e32 v0, v0, v17
	v_pk_fma_f32 v[2:3], v[6:7], v[6:7], v[2:3]
	v_add_f32_e32 v0, v1, v0
	v_add_f32_e32 v0, v2, v0
	v_add_f32_e32 v3, v3, v0
	ds_bpermute_b32 v17, v187, v3
	v_lshl_add_u64 v[0:1], s[18:19], 0, v[18:19]
	v_lshl_add_u64 v[18:19], v[202:203], 1, v[0:1]
	v_cvt_pk_bf16_f32 v11, v24, v25
	v_cvt_pk_bf16_f32 v2, v4, v5
	s_waitcnt lgkmcnt(0)
	v_add_f32_e32 v0, v3, v17
	ds_bpermute_b32 v1, v189, v0
	v_cvt_pk_bf16_f32 v3, v6, v7
	v_cvt_pk_bf16_f32 v4, v12, v13
	v_cvt_pk_bf16_f32 v5, v14, v15
	global_store_dwordx4 v[18:19], v[8:11], off nt
	global_store_dwordx4 v[18:19], v[2:5], off offset:256 nt
	s_and_saveexec_b64 s[0:1], vcc
	s_cbranch_execz .LBB0_560
	s_waitcnt lgkmcnt(0)
	v_add_f32_e32 v0, v0, v1
	v_lshl_add_u32 v1, v16, 2, 0
	v_add_u32_e32 v1, 0x20400, v1
	ds_add_f32 v1, v0
	s_branch .LBB0_560
